# counted lgkmcnt waits in attention MFMA blocks; FoX QK 6-deep fragment ring; hoisted/batched epilogue loads in P1/P5
# speedup vs baseline: 1.0073x; 1.0073x over previous
; __device__ __forceinline__ unsigned cvt_pk_bf16(float lo, float hi) { unsigned r; asm volatile("v_cvt_pk_bf16_f32 %0, %1, %2" : "=v"(r) : "v"(lo), "v"(hi)); return r; }
; #define GAS1 __attribute__((address_space(1)))
;     __device__ __forceinline__ void operator()(const f32x4 (&acc)[2][2][4][2], const Unit& u, int wr, int wc, int fr, int fq) const {
;     ...
;                         const f32x4 b0 = *(const GAS1 f32x4*)(bias + col) * -1.4426950408889634f, b1 = *(const GAS1 f32x4*)(bias + col + 4) * -1.4426950408889634f;
; #pragma unroll
;                         for (int j = 0; j < 4; ++j) { v0[j] = __builtin_amdgcn_rcpf(1.0f + __builtin_amdgcn_exp2f(__builtin_fmaf(v0[j], -1.4426950408889634f, b0[j])));
;                                                       v1[j] = __builtin_amdgcn_rcpf(1.0f + __builtin_amdgcn_exp2f(__builtin_fmaf(v1[j], -1.4426950408889634f, b1[j]))); }
;     ...
;                 u32x4 w; w.x = cvt_pk_bf16(v0[0], v0[1]); w.y = cvt_pk_bf16(v0[2], v0[3]); w.z = cvt_pk_bf16(v1[0], v1[1]); w.w = cvt_pk_bf16(v1[2], v1[3]);
;                 if (bj == 0) asm volatile("ds_write_b128 %0, %1" :: "v"(wa), "v"(w)); else asm volatile("ds_write_b128 %0, %1 offset:64" :: "v"(wa), "v"(w));
;             }
;             asm volatile("ds_read_b128 %0, %1" : "=&v"(rb[g & 1][0]) : "v"(ra));
;             asm volatile("ds_read_b128 %0, %1 offset:1152" : "=&v"(rb[g & 1][1]) : "v"(ra));
.LBB0_767:
	s_lshl_b32 s38, s6, 8
	s_cmp_lt_i32 s6, 16
	v_or_b32_e32 v146, s38, v152
	s_cselect_b64 s[42:43], -1, 0
	s_cmp_gt_i32 s6, 15
	v_ashrrev_i32_e32 v147, 31, v146
	s_cbranch_scc1 .LBB0_769
	v_lshl_add_u64 v[162:163], v[146:147], 2, s[10:11]
	global_load_dwordx4 v[192:195], v[162:163], off offset:128
	global_load_dwordx4 v[196:199], v[162:163], off offset:144
	global_load_dwordx4 v[158:161], v[162:163], off
	s_nop 0
	global_load_dwordx4 v[162:165], v[162:163], off offset:16
	s_waitcnt vmcnt(0)
	v_mul_f32_e32 v158, 0xbfb8aa3b, v158
	v_mul_f32_e32 v162, 0xbfb8aa3b, v162
	v_mul_f32_e32 v159, 0xbfb8aa3b, v159
	v_mul_f32_e32 v163, 0xbfb8aa3b, v163
	v_mul_f32_e32 v160, 0xbfb8aa3b, v160
	v_mul_f32_e32 v164, 0xbfb8aa3b, v164
	v_mul_f32_e32 v161, 0xbfb8aa3b, v161
	v_mul_f32_e32 v165, 0xbfb8aa3b, v165
	v_mov_b32_e32 v176, v158
	v_mov_b32_e32 v177, v159
	v_mov_b32_e32 v178, v160
	v_mov_b32_e32 v179, v161
	v_mov_b32_e32 v180, v162
	v_mov_b32_e32 v181, v163
	v_mov_b32_e32 v182, v164
	v_mov_b32_e32 v183, v165
	v_mul_f32_e32 v184, 0xbfb8aa3b, v192
	v_mul_f32_e32 v185, 0xbfb8aa3b, v193
	v_mul_f32_e32 v186, 0xbfb8aa3b, v194
	v_mul_f32_e32 v187, 0xbfb8aa3b, v195
	v_mul_f32_e32 v188, 0xbfb8aa3b, v196
	v_mul_f32_e32 v189, 0xbfb8aa3b, v197
	v_mul_f32_e32 v190, 0xbfb8aa3b, v198
	v_mul_f32_e32 v191, 0xbfb8aa3b, v199
	v_fmac_f32_e32 v158, 0xbfb8aa3b, v124
	v_fmac_f32_e32 v162, 0xbfb8aa3b, v120
	v_fmac_f32_e32 v159, 0xbfb8aa3b, v125
	v_fmac_f32_e32 v163, 0xbfb8aa3b, v121
	v_fmac_f32_e32 v160, 0xbfb8aa3b, v126
	v_fmac_f32_e32 v164, 0xbfb8aa3b, v122
	v_fmac_f32_e32 v161, 0xbfb8aa3b, v127
	v_fmac_f32_e32 v165, 0xbfb8aa3b, v123
	v_exp_f32_e32 v120, v158
	v_exp_f32_e32 v121, v162
	v_exp_f32_e32 v122, v159
	v_exp_f32_e32 v123, v163
	v_exp_f32_e32 v124, v160
	v_exp_f32_e32 v125, v164
	v_exp_f32_e32 v126, v161
	v_exp_f32_e32 v127, v165
	v_add_f32_e32 v120, 1.0, v120
	v_add_f32_e32 v121, 1.0, v121
	v_add_f32_e32 v122, 1.0, v122
	v_add_f32_e32 v123, 1.0, v123
	v_add_f32_e32 v158, 1.0, v124
	v_add_f32_e32 v159, 1.0, v125
	v_add_f32_e32 v160, 1.0, v126
	v_add_f32_e32 v161, 1.0, v127
	v_rcp_f32_e32 v124, v120
	v_rcp_f32_e32 v120, v121
	v_rcp_f32_e32 v125, v122
	v_rcp_f32_e32 v121, v123
	v_rcp_f32_e32 v126, v158
	v_rcp_f32_e32 v122, v159
	v_rcp_f32_e32 v127, v160
	v_rcp_f32_e32 v123, v161
.LBB0_769:
	v_cvt_pk_bf16_f32 v124, v124, v125
	v_cvt_pk_bf16_f32 v125, v126, v127
	v_cvt_pk_bf16_f32 v126, v120, v121
	v_cndmask_b32_e64 v120, 0, 1, s[42:43]
	v_cmp_ne_u32_e64 s[6:7], 1, v120
	s_andn2_b64 vcc, exec, s[42:43]
	v_cvt_pk_bf16_f32 v127, v122, v123
	s_nop 0
	ds_write_b128 v153, v[124:127]
	s_cbranch_vccnz .LBB0_771
	v_mov_b32_e32 v120, v184
	v_mov_b32_e32 v124, v188
	v_mov_b32_e32 v121, v185
	v_mov_b32_e32 v125, v189
	v_mov_b32_e32 v122, v186
	v_mov_b32_e32 v126, v190
	v_mov_b32_e32 v123, v187
	v_mov_b32_e32 v127, v191
	v_fmac_f32_e32 v120, 0xbfb8aa3b, v116
	v_fmac_f32_e32 v124, 0xbfb8aa3b, v112
	v_fmac_f32_e32 v121, 0xbfb8aa3b, v117
	v_fmac_f32_e32 v125, 0xbfb8aa3b, v113
	v_fmac_f32_e32 v122, 0xbfb8aa3b, v118
	v_fmac_f32_e32 v126, 0xbfb8aa3b, v114
	v_fmac_f32_e32 v123, 0xbfb8aa3b, v119
	v_fmac_f32_e32 v127, 0xbfb8aa3b, v115
	v_exp_f32_e32 v112, v120
	v_exp_f32_e32 v113, v124
	v_exp_f32_e32 v114, v121
	v_exp_f32_e32 v115, v125
	v_exp_f32_e32 v116, v122
	v_exp_f32_e32 v117, v126
	v_exp_f32_e32 v118, v123
	v_exp_f32_e32 v119, v127
	v_add_f32_e32 v112, 1.0, v112
	v_add_f32_e32 v113, 1.0, v113
	v_add_f32_e32 v114, 1.0, v114
	v_add_f32_e32 v115, 1.0, v115
	v_add_f32_e32 v120, 1.0, v116
	v_add_f32_e32 v121, 1.0, v117
	v_add_f32_e32 v122, 1.0, v118
	v_add_f32_e32 v123, 1.0, v119
	v_rcp_f32_e32 v116, v112
	v_rcp_f32_e32 v112, v113
	v_rcp_f32_e32 v117, v114
	v_rcp_f32_e32 v113, v115
	v_rcp_f32_e32 v118, v120
	v_rcp_f32_e32 v114, v121
	v_rcp_f32_e32 v119, v122
	v_rcp_f32_e32 v115, v123
.LBB0_771:
	v_cvt_pk_bf16_f32 v116, v116, v117
	v_cvt_pk_bf16_f32 v117, v118, v119
	v_cvt_pk_bf16_f32 v118, v112, v113
	v_cvt_pk_bf16_f32 v119, v114, v115
	s_and_b64 vcc, exec, s[6:7]
	ds_write_b128 v153, v[116:119] offset:64
	ds_read_b128 v[116:119], v154
	ds_read_b128 v[112:115], v154 offset:1152
	s_cbranch_vccnz .LBB0_773
	v_mov_b32_e32 v120, v176
	v_mov_b32_e32 v124, v180
	v_mov_b32_e32 v121, v177
	v_mov_b32_e32 v125, v181
	v_mov_b32_e32 v122, v178
	v_mov_b32_e32 v126, v182
	v_mov_b32_e32 v123, v179
	v_mov_b32_e32 v127, v183
	v_fmac_f32_e32 v120, 0xbfb8aa3b, v108
	v_fmac_f32_e32 v124, 0xbfb8aa3b, v104
	v_fmac_f32_e32 v121, 0xbfb8aa3b, v109
	v_fmac_f32_e32 v125, 0xbfb8aa3b, v105
	v_fmac_f32_e32 v122, 0xbfb8aa3b, v110
	v_fmac_f32_e32 v126, 0xbfb8aa3b, v106
	v_fmac_f32_e32 v123, 0xbfb8aa3b, v111
	v_fmac_f32_e32 v127, 0xbfb8aa3b, v107
	v_exp_f32_e32 v104, v120
	v_exp_f32_e32 v105, v124
	v_exp_f32_e32 v106, v121
	v_exp_f32_e32 v107, v125
	v_exp_f32_e32 v108, v122
	v_exp_f32_e32 v109, v126
	v_exp_f32_e32 v110, v123
	v_exp_f32_e32 v111, v127
	v_add_f32_e32 v104, 1.0, v104
	v_add_f32_e32 v105, 1.0, v105
	v_add_f32_e32 v106, 1.0, v106
	v_add_f32_e32 v107, 1.0, v107
	v_add_f32_e32 v120, 1.0, v108
	v_add_f32_e32 v121, 1.0, v109
	v_add_f32_e32 v122, 1.0, v110
	v_add_f32_e32 v123, 1.0, v111
	v_rcp_f32_e32 v108, v104
	v_rcp_f32_e32 v104, v105
	v_rcp_f32_e32 v109, v106
	v_rcp_f32_e32 v105, v107
	v_rcp_f32_e32 v110, v120
	v_rcp_f32_e32 v106, v121
	v_rcp_f32_e32 v111, v122
	v_rcp_f32_e32 v107, v123
; __device__ __forceinline__ unsigned cvt_pk_bf16(float lo, float hi) { unsigned r; asm volatile("v_cvt_pk_bf16_f32 %0, %1, %2" : "=v"(r) : "v"(lo), "v"(hi)); return r; }
; #define GAS1 __attribute__((address_space(1)))
;     __device__ __forceinline__ void operator()(const f32x4 (&acc)[2][2][4][2], const Unit& u, int wr, int wc, int fr, int fq) const {
;     ...
;                         const f32x4 b0 = *(const GAS1 f32x4*)(bias + col) * -1.4426950408889634f, b1 = *(const GAS1 f32x4*)(bias + col + 4) * -1.4426950408889634f;
; #pragma unroll
;                         for (int j = 0; j < 4; ++j) { v0[j] = __builtin_amdgcn_rcpf(1.0f + __builtin_amdgcn_exp2f(__builtin_fmaf(v0[j], -1.4426950408889634f, b0[j])));
;                                                       v1[j] = __builtin_amdgcn_rcpf(1.0f + __builtin_amdgcn_exp2f(__builtin_fmaf(v1[j], -1.4426950408889634f, b1[j]))); }
;     ...
;                 u32x4 w; w.x = cvt_pk_bf16(v0[0], v0[1]); w.y = cvt_pk_bf16(v0[2], v0[3]); w.z = cvt_pk_bf16(v1[0], v1[1]); w.w = cvt_pk_bf16(v1[2], v1[3]);
;                 if (bj == 0) asm volatile("ds_write_b128 %0, %1" :: "v"(wa), "v"(w)); else asm volatile("ds_write_b128 %0, %1 offset:64" :: "v"(wa), "v"(w));
;             }
;             asm volatile("ds_read_b128 %0, %1" : "=&v"(rb[g & 1][0]) : "v"(ra));
;             asm volatile("ds_read_b128 %0, %1 offset:1152" : "=&v"(rb[g & 1][1]) : "v"(ra));
;             if (g >= 1) {
;                 asm volatile("s_waitcnt lgkmcnt(4)" : "+v"(rb[(g - 1) & 1][0]), "+v"(rb[(g - 1) & 1][1]));
;                 bf16_t* ob = obase + (size_t)(((g - 1) >> 2) * HALF + ((g - 1) & 3) * 16) * ldc;
;                 *(GAS1 u32x4*)ob = rb[(g - 1) & 1][0]; *(GAS1 u32x4*)(ob + (size_t)8 * ldc) = rb[(g - 1) & 1][1];
;             }
.LBB0_773:
	s_and_b64 vcc, exec, s[6:7]
	v_cvt_pk_bf16_f32 v108, v108, v109
	v_cvt_pk_bf16_f32 v109, v110, v111
	v_cvt_pk_bf16_f32 v110, v104, v105
	v_cvt_pk_bf16_f32 v111, v106, v107
	s_nop 0
	ds_write_b128 v153, v[108:111]
	s_cbranch_vccnz .LBB0_775
	v_mov_b32_e32 v104, v184
	v_mov_b32_e32 v108, v188
	v_mov_b32_e32 v105, v185
	v_mov_b32_e32 v109, v189
	v_mov_b32_e32 v106, v186
	v_mov_b32_e32 v110, v190
	v_mov_b32_e32 v107, v187
	v_mov_b32_e32 v111, v191
	v_fmac_f32_e32 v104, 0xbfb8aa3b, v100
	v_fmac_f32_e32 v108, 0xbfb8aa3b, v96
	v_fmac_f32_e32 v105, 0xbfb8aa3b, v101
	v_fmac_f32_e32 v109, 0xbfb8aa3b, v97
	v_fmac_f32_e32 v106, 0xbfb8aa3b, v102
	v_fmac_f32_e32 v110, 0xbfb8aa3b, v98
	v_fmac_f32_e32 v107, 0xbfb8aa3b, v103
	v_fmac_f32_e32 v111, 0xbfb8aa3b, v99
	v_exp_f32_e32 v96, v104
	v_exp_f32_e32 v97, v108
	v_exp_f32_e32 v98, v105
	v_exp_f32_e32 v99, v109
	v_exp_f32_e32 v100, v106
	v_exp_f32_e32 v101, v110
	v_exp_f32_e32 v102, v107
	v_exp_f32_e32 v103, v111
	v_add_f32_e32 v96, 1.0, v96
	v_add_f32_e32 v97, 1.0, v97
	v_add_f32_e32 v98, 1.0, v98
	v_add_f32_e32 v99, 1.0, v99
	v_add_f32_e32 v104, 1.0, v100
	v_add_f32_e32 v105, 1.0, v101
	v_add_f32_e32 v106, 1.0, v102
	v_add_f32_e32 v107, 1.0, v103
	v_rcp_f32_e32 v100, v96
	v_rcp_f32_e32 v96, v97
	v_rcp_f32_e32 v101, v98
	v_rcp_f32_e32 v97, v99
	v_rcp_f32_e32 v102, v104
	v_rcp_f32_e32 v98, v105
	v_rcp_f32_e32 v103, v106
	v_rcp_f32_e32 v99, v107
.LBB0_775:
	v_lshl_add_u32 v106, s36, 8, v151
	v_mov_b64_e32 v[104:105], s[16:17]
	v_mad_i64_i32 v[104:105], s[40:41], v106, s71, v[104:105]
	s_ashr_i32 s39, s38, 31
	v_lshl_add_u64 v[104:105], s[38:39], 1, v[104:105]
	v_lshl_add_u64 v[104:105], v[104:105], 0, s[12:13]
	v_lshl_add_u64 v[104:105], v[104:105], 0, v[136:137]
	v_add_co_u32_e32 v106, vcc, 0x1c000, v104
	v_cvt_pk_bf16_f32 v100, v100, v101
	v_cvt_pk_bf16_f32 v101, v102, v103
	v_cvt_pk_bf16_f32 v102, v96, v97
	v_cvt_pk_bf16_f32 v103, v98, v99
	s_nop 1
	v_addc_co_u32_e32 v107, vcc, 0, v105, vcc
	s_and_b64 vcc, exec, s[6:7]
	ds_write_b128 v153, v[100:103] offset:64
	ds_read_b128 v[100:103], v154
	ds_read_b128 v[96:99], v154 offset:1152
	s_waitcnt lgkmcnt(4)
	global_store_dwordx4 v[104:105], v[116:119], off
	global_store_dwordx4 v[106:107], v[112:115], off
	s_cbranch_vccnz .LBB0_777
	v_mov_b32_e32 v106, v176
	v_mov_b32_e32 v110, v180
	v_mov_b32_e32 v107, v177
	v_mov_b32_e32 v111, v181
	v_mov_b32_e32 v108, v178
	v_mov_b32_e32 v112, v182
	v_mov_b32_e32 v109, v179
	v_mov_b32_e32 v113, v183
	v_fmac_f32_e32 v106, 0xbfb8aa3b, v92
	v_fmac_f32_e32 v110, 0xbfb8aa3b, v88
	v_fmac_f32_e32 v107, 0xbfb8aa3b, v93
	v_fmac_f32_e32 v111, 0xbfb8aa3b, v89
	v_fmac_f32_e32 v108, 0xbfb8aa3b, v94
	v_fmac_f32_e32 v112, 0xbfb8aa3b, v90
	v_fmac_f32_e32 v109, 0xbfb8aa3b, v95
	v_fmac_f32_e32 v113, 0xbfb8aa3b, v91
	v_exp_f32_e32 v88, v106
	v_exp_f32_e32 v89, v110
	v_exp_f32_e32 v90, v107
	v_exp_f32_e32 v91, v111
	v_exp_f32_e32 v92, v108
	v_exp_f32_e32 v93, v112
	v_exp_f32_e32 v94, v109
	v_exp_f32_e32 v95, v113
	v_add_f32_e32 v88, 1.0, v88
	v_add_f32_e32 v89, 1.0, v89
	v_add_f32_e32 v90, 1.0, v90
	v_add_f32_e32 v91, 1.0, v91
	v_add_f32_e32 v106, 1.0, v92
	v_add_f32_e32 v107, 1.0, v93
	v_add_f32_e32 v108, 1.0, v94
	v_add_f32_e32 v109, 1.0, v95
	v_rcp_f32_e32 v92, v88
	v_rcp_f32_e32 v88, v89
	v_rcp_f32_e32 v93, v90
	v_rcp_f32_e32 v89, v91
	v_rcp_f32_e32 v94, v106
	v_rcp_f32_e32 v90, v107
	v_rcp_f32_e32 v95, v108
	v_rcp_f32_e32 v91, v109
.LBB0_777:
	s_and_b64 vcc, exec, s[6:7]
	v_cvt_pk_bf16_f32 v92, v92, v93
	v_cvt_pk_bf16_f32 v93, v94, v95
	v_cvt_pk_bf16_f32 v94, v88, v89
	v_cvt_pk_bf16_f32 v95, v90, v91
	s_nop 0
	ds_write_b128 v153, v[92:95]
	s_cbranch_vccnz .LBB0_779
	v_mov_b32_e32 v88, v184
	v_mov_b32_e32 v92, v188
	v_mov_b32_e32 v89, v185
	v_mov_b32_e32 v93, v189
	v_mov_b32_e32 v90, v186
	v_mov_b32_e32 v94, v190
	v_mov_b32_e32 v91, v187
	v_mov_b32_e32 v95, v191
	v_fmac_f32_e32 v88, 0xbfb8aa3b, v84
	v_fmac_f32_e32 v92, 0xbfb8aa3b, v80
	v_fmac_f32_e32 v89, 0xbfb8aa3b, v85
	v_fmac_f32_e32 v93, 0xbfb8aa3b, v81
	v_fmac_f32_e32 v90, 0xbfb8aa3b, v86
	v_fmac_f32_e32 v94, 0xbfb8aa3b, v82
	v_fmac_f32_e32 v91, 0xbfb8aa3b, v87
	v_fmac_f32_e32 v95, 0xbfb8aa3b, v83
	v_exp_f32_e32 v80, v88
	v_exp_f32_e32 v81, v92
	v_exp_f32_e32 v82, v89
	v_exp_f32_e32 v83, v93
	v_exp_f32_e32 v84, v90
	v_exp_f32_e32 v85, v94
	v_exp_f32_e32 v86, v91
	v_exp_f32_e32 v87, v95
	v_add_f32_e32 v80, 1.0, v80
	v_add_f32_e32 v81, 1.0, v81
	v_add_f32_e32 v82, 1.0, v82
	v_add_f32_e32 v83, 1.0, v83
	v_add_f32_e32 v88, 1.0, v84
	v_add_f32_e32 v89, 1.0, v85
	v_add_f32_e32 v90, 1.0, v86
	v_add_f32_e32 v91, 1.0, v87
	v_rcp_f32_e32 v84, v80
	v_rcp_f32_e32 v80, v81
	v_rcp_f32_e32 v85, v82
	v_rcp_f32_e32 v81, v83
	v_rcp_f32_e32 v86, v88
	v_rcp_f32_e32 v82, v89
	v_rcp_f32_e32 v87, v90
	v_rcp_f32_e32 v83, v91
.LBB0_779:
	v_add_co_u32_e32 v88, vcc, 0x38000, v104
	v_cvt_pk_bf16_f32 v84, v84, v85
	v_cvt_pk_bf16_f32 v85, v86, v87
	v_cvt_pk_bf16_f32 v86, v80, v81
	v_cvt_pk_bf16_f32 v87, v82, v83
	s_nop 1
	v_addc_co_u32_e32 v89, vcc, 0, v105, vcc
	ds_write_b128 v153, v[84:87] offset:64
	ds_read_b128 v[84:87], v154
	ds_read_b128 v[80:83], v154 offset:1152
	s_waitcnt lgkmcnt(4)
	global_store_dwordx4 v[88:89], v[100:103], off
	v_add_co_u32_e32 v88, vcc, 0x54000, v104
	s_nop 1
	v_addc_co_u32_e32 v89, vcc, 0, v105, vcc
	s_and_b64 vcc, exec, s[6:7]
	global_store_dwordx4 v[88:89], v[96:99], off
	s_cbranch_vccnz .LBB0_781
	v_mov_b32_e32 v88, v176
	v_mov_b32_e32 v92, v180
	v_mov_b32_e32 v89, v177
	v_mov_b32_e32 v93, v181
	v_mov_b32_e32 v90, v178
	v_mov_b32_e32 v94, v182
	v_mov_b32_e32 v91, v179
	v_mov_b32_e32 v95, v183
	v_fmac_f32_e32 v88, 0xbfb8aa3b, v76
	v_fmac_f32_e32 v92, 0xbfb8aa3b, v72
	v_fmac_f32_e32 v89, 0xbfb8aa3b, v77
	v_fmac_f32_e32 v93, 0xbfb8aa3b, v73
	v_fmac_f32_e32 v90, 0xbfb8aa3b, v78
	v_fmac_f32_e32 v94, 0xbfb8aa3b, v74
	v_fmac_f32_e32 v91, 0xbfb8aa3b, v79
	v_fmac_f32_e32 v95, 0xbfb8aa3b, v75
	v_exp_f32_e32 v72, v88
	v_exp_f32_e32 v73, v92
	v_exp_f32_e32 v74, v89
	v_exp_f32_e32 v75, v93
	v_exp_f32_e32 v76, v90
	v_exp_f32_e32 v77, v94
	v_exp_f32_e32 v78, v91
	v_exp_f32_e32 v79, v95
	v_add_f32_e32 v72, 1.0, v72
	v_add_f32_e32 v73, 1.0, v73
	v_add_f32_e32 v74, 1.0, v74
	v_add_f32_e32 v75, 1.0, v75
	v_add_f32_e32 v88, 1.0, v76
	v_add_f32_e32 v89, 1.0, v77
	v_add_f32_e32 v90, 1.0, v78
	v_add_f32_e32 v91, 1.0, v79
	v_rcp_f32_e32 v76, v72
	v_rcp_f32_e32 v72, v73
	v_rcp_f32_e32 v77, v74
	v_rcp_f32_e32 v73, v75
	v_rcp_f32_e32 v78, v88
	v_rcp_f32_e32 v74, v89
	v_rcp_f32_e32 v79, v90
	v_rcp_f32_e32 v75, v91
; __device__ __forceinline__ unsigned cvt_pk_bf16(float lo, float hi) { unsigned r; asm volatile("v_cvt_pk_bf16_f32 %0, %1, %2" : "=v"(r) : "v"(lo), "v"(hi)); return r; }
; #define GAS1 __attribute__((address_space(1)))
;     __device__ __forceinline__ void operator()(const f32x4 (&acc)[2][2][4][2], const Unit& u, int wr, int wc, int fr, int fq) const {
;     ...
;                         const f32x4 b0 = *(const GAS1 f32x4*)(bias + col) * -1.4426950408889634f, b1 = *(const GAS1 f32x4*)(bias + col + 4) * -1.4426950408889634f;
; #pragma unroll
;                         for (int j = 0; j < 4; ++j) { v0[j] = __builtin_amdgcn_rcpf(1.0f + __builtin_amdgcn_exp2f(__builtin_fmaf(v0[j], -1.4426950408889634f, b0[j])));
;                                                       v1[j] = __builtin_amdgcn_rcpf(1.0f + __builtin_amdgcn_exp2f(__builtin_fmaf(v1[j], -1.4426950408889634f, b1[j]))); }
;     ...
;                 u32x4 w; w.x = cvt_pk_bf16(v0[0], v0[1]); w.y = cvt_pk_bf16(v0[2], v0[3]); w.z = cvt_pk_bf16(v1[0], v1[1]); w.w = cvt_pk_bf16(v1[2], v1[3]);
;                 if (bj == 0) asm volatile("ds_write_b128 %0, %1" :: "v"(wa), "v"(w)); else asm volatile("ds_write_b128 %0, %1 offset:64" :: "v"(wa), "v"(w));
;             }
;             asm volatile("ds_read_b128 %0, %1" : "=&v"(rb[g & 1][0]) : "v"(ra));
;             asm volatile("ds_read_b128 %0, %1 offset:1152" : "=&v"(rb[g & 1][1]) : "v"(ra));
;             if (g >= 1) {
;                 asm volatile("s_waitcnt lgkmcnt(4)" : "+v"(rb[(g - 1) & 1][0]), "+v"(rb[(g - 1) & 1][1]));
;                 bf16_t* ob = obase + (size_t)(((g - 1) >> 2) * HALF + ((g - 1) & 3) * 16) * ldc;
;                 *(GAS1 u32x4*)ob = rb[(g - 1) & 1][0]; *(GAS1 u32x4*)(ob + (size_t)8 * ldc) = rb[(g - 1) & 1][1];
;             }
.LBB0_781:
	s_and_b64 vcc, exec, s[6:7]
	v_cvt_pk_bf16_f32 v76, v76, v77
	v_cvt_pk_bf16_f32 v77, v78, v79
	v_cvt_pk_bf16_f32 v78, v72, v73
	v_cvt_pk_bf16_f32 v79, v74, v75
	s_nop 0
	ds_write_b128 v153, v[76:79]
	s_cbranch_vccnz .LBB0_783
	v_mov_b32_e32 v72, v184
	v_mov_b32_e32 v76, v188
	v_mov_b32_e32 v73, v185
	v_mov_b32_e32 v77, v189
	v_mov_b32_e32 v74, v186
	v_mov_b32_e32 v78, v190
	v_mov_b32_e32 v75, v187
	v_mov_b32_e32 v79, v191
	v_fmac_f32_e32 v72, 0xbfb8aa3b, v68
	v_fmac_f32_e32 v76, 0xbfb8aa3b, v64
	v_fmac_f32_e32 v73, 0xbfb8aa3b, v69
	v_fmac_f32_e32 v77, 0xbfb8aa3b, v65
	v_fmac_f32_e32 v74, 0xbfb8aa3b, v70
	v_fmac_f32_e32 v78, 0xbfb8aa3b, v66
	v_fmac_f32_e32 v75, 0xbfb8aa3b, v71
	v_fmac_f32_e32 v79, 0xbfb8aa3b, v67
	v_exp_f32_e32 v64, v72
	v_exp_f32_e32 v65, v76
	v_exp_f32_e32 v66, v73
	v_exp_f32_e32 v67, v77
	v_exp_f32_e32 v68, v74
	v_exp_f32_e32 v69, v78
	v_exp_f32_e32 v70, v75
	v_exp_f32_e32 v71, v79
	v_add_f32_e32 v64, 1.0, v64
	v_add_f32_e32 v65, 1.0, v65
	v_add_f32_e32 v66, 1.0, v66
	v_add_f32_e32 v67, 1.0, v67
	v_add_f32_e32 v72, 1.0, v68
	v_add_f32_e32 v73, 1.0, v69
	v_add_f32_e32 v74, 1.0, v70
	v_add_f32_e32 v75, 1.0, v71
	v_rcp_f32_e32 v68, v64
	v_rcp_f32_e32 v64, v65
	v_rcp_f32_e32 v69, v66
	v_rcp_f32_e32 v65, v67
	v_rcp_f32_e32 v70, v72
	v_rcp_f32_e32 v66, v73
	v_rcp_f32_e32 v71, v74
	v_rcp_f32_e32 v67, v75
.LBB0_783:
	v_add_co_u32_e32 v72, vcc, 0x70000, v104
	v_cvt_pk_bf16_f32 v68, v68, v69
	v_cvt_pk_bf16_f32 v69, v70, v71
	v_cvt_pk_bf16_f32 v70, v64, v65
	v_cvt_pk_bf16_f32 v71, v66, v67
	s_nop 1
	v_addc_co_u32_e32 v73, vcc, 0, v105, vcc
	ds_write_b128 v153, v[68:71] offset:64
	ds_read_b128 v[68:71], v154
	ds_read_b128 v[64:67], v154 offset:1152
	s_waitcnt lgkmcnt(4)
	global_store_dwordx4 v[72:73], v[84:87], off
	v_add_co_u32_e32 v72, vcc, 0x8c000, v104
	s_nop 1
	v_addc_co_u32_e32 v73, vcc, 0, v105, vcc
	s_and_b64 vcc, exec, s[6:7]
	global_store_dwordx4 v[72:73], v[80:83], off
	s_cbranch_vccnz .LBB0_785
	v_mov_b32_e32 v72, v176
	v_mov_b32_e32 v76, v180
	v_mov_b32_e32 v73, v177
	v_mov_b32_e32 v77, v181
	v_mov_b32_e32 v74, v178
	v_mov_b32_e32 v78, v182
	v_mov_b32_e32 v75, v179
	v_mov_b32_e32 v79, v183
	v_fmac_f32_e32 v72, 0xbfb8aa3b, v60
	v_fmac_f32_e32 v76, 0xbfb8aa3b, v56
	v_fmac_f32_e32 v73, 0xbfb8aa3b, v61
	v_fmac_f32_e32 v77, 0xbfb8aa3b, v57
	v_fmac_f32_e32 v74, 0xbfb8aa3b, v62
	v_fmac_f32_e32 v78, 0xbfb8aa3b, v58
	v_fmac_f32_e32 v75, 0xbfb8aa3b, v63
	v_fmac_f32_e32 v79, 0xbfb8aa3b, v59
	v_exp_f32_e32 v56, v72
	v_exp_f32_e32 v57, v76
	v_exp_f32_e32 v58, v73
	v_exp_f32_e32 v59, v77
	v_exp_f32_e32 v60, v74
	v_exp_f32_e32 v61, v78
	v_exp_f32_e32 v62, v75
	v_exp_f32_e32 v63, v79
	v_add_f32_e32 v56, 1.0, v56
	v_add_f32_e32 v57, 1.0, v57
	v_add_f32_e32 v58, 1.0, v58
	v_add_f32_e32 v59, 1.0, v59
	v_add_f32_e32 v72, 1.0, v60
	v_add_f32_e32 v73, 1.0, v61
	v_add_f32_e32 v74, 1.0, v62
	v_add_f32_e32 v75, 1.0, v63
	v_rcp_f32_e32 v60, v56
	v_rcp_f32_e32 v56, v57
	v_rcp_f32_e32 v61, v58
	v_rcp_f32_e32 v57, v59
	v_rcp_f32_e32 v62, v72
	v_rcp_f32_e32 v58, v73
	v_rcp_f32_e32 v63, v74
	v_rcp_f32_e32 v59, v75
.LBB0_785:
	s_and_b64 vcc, exec, s[6:7]
	v_cvt_pk_bf16_f32 v60, v60, v61
	v_cvt_pk_bf16_f32 v61, v62, v63
	v_cvt_pk_bf16_f32 v62, v56, v57
	v_cvt_pk_bf16_f32 v63, v58, v59
	s_nop 0
	ds_write_b128 v153, v[60:63]
	s_cbranch_vccnz .LBB0_787
	v_mov_b32_e32 v56, v184
	v_mov_b32_e32 v60, v188
	v_mov_b32_e32 v57, v185
	v_mov_b32_e32 v61, v189
	v_mov_b32_e32 v58, v186
	v_mov_b32_e32 v62, v190
	v_mov_b32_e32 v59, v187
	v_mov_b32_e32 v63, v191
	v_fmac_f32_e32 v56, 0xbfb8aa3b, v52
	v_fmac_f32_e32 v60, 0xbfb8aa3b, v48
	v_fmac_f32_e32 v57, 0xbfb8aa3b, v53
	v_fmac_f32_e32 v61, 0xbfb8aa3b, v49
	v_fmac_f32_e32 v58, 0xbfb8aa3b, v54
	v_fmac_f32_e32 v62, 0xbfb8aa3b, v50
	v_fmac_f32_e32 v59, 0xbfb8aa3b, v55
	v_fmac_f32_e32 v63, 0xbfb8aa3b, v51
	v_exp_f32_e32 v48, v56
	v_exp_f32_e32 v49, v60
	v_exp_f32_e32 v50, v57
	v_exp_f32_e32 v51, v61
	v_exp_f32_e32 v52, v58
	v_exp_f32_e32 v53, v62
	v_exp_f32_e32 v54, v59
	v_exp_f32_e32 v55, v63
	v_add_f32_e32 v48, 1.0, v48
	v_add_f32_e32 v49, 1.0, v49
	v_add_f32_e32 v50, 1.0, v50
	v_add_f32_e32 v51, 1.0, v51
	v_add_f32_e32 v56, 1.0, v52
	v_add_f32_e32 v57, 1.0, v53
	v_add_f32_e32 v58, 1.0, v54
	v_add_f32_e32 v59, 1.0, v55
	v_rcp_f32_e32 v52, v48
	v_rcp_f32_e32 v48, v49
	v_rcp_f32_e32 v53, v50
	v_rcp_f32_e32 v49, v51
	v_rcp_f32_e32 v54, v56
	v_rcp_f32_e32 v50, v57
	v_rcp_f32_e32 v55, v58
	v_rcp_f32_e32 v51, v59
.LBB0_787:
	v_add_co_u32_e32 v56, vcc, 0xa8000, v104
	v_cvt_pk_bf16_f32 v52, v52, v53
	v_cvt_pk_bf16_f32 v53, v54, v55
	v_cvt_pk_bf16_f32 v54, v48, v49
	v_cvt_pk_bf16_f32 v55, v50, v51
	s_nop 1
	v_addc_co_u32_e32 v57, vcc, 0, v105, vcc
	ds_write_b128 v153, v[52:55] offset:64
	ds_read_b128 v[52:55], v154
	ds_read_b128 v[48:51], v154 offset:1152
	s_waitcnt lgkmcnt(4)
	global_store_dwordx4 v[56:57], v[68:71], off
	v_add_co_u32_e32 v56, vcc, 0xc4000, v104
	s_nop 1
	v_addc_co_u32_e32 v57, vcc, 0, v105, vcc
	s_and_b64 vcc, exec, s[6:7]
	global_store_dwordx4 v[56:57], v[64:67], off
	s_cbranch_vccnz .LBB0_789
	v_mov_b32_e32 v56, v176
	v_mov_b32_e32 v60, v180
	v_mov_b32_e32 v57, v177
	v_mov_b32_e32 v61, v181
	v_mov_b32_e32 v58, v178
	v_mov_b32_e32 v62, v182
	v_mov_b32_e32 v59, v179
	v_mov_b32_e32 v63, v183
	v_fmac_f32_e32 v56, 0xbfb8aa3b, v44
	v_fmac_f32_e32 v60, 0xbfb8aa3b, v40
	v_fmac_f32_e32 v57, 0xbfb8aa3b, v45
	v_fmac_f32_e32 v61, 0xbfb8aa3b, v41
	v_fmac_f32_e32 v58, 0xbfb8aa3b, v46
	v_fmac_f32_e32 v62, 0xbfb8aa3b, v42
	v_fmac_f32_e32 v59, 0xbfb8aa3b, v47
	v_fmac_f32_e32 v63, 0xbfb8aa3b, v43
	v_exp_f32_e32 v40, v56
	v_exp_f32_e32 v41, v60
	v_exp_f32_e32 v42, v57
	v_exp_f32_e32 v43, v61
	v_exp_f32_e32 v44, v58
	v_exp_f32_e32 v45, v62
	v_exp_f32_e32 v46, v59
	v_exp_f32_e32 v47, v63
	v_add_f32_e32 v40, 1.0, v40
	v_add_f32_e32 v41, 1.0, v41
	v_add_f32_e32 v42, 1.0, v42
	v_add_f32_e32 v43, 1.0, v43
	v_add_f32_e32 v56, 1.0, v44
	v_add_f32_e32 v57, 1.0, v45
	v_add_f32_e32 v58, 1.0, v46
	v_add_f32_e32 v59, 1.0, v47
	v_rcp_f32_e32 v44, v40
	v_rcp_f32_e32 v40, v41
	v_rcp_f32_e32 v45, v42
	v_rcp_f32_e32 v41, v43
	v_rcp_f32_e32 v46, v56
	v_rcp_f32_e32 v42, v57
	v_rcp_f32_e32 v47, v58
	v_rcp_f32_e32 v43, v59
; __device__ __forceinline__ unsigned cvt_pk_bf16(float lo, float hi) { unsigned r; asm volatile("v_cvt_pk_bf16_f32 %0, %1, %2" : "=v"(r) : "v"(lo), "v"(hi)); return r; }
; #define GAS1 __attribute__((address_space(1)))
;     __device__ __forceinline__ void operator()(const f32x4 (&acc)[2][2][4][2], const Unit& u, int wr, int wc, int fr, int fq) const {
;     ...
;                         const f32x4 b0 = *(const GAS1 f32x4*)(bias + col) * -1.4426950408889634f, b1 = *(const GAS1 f32x4*)(bias + col + 4) * -1.4426950408889634f;
; #pragma unroll
;                         for (int j = 0; j < 4; ++j) { v0[j] = __builtin_amdgcn_rcpf(1.0f + __builtin_amdgcn_exp2f(__builtin_fmaf(v0[j], -1.4426950408889634f, b0[j])));
;                                                       v1[j] = __builtin_amdgcn_rcpf(1.0f + __builtin_amdgcn_exp2f(__builtin_fmaf(v1[j], -1.4426950408889634f, b1[j]))); }
;     ...
;                 u32x4 w; w.x = cvt_pk_bf16(v0[0], v0[1]); w.y = cvt_pk_bf16(v0[2], v0[3]); w.z = cvt_pk_bf16(v1[0], v1[1]); w.w = cvt_pk_bf16(v1[2], v1[3]);
;                 if (bj == 0) asm volatile("ds_write_b128 %0, %1" :: "v"(wa), "v"(w)); else asm volatile("ds_write_b128 %0, %1 offset:64" :: "v"(wa), "v"(w));
;             }
;             asm volatile("ds_read_b128 %0, %1" : "=&v"(rb[g & 1][0]) : "v"(ra));
;             asm volatile("ds_read_b128 %0, %1 offset:1152" : "=&v"(rb[g & 1][1]) : "v"(ra));
;             if (g >= 1) {
;                 asm volatile("s_waitcnt lgkmcnt(4)" : "+v"(rb[(g - 1) & 1][0]), "+v"(rb[(g - 1) & 1][1]));
;                 bf16_t* ob = obase + (size_t)(((g - 1) >> 2) * HALF + ((g - 1) & 3) * 16) * ldc;
;                 *(GAS1 u32x4*)ob = rb[(g - 1) & 1][0]; *(GAS1 u32x4*)(ob + (size_t)8 * ldc) = rb[(g - 1) & 1][1];
;             }
.LBB0_789:
	s_and_b64 vcc, exec, s[6:7]
	v_cvt_pk_bf16_f32 v44, v44, v45
	v_cvt_pk_bf16_f32 v45, v46, v47
	v_cvt_pk_bf16_f32 v46, v40, v41
	v_cvt_pk_bf16_f32 v47, v42, v43
	s_nop 0
	ds_write_b128 v153, v[44:47]
	s_cbranch_vccnz .LBB0_791
	v_mov_b32_e32 v40, v184
	v_mov_b32_e32 v44, v188
	v_mov_b32_e32 v41, v185
	v_mov_b32_e32 v45, v189
	v_mov_b32_e32 v42, v186
	v_mov_b32_e32 v46, v190
	v_mov_b32_e32 v43, v187
	v_mov_b32_e32 v47, v191
	v_fmac_f32_e32 v40, 0xbfb8aa3b, v36
	v_fmac_f32_e32 v44, 0xbfb8aa3b, v32
	v_fmac_f32_e32 v41, 0xbfb8aa3b, v37
	v_fmac_f32_e32 v45, 0xbfb8aa3b, v33
	v_fmac_f32_e32 v42, 0xbfb8aa3b, v38
	v_fmac_f32_e32 v46, 0xbfb8aa3b, v34
	v_fmac_f32_e32 v43, 0xbfb8aa3b, v39
	v_fmac_f32_e32 v47, 0xbfb8aa3b, v35
	v_exp_f32_e32 v32, v40
	v_exp_f32_e32 v33, v44
	v_exp_f32_e32 v34, v41
	v_exp_f32_e32 v35, v45
	v_exp_f32_e32 v36, v42
	v_exp_f32_e32 v37, v46
	v_exp_f32_e32 v38, v43
	v_exp_f32_e32 v39, v47
	v_add_f32_e32 v32, 1.0, v32
	v_add_f32_e32 v33, 1.0, v33
	v_add_f32_e32 v34, 1.0, v34
	v_add_f32_e32 v35, 1.0, v35
	v_add_f32_e32 v40, 1.0, v36
	v_add_f32_e32 v41, 1.0, v37
	v_add_f32_e32 v42, 1.0, v38
	v_add_f32_e32 v43, 1.0, v39
	v_rcp_f32_e32 v36, v32
	v_rcp_f32_e32 v32, v33
	v_rcp_f32_e32 v37, v34
	v_rcp_f32_e32 v33, v35
	v_rcp_f32_e32 v38, v40
	v_rcp_f32_e32 v34, v41
	v_rcp_f32_e32 v39, v42
	v_rcp_f32_e32 v35, v43
.LBB0_791:
	v_add_co_u32_e32 v40, vcc, 0x1c0000, v104
	v_cvt_pk_bf16_f32 v36, v36, v37
	v_cvt_pk_bf16_f32 v37, v38, v39
	v_cvt_pk_bf16_f32 v38, v32, v33
	v_cvt_pk_bf16_f32 v39, v34, v35
	s_nop 1
	v_addc_co_u32_e32 v41, vcc, 0, v105, vcc
	ds_write_b128 v153, v[36:39] offset:64
	ds_read_b128 v[36:39], v154
	ds_read_b128 v[32:35], v154 offset:1152
	s_waitcnt lgkmcnt(4)
	global_store_dwordx4 v[40:41], v[52:55], off
	v_add_co_u32_e32 v40, vcc, 0x1dc000, v104
	s_nop 1
	v_addc_co_u32_e32 v41, vcc, 0, v105, vcc
	s_and_b64 vcc, exec, s[6:7]
	global_store_dwordx4 v[40:41], v[48:51], off
	s_cbranch_vccnz .LBB0_793
	v_mov_b32_e32 v40, v176
	v_mov_b32_e32 v44, v180
	v_mov_b32_e32 v41, v177
	v_mov_b32_e32 v45, v181
	v_mov_b32_e32 v42, v178
	v_mov_b32_e32 v46, v182
	v_mov_b32_e32 v43, v179
	v_mov_b32_e32 v47, v183
	v_fmac_f32_e32 v40, 0xbfb8aa3b, v28
	v_fmac_f32_e32 v44, 0xbfb8aa3b, v24
	v_fmac_f32_e32 v41, 0xbfb8aa3b, v29
	v_fmac_f32_e32 v45, 0xbfb8aa3b, v25
	v_fmac_f32_e32 v42, 0xbfb8aa3b, v30
	v_fmac_f32_e32 v46, 0xbfb8aa3b, v26
	v_fmac_f32_e32 v43, 0xbfb8aa3b, v31
	v_fmac_f32_e32 v47, 0xbfb8aa3b, v27
	v_exp_f32_e32 v24, v40
	v_exp_f32_e32 v25, v44
	v_exp_f32_e32 v26, v41
	v_exp_f32_e32 v27, v45
	v_exp_f32_e32 v28, v42
	v_exp_f32_e32 v29, v46
	v_exp_f32_e32 v30, v43
	v_exp_f32_e32 v31, v47
	v_add_f32_e32 v24, 1.0, v24
	v_add_f32_e32 v25, 1.0, v25
	v_add_f32_e32 v26, 1.0, v26
	v_add_f32_e32 v27, 1.0, v27
	v_add_f32_e32 v40, 1.0, v28
	v_add_f32_e32 v41, 1.0, v29
	v_add_f32_e32 v42, 1.0, v30
	v_add_f32_e32 v43, 1.0, v31
	v_rcp_f32_e32 v28, v24
	v_rcp_f32_e32 v24, v25
	v_rcp_f32_e32 v29, v26
	v_rcp_f32_e32 v25, v27
	v_rcp_f32_e32 v30, v40
	v_rcp_f32_e32 v26, v41
	v_rcp_f32_e32 v31, v42
	v_rcp_f32_e32 v27, v43
; __device__ __forceinline__ unsigned cvt_pk_bf16(float lo, float hi) { unsigned r; asm volatile("v_cvt_pk_bf16_f32 %0, %1, %2" : "=v"(r) : "v"(lo), "v"(hi)); return r; }
; #define GAS1 __attribute__((address_space(1)))
;     __device__ __forceinline__ void operator()(const f32x4 (&acc)[2][2][4][2], const Unit& u, int wr, int wc, int fr, int fq) const {
;     ...
;                         const f32x4 b0 = *(const GAS1 f32x4*)(bias + col) * -1.4426950408889634f, b1 = *(const GAS1 f32x4*)(bias + col + 4) * -1.4426950408889634f;
; #pragma unroll
;                         for (int j = 0; j < 4; ++j) { v0[j] = __builtin_amdgcn_rcpf(1.0f + __builtin_amdgcn_exp2f(__builtin_fmaf(v0[j], -1.4426950408889634f, b0[j])));
;                                                       v1[j] = __builtin_amdgcn_rcpf(1.0f + __builtin_amdgcn_exp2f(__builtin_fmaf(v1[j], -1.4426950408889634f, b1[j]))); }
;     ...
;                 u32x4 w; w.x = cvt_pk_bf16(v0[0], v0[1]); w.y = cvt_pk_bf16(v0[2], v0[3]); w.z = cvt_pk_bf16(v1[0], v1[1]); w.w = cvt_pk_bf16(v1[2], v1[3]);
;                 if (bj == 0) asm volatile("ds_write_b128 %0, %1" :: "v"(wa), "v"(w)); else asm volatile("ds_write_b128 %0, %1 offset:64" :: "v"(wa), "v"(w));
;             }
;             asm volatile("ds_read_b128 %0, %1" : "=&v"(rb[g & 1][0]) : "v"(ra));
;             asm volatile("ds_read_b128 %0, %1 offset:1152" : "=&v"(rb[g & 1][1]) : "v"(ra));
;             if (g >= 1) {
;                 asm volatile("s_waitcnt lgkmcnt(4)" : "+v"(rb[(g - 1) & 1][0]), "+v"(rb[(g - 1) & 1][1]));
;                 bf16_t* ob = obase + (size_t)(((g - 1) >> 2) * HALF + ((g - 1) & 3) * 16) * ldc;
;                 *(GAS1 u32x4*)ob = rb[(g - 1) & 1][0]; *(GAS1 u32x4*)(ob + (size_t)8 * ldc) = rb[(g - 1) & 1][1];
;             }
.LBB0_793:
	s_and_b64 vcc, exec, s[6:7]
	v_cvt_pk_bf16_f32 v28, v28, v29
	v_cvt_pk_bf16_f32 v29, v30, v31
	v_cvt_pk_bf16_f32 v30, v24, v25
	v_cvt_pk_bf16_f32 v31, v26, v27
	s_nop 0
	ds_write_b128 v153, v[28:31]
	s_cbranch_vccnz .LBB0_795
	v_mov_b32_e32 v24, v184
	v_mov_b32_e32 v28, v188
	v_mov_b32_e32 v25, v185
	v_mov_b32_e32 v29, v189
	v_mov_b32_e32 v26, v186
	v_mov_b32_e32 v30, v190
	v_mov_b32_e32 v27, v187
	v_mov_b32_e32 v31, v191
	v_fmac_f32_e32 v24, 0xbfb8aa3b, v20
	v_fmac_f32_e32 v28, 0xbfb8aa3b, v16
	v_fmac_f32_e32 v25, 0xbfb8aa3b, v21
	v_fmac_f32_e32 v29, 0xbfb8aa3b, v17
	v_fmac_f32_e32 v26, 0xbfb8aa3b, v22
	v_fmac_f32_e32 v30, 0xbfb8aa3b, v18
	v_fmac_f32_e32 v27, 0xbfb8aa3b, v23
	v_fmac_f32_e32 v31, 0xbfb8aa3b, v19
	v_exp_f32_e32 v16, v24
	v_exp_f32_e32 v17, v28
	v_exp_f32_e32 v18, v25
	v_exp_f32_e32 v19, v29
	v_exp_f32_e32 v20, v26
	v_exp_f32_e32 v21, v30
	v_exp_f32_e32 v22, v27
	v_exp_f32_e32 v23, v31
	v_add_f32_e32 v16, 1.0, v16
	v_add_f32_e32 v17, 1.0, v17
	v_add_f32_e32 v18, 1.0, v18
	v_add_f32_e32 v19, 1.0, v19
	v_add_f32_e32 v24, 1.0, v20
	v_add_f32_e32 v25, 1.0, v21
	v_add_f32_e32 v26, 1.0, v22
	v_add_f32_e32 v27, 1.0, v23
	v_rcp_f32_e32 v20, v16
	v_rcp_f32_e32 v16, v17
	v_rcp_f32_e32 v21, v18
	v_rcp_f32_e32 v17, v19
	v_rcp_f32_e32 v22, v24
	v_rcp_f32_e32 v18, v25
	v_rcp_f32_e32 v23, v26
	v_rcp_f32_e32 v19, v27
.LBB0_795:
	v_add_co_u32_e32 v24, vcc, 0x1f8000, v104
	v_cvt_pk_bf16_f32 v20, v20, v21
	v_cvt_pk_bf16_f32 v21, v22, v23
	v_cvt_pk_bf16_f32 v22, v16, v17
	v_cvt_pk_bf16_f32 v23, v18, v19
	s_nop 1
	v_addc_co_u32_e32 v25, vcc, 0, v105, vcc
	ds_write_b128 v153, v[20:23] offset:64
	ds_read_b128 v[20:23], v154
	ds_read_b128 v[16:19], v154 offset:1152
	s_waitcnt lgkmcnt(4)
	global_store_dwordx4 v[24:25], v[36:39], off
	v_add_co_u32_e32 v24, vcc, 0x214000, v104
	s_nop 1
	v_addc_co_u32_e32 v25, vcc, 0, v105, vcc
	s_and_b64 vcc, exec, s[6:7]
	global_store_dwordx4 v[24:25], v[32:35], off
	s_cbranch_vccnz .LBB0_797
	v_mov_b32_e32 v24, v176
	v_mov_b32_e32 v28, v180
	v_mov_b32_e32 v25, v177
	v_mov_b32_e32 v29, v181
	v_mov_b32_e32 v26, v178
	v_mov_b32_e32 v30, v182
	v_mov_b32_e32 v27, v179
	v_mov_b32_e32 v31, v183
	v_fmac_f32_e32 v24, 0xbfb8aa3b, v12
	v_fmac_f32_e32 v28, 0xbfb8aa3b, v8
	v_fmac_f32_e32 v25, 0xbfb8aa3b, v13
	v_fmac_f32_e32 v29, 0xbfb8aa3b, v9
	v_fmac_f32_e32 v26, 0xbfb8aa3b, v14
	v_fmac_f32_e32 v30, 0xbfb8aa3b, v10
	v_fmac_f32_e32 v27, 0xbfb8aa3b, v15
	v_fmac_f32_e32 v31, 0xbfb8aa3b, v11
	v_exp_f32_e32 v8, v24
	v_exp_f32_e32 v9, v28
	v_exp_f32_e32 v10, v25
	v_exp_f32_e32 v11, v29
	v_exp_f32_e32 v12, v26
	v_exp_f32_e32 v13, v30
	v_exp_f32_e32 v14, v27
	v_exp_f32_e32 v15, v31
	v_add_f32_e32 v8, 1.0, v8
	v_add_f32_e32 v9, 1.0, v9
	v_add_f32_e32 v10, 1.0, v10
	v_add_f32_e32 v11, 1.0, v11
	v_add_f32_e32 v24, 1.0, v12
	v_add_f32_e32 v25, 1.0, v13
	v_add_f32_e32 v26, 1.0, v14
	v_add_f32_e32 v27, 1.0, v15
	v_rcp_f32_e32 v12, v8
	v_rcp_f32_e32 v8, v9
	v_rcp_f32_e32 v13, v10
	v_rcp_f32_e32 v9, v11
	v_rcp_f32_e32 v14, v24
	v_rcp_f32_e32 v10, v25
	v_rcp_f32_e32 v15, v26
	v_rcp_f32_e32 v11, v27
.LBB0_797:
	s_and_b64 vcc, exec, s[6:7]
	v_cvt_pk_bf16_f32 v12, v12, v13
	v_cvt_pk_bf16_f32 v13, v14, v15
	v_cvt_pk_bf16_f32 v14, v8, v9
	v_cvt_pk_bf16_f32 v15, v10, v11
	s_nop 0
	ds_write_b128 v153, v[12:15]
	s_cbranch_vccnz .LBB0_799
	v_mov_b32_e32 v8, v184
	v_mov_b32_e32 v12, v188
	v_mov_b32_e32 v9, v185
	v_mov_b32_e32 v13, v189
	v_mov_b32_e32 v10, v186
	v_mov_b32_e32 v14, v190
	v_mov_b32_e32 v11, v187
	v_mov_b32_e32 v15, v191
	v_fmac_f32_e32 v8, 0xbfb8aa3b, v4
	v_fmac_f32_e32 v12, 0xbfb8aa3b, v0
	v_fmac_f32_e32 v9, 0xbfb8aa3b, v5
	v_fmac_f32_e32 v13, 0xbfb8aa3b, v1
	v_fmac_f32_e32 v10, 0xbfb8aa3b, v6
	v_fmac_f32_e32 v14, 0xbfb8aa3b, v2
	v_fmac_f32_e32 v11, 0xbfb8aa3b, v7
	v_fmac_f32_e32 v15, 0xbfb8aa3b, v3
	v_exp_f32_e32 v0, v8
	v_exp_f32_e32 v1, v12
	v_exp_f32_e32 v2, v9
	v_exp_f32_e32 v3, v13
	v_exp_f32_e32 v4, v10
	v_exp_f32_e32 v5, v14
	v_exp_f32_e32 v6, v11
	v_exp_f32_e32 v7, v15
	v_add_f32_e32 v0, 1.0, v0
	v_add_f32_e32 v1, 1.0, v1
	v_add_f32_e32 v2, 1.0, v2
	v_add_f32_e32 v3, 1.0, v3
	v_add_f32_e32 v8, 1.0, v4
	v_add_f32_e32 v9, 1.0, v5
	v_add_f32_e32 v10, 1.0, v6
	v_add_f32_e32 v11, 1.0, v7
	v_rcp_f32_e32 v4, v0
	v_rcp_f32_e32 v0, v1
	v_rcp_f32_e32 v5, v2
	v_rcp_f32_e32 v1, v3
	v_rcp_f32_e32 v6, v8
	v_rcp_f32_e32 v2, v9
	v_rcp_f32_e32 v7, v10
	v_rcp_f32_e32 v3, v11

; __device__ __forceinline__ unsigned cvt_pk_bf16(float lo, float hi) { unsigned r; asm volatile("v_cvt_pk_bf16_f32 %0, %1, %2" : "=v"(r) : "v"(lo), "v"(hi)); return r; }
; #define LAS __attribute__((address_space(3)))
; template <bool MLA, bool grpB>
; __device__ __forceinline__ void attn_unit_g(LAS unsigned char* lds, const AttnPtrs& P, int b, int h, int qblk) {
;     ...
;         float ps = 0.f;
; #pragma unroll
;         for (int blk = 0; blk < 2; ++blk)
; #pragma unroll
;             for (int r = 0; r < 16; ++r) { const float pv_ = __builtin_amdgcn_exp2f(sc[blk][r] - mref); sc[blk][r] = pv_; ps += pv_; }
;         lrun += ps;
; #pragma unroll
;         for (int blk = 0; blk < 2; ++blk)
; #pragma unroll
;             for (int ks = 0; ks < 2; ++ks) { u32x4 w;
;                 w.x = pg8::cvt_pk_bf16(sc[blk][8 * ks + 0], sc[blk][8 * ks + 1]); w.y = pg8::cvt_pk_bf16(sc[blk][8 * ks + 2], sc[blk][8 * ks + 3]);
;                 w.z = pg8::cvt_pk_bf16(sc[blk][8 * ks + 4], sc[blk][8 * ks + 5]); w.w = pg8::cvt_pk_bf16(sc[blk][8 * ks + 6], sc[blk][8 * ks + 7]);
;                 pb[blk][ks] = __builtin_bit_cast(bf16x8, w); }
;         __builtin_amdgcn_sched_barrier(0);
;     };
;     auto pv = [&](int voff) {
;         const LAS unsigned char* va = lds + varow + voff;
;         bf16x8 a[PFD];
;         auto ld = [&](int i) -> bf16x8 {
;             const int dvb = i & 3, bk = i >> 2, so = ((4 * (bk >> 1) + 2 * hi + (bk & 1)) ^ vswz) * 16;
;             return *(const LAS bf16x8*)(va + 32 * dvb * VROW + so);
;         };
; #pragma unroll
;         for (int i = 0; i < PFD; ++i) a[i] = ld(i);
; #pragma unroll
;         for (int i = 0; i < 16; ++i) {
;             o[i & 3] = __builtin_amdgcn_mfma_f32_32x32x16_bf16(a[i % PFD], pb[i >> 3][(i >> 2) & 1], o[i & 3], 0, 0, 0);
;             if (i + PFD < 16) a[i % PFD] = ld(i + PFD);
;         }
;         __builtin_amdgcn_sched_group_barrier(0x100, PFD, 0);
; #pragma unroll
;         for (int i = 0; i < 16; ++i) { __builtin_amdgcn_sched_group_barrier(0x008, 1, 0); __builtin_amdgcn_sched_group_barrier(0x100, 1, 0); }
;         __builtin_amdgcn_sched_barrier(0);
.LBB0_1151:
	v_sub_f32_e32 v18, v18, v178
	v_exp_f32_e32 v18, v18
	v_sub_f32_e32 v19, v19, v178
	v_exp_f32_e32 v19, v19
	v_sub_f32_e32 v20, v20, v178
	v_exp_f32_e32 v20, v20
	v_sub_f32_e32 v21, v21, v178
	v_exp_f32_e32 v21, v21
	v_sub_f32_e32 v22, v22, v178
	v_add_f32_e32 v179, 0, v18
	v_exp_f32_e32 v22, v22
	v_sub_f32_e32 v23, v23, v178
	v_add_f32_e32 v179, v19, v179
	v_exp_f32_e32 v23, v23
	v_sub_f32_e32 v24, v24, v178
	v_add_f32_e32 v179, v20, v179
	v_exp_f32_e32 v24, v24
	v_sub_f32_e32 v25, v25, v178
	v_add_f32_e32 v179, v21, v179
	v_exp_f32_e32 v25, v25
	v_sub_f32_e32 v26, v26, v178
	v_add_f32_e32 v179, v22, v179
	v_exp_f32_e32 v26, v26
	v_sub_f32_e32 v27, v27, v178
	v_add_f32_e32 v179, v23, v179
	v_exp_f32_e32 v27, v27
	v_sub_f32_e32 v28, v28, v178
	v_add_f32_e32 v179, v24, v179
	v_exp_f32_e32 v28, v28
	v_sub_f32_e32 v29, v29, v178
	v_add_f32_e32 v179, v25, v179
	v_exp_f32_e32 v29, v29
	v_sub_f32_e32 v30, v30, v178
	v_add_f32_e32 v179, v26, v179
	v_exp_f32_e32 v30, v30
	v_sub_f32_e32 v31, v31, v178
	v_add_f32_e32 v179, v27, v179
	v_exp_f32_e32 v31, v31
	v_sub_f32_e32 v32, v32, v178
	v_add_f32_e32 v179, v28, v179
	v_exp_f32_e32 v32, v32
	v_sub_f32_e32 v33, v33, v178
	v_add_f32_e32 v179, v29, v179
	v_exp_f32_e32 v33, v33
	v_sub_f32_e32 v50, v50, v178
	v_add_f32_e32 v179, v30, v179
	v_exp_f32_e32 v50, v50
	v_sub_f32_e32 v51, v51, v178
	v_add_f32_e32 v179, v31, v179
	v_exp_f32_e32 v51, v51
	v_sub_f32_e32 v52, v52, v178
	v_add_f32_e32 v179, v32, v179
	v_exp_f32_e32 v52, v52
	v_sub_f32_e32 v53, v53, v178
	v_add_f32_e32 v179, v33, v179
	v_exp_f32_e32 v53, v53
	v_sub_f32_e32 v54, v54, v178
	v_add_f32_e32 v179, v50, v179
	v_exp_f32_e32 v54, v54
	v_sub_f32_e32 v55, v55, v178
	v_add_f32_e32 v179, v51, v179
	v_exp_f32_e32 v55, v55
	v_sub_f32_e32 v56, v56, v178
	v_add_f32_e32 v179, v52, v179
	v_exp_f32_e32 v56, v56
	v_sub_f32_e32 v57, v57, v178
	v_add_f32_e32 v179, v53, v179
	v_exp_f32_e32 v57, v57
	v_sub_f32_e32 v58, v58, v178
	v_add_f32_e32 v179, v54, v179
	v_exp_f32_e32 v58, v58
	v_sub_f32_e32 v59, v59, v178
	v_add_f32_e32 v179, v55, v179
	v_exp_f32_e32 v59, v59
	v_sub_f32_e32 v60, v60, v178
	v_add_f32_e32 v179, v56, v179
	v_exp_f32_e32 v60, v60
	v_sub_f32_e32 v61, v61, v178
	v_add_f32_e32 v179, v57, v179
	v_exp_f32_e32 v61, v61
	v_sub_f32_e32 v62, v62, v178
	v_add_f32_e32 v179, v58, v179
	v_exp_f32_e32 v62, v62
	v_sub_f32_e32 v63, v63, v178
	v_add_f32_e32 v179, v59, v179
	v_exp_f32_e32 v63, v63
	v_sub_f32_e32 v64, v64, v178
	v_add_f32_e32 v179, v60, v179
	v_exp_f32_e32 v64, v64
	v_sub_f32_e32 v65, v65, v178
	v_add_f32_e32 v179, v61, v179
	v_exp_f32_e32 v65, v65
	v_add_f32_e32 v179, v62, v179
	v_add_f32_e32 v179, v63, v179
	v_add_f32_e32 v179, v64, v179
	v_add_f32_e32 v179, v65, v179
	v_add_f32_e32 v176, v176, v179
	v_cvt_pk_bf16_f32 v180, v18, v19
	v_cvt_pk_bf16_f32 v181, v20, v21
	v_cvt_pk_bf16_f32 v182, v22, v23
	v_cvt_pk_bf16_f32 v183, v24, v25
	v_cvt_pk_bf16_f32 v184, v26, v27
	v_cvt_pk_bf16_f32 v185, v28, v29
	v_cvt_pk_bf16_f32 v186, v30, v31
	v_cvt_pk_bf16_f32 v187, v32, v33
	v_cvt_pk_bf16_f32 v188, v50, v51
	v_cvt_pk_bf16_f32 v189, v52, v53
	v_cvt_pk_bf16_f32 v190, v54, v55
	v_cvt_pk_bf16_f32 v191, v56, v57
	v_cvt_pk_bf16_f32 v192, v58, v59
	v_cvt_pk_bf16_f32 v193, v60, v61
	v_cvt_pk_bf16_f32 v194, v62, v63
	v_cvt_pk_bf16_f32 v195, v64, v65
	v_add_u32_e32 v179, s12, v167
	v_add_u32_e32 v210, v179, v168
	ds_read_b128 v[196:199], v210
	ds_read_b128 v[202:205], v210 offset:4096
	ds_read_b128 v[206:209], v210 offset:8192
	ds_read_b128 v[210:213], v210 offset:12288
	v_add_u32_e32 v222, v179, v169
	ds_read_b128 v[214:217], v222
	ds_read_b128 v[218:221], v222 offset:4096
	s_waitcnt lgkmcnt(5)
	v_mfma_f32_32x32x16_bf16 v[82:97], v[196:199], v[180:183], v[82:97]
	ds_read_b128 v[196:199], v222 offset:8192
	s_waitcnt lgkmcnt(5)
	v_mfma_f32_32x32x16_bf16 v[66:81], v[202:205], v[180:183], v[66:81]
	ds_read_b128 v[202:205], v222 offset:12288
	v_add_u32_e32 v222, v179, v175
	v_add_u32_e32 v179, v179, v177
	s_waitcnt lgkmcnt(5)
	v_mfma_f32_32x32x16_bf16 v[34:49], v[206:209], v[180:183], v[34:49]
	ds_read_b128 v[206:209], v222
	s_waitcnt lgkmcnt(5)
	v_mfma_f32_32x32x16_bf16 v[2:17], v[210:213], v[180:183], v[2:17]
	ds_read_b128 v[180:183], v222 offset:4096
	s_waitcnt lgkmcnt(5)
	v_mfma_f32_32x32x16_bf16 v[82:97], v[214:217], v[184:187], v[82:97]
	ds_read_b128 v[210:213], v222 offset:8192
	s_waitcnt lgkmcnt(5)
	v_mfma_f32_32x32x16_bf16 v[66:81], v[218:221], v[184:187], v[66:81]
	ds_read_b128 v[214:217], v222 offset:12288
	s_waitcnt lgkmcnt(5)
	v_mfma_f32_32x32x16_bf16 v[34:49], v[196:199], v[184:187], v[34:49]
	ds_read_b128 v[196:199], v179
	s_waitcnt lgkmcnt(5)
	v_mfma_f32_32x32x16_bf16 v[2:17], v[202:205], v[184:187], v[2:17]
	ds_read_b128 v[184:187], v179 offset:4096
	s_waitcnt lgkmcnt(5)
	v_mfma_f32_32x32x16_bf16 v[82:97], v[206:209], v[188:191], v[82:97]
	ds_read_b128 v[202:205], v179 offset:8192
	s_waitcnt lgkmcnt(5)
	v_mfma_f32_32x32x16_bf16 v[66:81], v[180:183], v[188:191], v[66:81]
	ds_read_b128 v[180:183], v179 offset:12288
	s_waitcnt lgkmcnt(5)
	v_mfma_f32_32x32x16_bf16 v[34:49], v[210:213], v[188:191], v[34:49]
	s_waitcnt lgkmcnt(4)
	v_mfma_f32_32x32x16_bf16 v[2:17], v[214:217], v[188:191], v[2:17]
	s_waitcnt lgkmcnt(3)
	v_mfma_f32_32x32x16_bf16 v[82:97], v[196:199], v[192:195], v[82:97]
	s_waitcnt lgkmcnt(2)
	v_mfma_f32_32x32x16_bf16 v[66:81], v[184:187], v[192:195], v[66:81]
	s_waitcnt lgkmcnt(1)
	v_mfma_f32_32x32x16_bf16 v[34:49], v[202:205], v[192:195], v[34:49]
	s_waitcnt lgkmcnt(0)
	v_mfma_f32_32x32x16_bf16 v[2:17], v[180:183], v[192:195], v[2:17]
; #define LAS __attribute__((address_space(3)))
; template <bool MLA, bool grpB>
; __device__ __forceinline__ void attn_unit_g(LAS unsigned char* lds, const AttnPtrs& P, int b, int h, int qblk) {
;     ...
;         const LAS unsigned char* ka = lds + koff + karow;
;         bf16x8 a[PFD];
;         auto ld = [&](int i) -> bf16x8 {
;             const int d0 = i >> 1, blk = i & 1, seg = 2 * d0;
;             int so;
;             if (MLA) so = (((seg + hi) & 24) | (((seg + hi) ^ kswz) & 7)) * 16; else so = ((seg + hi) ^ kswz) * 16;
;             return *(const LAS bf16x8*)(ka + blk * 32 * KROW + so);
;         };
; #pragma unroll
;         for (int i = 0; i < PFD; ++i) a[i] = ld(i);
; #pragma unroll
;         for (int i = 0; i < 2 * ND0; ++i) {
;             const f32x16 zc = {0.f, 0.f, 0.f, 0.f, 0.f, 0.f, 0.f, 0.f, 0.f, 0.f, 0.f, 0.f, 0.f, 0.f, 0.f, 0.f};
;             sc[i & 1] = __builtin_amdgcn_mfma_f32_32x32x16_bf16(a[i % PFD], qf[i >> 1], (MLA && i < 2) ? zc : sc[i & 1], 0, 0, 0);
;             if (i + PFD < 2 * ND0) a[i % PFD] = ld(i + PFD);
;         }
;         __builtin_amdgcn_sched_group_barrier(0x100, PFD, 0);
; #pragma unroll
;         for (int i = 0; i < 2 * ND0; ++i) { __builtin_amdgcn_sched_group_barrier(0x008, 1, 0); __builtin_amdgcn_sched_group_barrier(0x100, 1, 0); }
;         __builtin_amdgcn_sched_barrier(0);
;     ...
;         else { if (j <= my_last) { sm(j); pv(vcur); } if (j > 0 && j - 1 <= my_last) qk(knext); }
.LBB0_1152:
	s_cmp_eq_u32 s36, -3
	s_cselect_b64 s[26:27], -1, 0
	s_cmp_gt_i32 s16, s13
	s_cselect_b64 s[16:17], -1, 0
	s_or_b64 s[16:17], s[26:27], s[16:17]
	s_and_b64 vcc, exec, s[16:17]
	s_cbranch_vccnz .LBB0_1156
	v_add_u32_e32 v54, s23, v161
	v_add_u32_e32 v179, v54, v162
	ds_read_b128 v[18:21], v179
	ds_read_b128 v[50:53], v179 offset:12288
	v_add_u32_e32 v206, v54, v163
	v_add_u32_e32 v207, v54, v164
	ds_read_b128 v[180:183], v206
	ds_read_b128 v[184:187], v206 offset:12288
	v_add_u32_e32 v208, v54, v165
	ds_read_b128 v[188:191], v207
	ds_read_b128 v[192:195], v207 offset:12288
	s_waitcnt lgkmcnt(5)
	v_mfma_f32_32x32x16_bf16 v[18:33], v[18:21], v[98:101], 0
	ds_read_b128 v[196:199], v208
	s_waitcnt lgkmcnt(5)
	v_mfma_f32_32x32x16_bf16 v[50:65], v[50:53], v[98:101], 0
	ds_read_b128 v[202:205], v208 offset:12288
	s_waitcnt lgkmcnt(5)
	v_mfma_f32_32x32x16_bf16 v[18:33], v[180:183], v[102:105], v[18:33]
	ds_read_b128 v[180:183], v179 offset:128
	s_waitcnt lgkmcnt(5)
	v_mfma_f32_32x32x16_bf16 v[50:65], v[184:187], v[102:105], v[50:65]
	ds_read_b128 v[184:187], v179 offset:12416
	s_waitcnt lgkmcnt(5)
	v_mfma_f32_32x32x16_bf16 v[18:33], v[188:191], v[106:109], v[18:33]
	ds_read_b128 v[188:191], v206 offset:128
	s_waitcnt lgkmcnt(5)
	v_mfma_f32_32x32x16_bf16 v[50:65], v[192:195], v[106:109], v[50:65]
	ds_read_b128 v[192:195], v206 offset:12416
	s_waitcnt lgkmcnt(5)
	v_mfma_f32_32x32x16_bf16 v[18:33], v[196:199], v[110:113], v[18:33]
	ds_read_b128 v[196:199], v207 offset:128
	s_waitcnt lgkmcnt(5)
	v_mfma_f32_32x32x16_bf16 v[50:65], v[202:205], v[110:113], v[50:65]
	ds_read_b128 v[202:205], v207 offset:12416
	s_waitcnt lgkmcnt(5)
	v_mfma_f32_32x32x16_bf16 v[18:33], v[180:183], v[114:117], v[18:33]
	ds_read_b128 v[180:183], v208 offset:128
	s_waitcnt lgkmcnt(5)
	v_mfma_f32_32x32x16_bf16 v[50:65], v[184:187], v[114:117], v[50:65]
	ds_read_b128 v[184:187], v208 offset:12416
	s_waitcnt lgkmcnt(5)
	v_mfma_f32_32x32x16_bf16 v[18:33], v[188:191], v[118:121], v[18:33]
	ds_read_b128 v[188:191], v179 offset:256
	s_waitcnt lgkmcnt(5)
	v_mfma_f32_32x32x16_bf16 v[50:65], v[192:195], v[118:121], v[50:65]
	ds_read_b128 v[192:195], v179 offset:12544
	s_waitcnt lgkmcnt(5)
	v_mfma_f32_32x32x16_bf16 v[18:33], v[196:199], v[122:125], v[18:33]
	ds_read_b128 v[196:199], v206 offset:256
	s_waitcnt lgkmcnt(5)
	v_mfma_f32_32x32x16_bf16 v[50:65], v[202:205], v[122:125], v[50:65]
	ds_read_b128 v[202:205], v206 offset:12544
	s_waitcnt lgkmcnt(5)
	v_mfma_f32_32x32x16_bf16 v[18:33], v[180:183], v[126:129], v[18:33]
	ds_read_b128 v[180:183], v207 offset:256
	s_waitcnt lgkmcnt(5)
	v_mfma_f32_32x32x16_bf16 v[50:65], v[184:187], v[126:129], v[50:65]
	ds_read_b128 v[184:187], v207 offset:12544
	s_waitcnt lgkmcnt(5)
	v_mfma_f32_32x32x16_bf16 v[18:33], v[188:191], v[130:133], v[18:33]
	ds_read_b128 v[188:191], v208 offset:256
	s_waitcnt lgkmcnt(5)
	v_mfma_f32_32x32x16_bf16 v[50:65], v[192:195], v[130:133], v[50:65]
	ds_read_b128 v[192:195], v208 offset:12544
	s_waitcnt lgkmcnt(5)
	v_mfma_f32_32x32x16_bf16 v[18:33], v[196:199], v[134:137], v[18:33]
	s_waitcnt lgkmcnt(4)
	v_mfma_f32_32x32x16_bf16 v[50:65], v[202:205], v[134:137], v[50:65]
	s_waitcnt lgkmcnt(3)
	v_mfma_f32_32x32x16_bf16 v[18:33], v[180:183], v[138:141], v[18:33]
	s_waitcnt lgkmcnt(2)
	v_mfma_f32_32x32x16_bf16 v[50:65], v[184:187], v[138:141], v[50:65]
	s_waitcnt lgkmcnt(1)
	v_mfma_f32_32x32x16_bf16 v[18:33], v[188:191], v[142:145], v[18:33]
	s_waitcnt lgkmcnt(0)
	v_mfma_f32_32x32x16_bf16 v[50:65], v[192:195], v[142:145], v[50:65]
	s_mov_b64 s[16:17], -1
	s_and_b64 vcc, exec, s[14:15]
	s_cbranch_vccnz .LBB0_1157

; template <bool MLA, bool grpB>
; __device__ __forceinline__ void attn_unit_g(LAS unsigned char* lds, const AttnPtrs& P, int b, int h, int qblk) {
;     ...
;         const LAS unsigned char* ka = lds + koff + karow;
;         bf16x8 a[PFD];
;         auto ld = [&](int i) -> bf16x8 {
;             const int d0 = i >> 1, blk = i & 1, seg = 2 * d0;
;             int so;
;             if (MLA) so = (((seg + hi) & 24) | (((seg + hi) ^ kswz) & 7)) * 16; else so = ((seg + hi) ^ kswz) * 16;
;             return *(const LAS bf16x8*)(ka + blk * 32 * KROW + so);
;         };
; #pragma unroll
;         for (int i = 0; i < PFD; ++i) a[i] = ld(i);
; #pragma unroll
;         for (int i = 0; i < 2 * ND0; ++i) {
;             const f32x16 zc = {0.f, 0.f, 0.f, 0.f, 0.f, 0.f, 0.f, 0.f, 0.f, 0.f, 0.f, 0.f, 0.f, 0.f, 0.f, 0.f};
;             sc[i & 1] = __builtin_amdgcn_mfma_f32_32x32x16_bf16(a[i % PFD], qf[i >> 1], (MLA && i < 2) ? zc : sc[i & 1], 0, 0, 0);
;             if (i + PFD < 2 * ND0) a[i % PFD] = ld(i + PFD);
;         }
;         __builtin_amdgcn_sched_group_barrier(0x100, PFD, 0);
; #pragma unroll
;         for (int i = 0; i < 2 * ND0; ++i) { __builtin_amdgcn_sched_group_barrier(0x008, 1, 0); __builtin_amdgcn_sched_group_barrier(0x100, 1, 0); }
;         __builtin_amdgcn_sched_barrier(0);
;     };
;     float mref = -1e30f;
;     auto sm = [&](int j) {
;         if (j >= my_last) {
;             if (MLA) { if (j > my_last) {
; #pragma unroll
;                 for (int r = 0; r < 16; ++r) { sc[0][r] = -2e30f; sc[1][r] = -2e30f; } } }
;             else { const int qpos = q0 + r32;
; #pragma unroll
;                 for (int blk = 0; blk < 2; ++blk)
; #pragma unroll
;                     for (int r = 0; r < 16; ++r) { const int key = 64 * j + 32 * blk + 16 * hi + r; if (key > qpos) sc[blk][r] = -2e30f; } }
;         }
;         float big_ = 3.0e38f; asm volatile("" : "+v"(big_));
;         float mxa = MAX2(sc[0][0], sc[0][1]), mxb = MAX2(sc[0][2], sc[0][3]), mxc = MAX2(sc[1][0], sc[1][1]), mxd = MAX2(sc[1][2], sc[1][3]);
; #pragma unroll
;         for (int r = 4; r < 16; r += 4) { mxa = MAX2(mxa, MAX2(sc[0][r], sc[0][r + 1])); mxb = MAX2(mxb, MAX2(sc[0][r + 2], sc[0][r + 3])); mxc = MAX2(mxc, MAX2(sc[1][r], sc[1][r + 1])); mxd = MAX2(mxd, MAX2(sc[1][r + 2], sc[1][r + 3])); }
;         float mx = MAX2(MAX2(mxa, mxb), MAX2(mxc, mxd));
.LBB0_1214:
	v_add_u32_e32 v0, s26, v179
	v_add_u32_e32 v14, v0, v183
	ds_read_b128 v[2:5], v14
	ds_read_b128 v[6:9], v14 offset:12288
	v_add_u32_e32 v15, v0, v184
	v_add_u32_e32 v198, v0, v185
	ds_read_b128 v[10:13], v15
	ds_read_b128 v[194:197], v15 offset:12288
	v_add_u32_e32 v0, v0, v186
	ds_read_b128 v[202:205], v198
	ds_read_b128 v[206:209], v198 offset:12288
	s_waitcnt lgkmcnt(5)
	v_mfma_f32_32x32x16_bf16 v[96:111], v[2:5], v[112:115], 0
	ds_read_b128 v[2:5], v0
	s_waitcnt lgkmcnt(5)
	v_mfma_f32_32x32x16_bf16 v[80:95], v[6:9], v[112:115], 0
	ds_read_b128 v[6:9], v0 offset:12288
	s_waitcnt lgkmcnt(5)
	v_mfma_f32_32x32x16_bf16 v[96:111], v[10:13], v[116:119], v[96:111]
	ds_read_b128 v[10:13], v14 offset:128
	s_waitcnt lgkmcnt(5)
	v_mfma_f32_32x32x16_bf16 v[80:95], v[194:197], v[116:119], v[80:95]
	ds_read_b128 v[194:197], v14 offset:12416
	s_waitcnt lgkmcnt(5)
	v_mfma_f32_32x32x16_bf16 v[96:111], v[202:205], v[120:123], v[96:111]
	ds_read_b128 v[202:205], v15 offset:128
	s_waitcnt lgkmcnt(5)
	v_mfma_f32_32x32x16_bf16 v[80:95], v[206:209], v[120:123], v[80:95]
	ds_read_b128 v[206:209], v15 offset:12416
	s_waitcnt lgkmcnt(5)
	v_mfma_f32_32x32x16_bf16 v[96:111], v[2:5], v[124:127], v[96:111]
	ds_read_b128 v[2:5], v198 offset:128
	s_waitcnt lgkmcnt(5)
	v_mfma_f32_32x32x16_bf16 v[80:95], v[6:9], v[124:127], v[80:95]
	ds_read_b128 v[6:9], v198 offset:12416
	s_waitcnt lgkmcnt(5)
	v_mfma_f32_32x32x16_bf16 v[96:111], v[10:13], v[128:131], v[96:111]
	ds_read_b128 v[10:13], v0 offset:128
	s_waitcnt lgkmcnt(5)
	v_mfma_f32_32x32x16_bf16 v[80:95], v[194:197], v[128:131], v[80:95]
	ds_read_b128 v[194:197], v0 offset:12416
	s_waitcnt lgkmcnt(5)
	v_mfma_f32_32x32x16_bf16 v[96:111], v[202:205], v[132:135], v[96:111]
	ds_read_b128 v[202:205], v14 offset:256
	s_waitcnt lgkmcnt(5)
	v_mfma_f32_32x32x16_bf16 v[80:95], v[206:209], v[132:135], v[80:95]
	ds_read_b128 v[206:209], v14 offset:12544
	s_waitcnt lgkmcnt(5)
	v_mfma_f32_32x32x16_bf16 v[96:111], v[2:5], v[136:139], v[96:111]
	ds_read_b128 v[2:5], v15 offset:256
	s_waitcnt lgkmcnt(5)
	v_mfma_f32_32x32x16_bf16 v[80:95], v[6:9], v[136:139], v[80:95]
	ds_read_b128 v[6:9], v15 offset:12544
	s_waitcnt lgkmcnt(5)
	v_mfma_f32_32x32x16_bf16 v[96:111], v[10:13], v[140:143], v[96:111]
	ds_read_b128 v[10:13], v198 offset:256
	s_waitcnt lgkmcnt(5)
	v_mfma_f32_32x32x16_bf16 v[80:95], v[194:197], v[140:143], v[80:95]
	ds_read_b128 v[194:197], v198 offset:12544
	s_waitcnt lgkmcnt(5)
	v_mfma_f32_32x32x16_bf16 v[96:111], v[202:205], v[144:147], v[96:111]
	ds_read_b128 v[202:205], v0 offset:256
	s_waitcnt lgkmcnt(5)
	v_mfma_f32_32x32x16_bf16 v[80:95], v[206:209], v[144:147], v[80:95]
	ds_read_b128 v[206:209], v0 offset:12544
	s_waitcnt lgkmcnt(5)
	v_mfma_f32_32x32x16_bf16 v[96:111], v[2:5], v[148:151], v[96:111]
	s_waitcnt lgkmcnt(4)
	v_mfma_f32_32x32x16_bf16 v[80:95], v[6:9], v[148:151], v[80:95]
	s_waitcnt lgkmcnt(3)
	v_mfma_f32_32x32x16_bf16 v[96:111], v[10:13], v[152:155], v[96:111]
	s_waitcnt lgkmcnt(2)
	v_mfma_f32_32x32x16_bf16 v[80:95], v[194:197], v[152:155], v[80:95]
	s_waitcnt lgkmcnt(1)
	v_mfma_f32_32x32x16_bf16 v[96:111], v[202:205], v[156:159], v[96:111]
	s_waitcnt lgkmcnt(0)
	v_mfma_f32_32x32x16_bf16 v[80:95], v[206:209], v[156:159], v[80:95]
	v_mov_b32_e32 v0, 0x7f61b1e6
	s_nop 9
	v_med3_f32 v2, v96, v97, v0
	v_med3_f32 v6, v100, v101, v0
	v_med3_f32 v3, v98, v99, v0
	v_med3_f32 v2, v2, v6, v0
	v_med3_f32 v6, v102, v103, v0
	v_med3_f32 v4, v80, v81, v0
	v_med3_f32 v3, v3, v6, v0
	v_med3_f32 v6, v84, v85, v0
	v_med3_f32 v5, v82, v83, v0
	v_med3_f32 v4, v4, v6, v0
	v_med3_f32 v6, v86, v87, v0
	v_med3_f32 v5, v5, v6, v0
	v_med3_f32 v6, v104, v105, v0
	v_med3_f32 v2, v2, v6, v0
	v_med3_f32 v6, v106, v107, v0
	v_med3_f32 v3, v3, v6, v0
	v_med3_f32 v6, v88, v89, v0
	v_med3_f32 v4, v4, v6, v0
	v_med3_f32 v6, v90, v91, v0
	v_med3_f32 v5, v5, v6, v0
	v_med3_f32 v6, v108, v109, v0
	v_med3_f32 v2, v2, v6, v0
	v_med3_f32 v6, v110, v111, v0
	v_med3_f32 v3, v3, v6, v0
	v_med3_f32 v6, v92, v93, v0
	v_med3_f32 v4, v4, v6, v0
	v_med3_f32 v6, v94, v95, v0
	v_med3_f32 v5, v5, v6, v0
	v_med3_f32 v2, v2, v3, v0
	v_med3_f32 v3, v4, v5, v0
	v_and_b32_e32 v4, 64, v171
	v_med3_f32 v2, v2, v3, v0
	v_xor_b32_e32 v3, 32, v171
	v_add_u32_e32 v4, 64, v4
	v_cmp_lt_i32_e32 vcc, v3, v4
	s_nop 1
	v_cndmask_b32_e32 v3, v171, v3, vcc
	v_lshlrev_b32_e32 v3, 2, v3
	ds_bpermute_b32 v3, v3, v2
	s_waitcnt lgkmcnt(0)
	v_med3_f32 v0, v2, v3, v0
	v_add_f32_e32 v2, 0x41000000, v193
	v_cmp_gt_f32_e32 vcc, v0, v2
	s_cbranch_vccz .LBB0_1216
	v_max_f32_e32 v0, v0, v0
	v_max_f32_e32 v2, v193, v193
	v_max_f32_e32 v2, v2, v0
	v_sub_f32_e32 v0, v193, v2
	v_exp_f32_e32 v0, v0
	v_mov_b32_e32 v193, v2
	v_mul_f32_e32 v192, v192, v0
	v_pk_mul_f32 v[78:79], v[78:79], v[0:1] op_sel_hi:[1,0]
	v_pk_mul_f32 v[76:77], v[76:77], v[0:1] op_sel_hi:[1,0]
	v_pk_mul_f32 v[74:75], v[74:75], v[0:1] op_sel_hi:[1,0]
	v_pk_mul_f32 v[72:73], v[72:73], v[0:1] op_sel_hi:[1,0]
	v_pk_mul_f32 v[70:71], v[70:71], v[0:1] op_sel_hi:[1,0]
	v_pk_mul_f32 v[68:69], v[68:69], v[0:1] op_sel_hi:[1,0]
	v_pk_mul_f32 v[66:67], v[66:67], v[0:1] op_sel_hi:[1,0]
	v_pk_mul_f32 v[64:65], v[64:65], v[0:1] op_sel_hi:[1,0]
	v_pk_mul_f32 v[62:63], v[62:63], v[0:1] op_sel_hi:[1,0]
	v_pk_mul_f32 v[60:61], v[60:61], v[0:1] op_sel_hi:[1,0]
	v_pk_mul_f32 v[58:59], v[58:59], v[0:1] op_sel_hi:[1,0]
	v_pk_mul_f32 v[56:57], v[56:57], v[0:1] op_sel_hi:[1,0]
	v_pk_mul_f32 v[54:55], v[54:55], v[0:1] op_sel_hi:[1,0]
	v_pk_mul_f32 v[52:53], v[52:53], v[0:1] op_sel_hi:[1,0]
	v_pk_mul_f32 v[50:51], v[50:51], v[0:1] op_sel_hi:[1,0]
	v_pk_mul_f32 v[48:49], v[48:49], v[0:1] op_sel_hi:[1,0]
	v_pk_mul_f32 v[46:47], v[46:47], v[0:1] op_sel_hi:[1,0]
	v_pk_mul_f32 v[44:45], v[44:45], v[0:1] op_sel_hi:[1,0]
	v_pk_mul_f32 v[42:43], v[42:43], v[0:1] op_sel_hi:[1,0]
	v_pk_mul_f32 v[40:41], v[40:41], v[0:1] op_sel_hi:[1,0]
	v_pk_mul_f32 v[38:39], v[38:39], v[0:1] op_sel_hi:[1,0]
	v_pk_mul_f32 v[36:37], v[36:37], v[0:1] op_sel_hi:[1,0]
	v_pk_mul_f32 v[34:35], v[34:35], v[0:1] op_sel_hi:[1,0]
	v_pk_mul_f32 v[32:33], v[32:33], v[0:1] op_sel_hi:[1,0]
	v_pk_mul_f32 v[30:31], v[30:31], v[0:1] op_sel_hi:[1,0]
	v_pk_mul_f32 v[28:29], v[28:29], v[0:1] op_sel_hi:[1,0]
	v_pk_mul_f32 v[26:27], v[26:27], v[0:1] op_sel_hi:[1,0]
	v_pk_mul_f32 v[24:25], v[24:25], v[0:1] op_sel_hi:[1,0]
	v_pk_mul_f32 v[22:23], v[22:23], v[0:1] op_sel_hi:[1,0]
	v_pk_mul_f32 v[20:21], v[20:21], v[0:1] op_sel_hi:[1,0]
	v_pk_mul_f32 v[18:19], v[18:19], v[0:1] op_sel_hi:[1,0]
	v_pk_mul_f32 v[16:17], v[16:17], v[0:1] op_sel_hi:[1,0]
; __device__ __forceinline__ unsigned cvt_pk_bf16(float lo, float hi) { unsigned r; asm volatile("v_cvt_pk_bf16_f32 %0, %1, %2" : "=v"(r) : "v"(lo), "v"(hi)); return r; }
; #define LAS __attribute__((address_space(3)))
; template <bool MLA, bool grpB>
; __device__ __forceinline__ void attn_unit_g(LAS unsigned char* lds, const AttnPtrs& P, int b, int h, int qblk) {
;     ...
;         float ps = 0.f;
; #pragma unroll
;         for (int blk = 0; blk < 2; ++blk)
; #pragma unroll
;             for (int r = 0; r < 16; ++r) { const float pv_ = __builtin_amdgcn_exp2f(sc[blk][r] - mref); sc[blk][r] = pv_; ps += pv_; }
;         lrun += ps;
; #pragma unroll
;         for (int blk = 0; blk < 2; ++blk)
; #pragma unroll
;             for (int ks = 0; ks < 2; ++ks) { u32x4 w;
;                 w.x = pg8::cvt_pk_bf16(sc[blk][8 * ks + 0], sc[blk][8 * ks + 1]); w.y = pg8::cvt_pk_bf16(sc[blk][8 * ks + 2], sc[blk][8 * ks + 3]);
;                 w.z = pg8::cvt_pk_bf16(sc[blk][8 * ks + 4], sc[blk][8 * ks + 5]); w.w = pg8::cvt_pk_bf16(sc[blk][8 * ks + 6], sc[blk][8 * ks + 7]);
;                 pb[blk][ks] = __builtin_bit_cast(bf16x8, w); }
;         __builtin_amdgcn_sched_barrier(0);
;     };
;     auto pv = [&](int voff) {
;         const LAS unsigned char* va = lds + varow + voff;
;         bf16x8 a[PFD];
;         auto ld = [&](int i) -> bf16x8 {
;             const int dvb = i & 3, bk = i >> 2, so = ((4 * (bk >> 1) + 2 * hi + (bk & 1)) ^ vswz) * 16;
;             return *(const LAS bf16x8*)(va + 32 * dvb * VROW + so);
;         };
; #pragma unroll
;         for (int i = 0; i < PFD; ++i) a[i] = ld(i);
; #pragma unroll
;         for (int i = 0; i < 16; ++i) {
;             o[i & 3] = __builtin_amdgcn_mfma_f32_32x32x16_bf16(a[i % PFD], pb[i >> 3][(i >> 2) & 1], o[i & 3], 0, 0, 0);
;             if (i + PFD < 16) a[i % PFD] = ld(i + PFD);
;         }
;         __builtin_amdgcn_sched_group_barrier(0x100, PFD, 0);
; #pragma unroll
;         for (int i = 0; i < 16; ++i) { __builtin_amdgcn_sched_group_barrier(0x008, 1, 0); __builtin_amdgcn_sched_group_barrier(0x100, 1, 0); }
;         __builtin_amdgcn_sched_barrier(0);
.LBB0_1216:
	v_sub_f32_e32 v0, v96, v193
	v_exp_f32_e32 v0, v0
	v_sub_f32_e32 v2, v97, v193
	v_exp_f32_e32 v2, v2
	v_sub_f32_e32 v3, v98, v193
	v_exp_f32_e32 v3, v3
	v_sub_f32_e32 v4, v99, v193
	v_exp_f32_e32 v4, v4
	v_sub_f32_e32 v6, v100, v193
	v_add_f32_e32 v5, 0, v0
	v_exp_f32_e32 v6, v6
	v_sub_f32_e32 v7, v101, v193
	v_add_f32_e32 v5, v2, v5
	v_exp_f32_e32 v7, v7
	v_sub_f32_e32 v8, v102, v193
	v_add_f32_e32 v5, v3, v5
	v_exp_f32_e32 v8, v8
	v_sub_f32_e32 v9, v103, v193
	v_add_f32_e32 v5, v4, v5
	v_exp_f32_e32 v9, v9
	v_sub_f32_e32 v10, v104, v193
	v_add_f32_e32 v5, v6, v5
	v_exp_f32_e32 v10, v10
	v_sub_f32_e32 v11, v105, v193
	v_add_f32_e32 v5, v7, v5
	v_exp_f32_e32 v11, v11
	v_sub_f32_e32 v12, v106, v193
	v_add_f32_e32 v5, v8, v5
	v_exp_f32_e32 v12, v12
	v_sub_f32_e32 v13, v107, v193
	v_add_f32_e32 v5, v9, v5
	v_exp_f32_e32 v13, v13
	v_sub_f32_e32 v14, v108, v193
	v_add_f32_e32 v5, v10, v5
	v_exp_f32_e32 v14, v14
	v_sub_f32_e32 v15, v109, v193
	v_add_f32_e32 v5, v11, v5
	v_exp_f32_e32 v15, v15
	v_sub_f32_e32 v96, v110, v193
	v_add_f32_e32 v5, v12, v5
	v_exp_f32_e32 v96, v96
	v_sub_f32_e32 v97, v111, v193
	v_add_f32_e32 v5, v13, v5
	v_exp_f32_e32 v97, v97
	v_sub_f32_e32 v80, v80, v193
	v_add_f32_e32 v5, v14, v5
	v_exp_f32_e32 v80, v80
	v_sub_f32_e32 v81, v81, v193
	v_add_f32_e32 v5, v15, v5
	v_exp_f32_e32 v81, v81
	v_sub_f32_e32 v82, v82, v193
	v_add_f32_e32 v5, v96, v5
	v_exp_f32_e32 v82, v82
	v_sub_f32_e32 v83, v83, v193
	v_add_f32_e32 v5, v97, v5
	v_exp_f32_e32 v83, v83
	v_sub_f32_e32 v84, v84, v193
	v_add_f32_e32 v5, v80, v5
	v_exp_f32_e32 v84, v84
	v_sub_f32_e32 v85, v85, v193
	v_add_f32_e32 v5, v81, v5
	v_exp_f32_e32 v85, v85
	v_sub_f32_e32 v86, v86, v193
	v_add_f32_e32 v5, v82, v5
	v_exp_f32_e32 v86, v86
	v_sub_f32_e32 v87, v87, v193
	v_add_f32_e32 v5, v83, v5
	v_exp_f32_e32 v87, v87
	v_sub_f32_e32 v88, v88, v193
	v_add_f32_e32 v5, v84, v5
	v_exp_f32_e32 v88, v88
	v_sub_f32_e32 v89, v89, v193
	v_add_f32_e32 v5, v85, v5
	v_exp_f32_e32 v89, v89
	v_sub_f32_e32 v90, v90, v193
	v_add_f32_e32 v5, v86, v5
	v_exp_f32_e32 v90, v90
	v_sub_f32_e32 v91, v91, v193
	v_add_f32_e32 v5, v87, v5
	v_exp_f32_e32 v91, v91
	v_sub_f32_e32 v92, v92, v193
	v_add_f32_e32 v5, v88, v5
	v_exp_f32_e32 v92, v92
	v_sub_f32_e32 v93, v93, v193
	v_add_f32_e32 v5, v89, v5
	v_exp_f32_e32 v93, v93
	v_sub_f32_e32 v94, v94, v193
	v_add_f32_e32 v5, v90, v5
	v_exp_f32_e32 v94, v94
	v_sub_f32_e32 v95, v95, v193
	v_add_f32_e32 v5, v91, v5
	v_exp_f32_e32 v95, v95
	v_add_f32_e32 v5, v92, v5
	v_add_f32_e32 v5, v93, v5
	v_add_f32_e32 v5, v94, v5
	v_add_f32_e32 v5, v95, v5
	v_add_f32_e32 v192, v192, v5
	v_cvt_pk_bf16_f32 v2, v0, v2
	v_cvt_pk_bf16_f32 v3, v3, v4
	v_cvt_pk_bf16_f32 v4, v6, v7
	v_cvt_pk_bf16_f32 v5, v8, v9
	v_cvt_pk_bf16_f32 v6, v10, v11
	v_cvt_pk_bf16_f32 v7, v12, v13
	v_cvt_pk_bf16_f32 v8, v14, v15
	v_cvt_pk_bf16_f32 v9, v96, v97
	v_cvt_pk_bf16_f32 v10, v80, v81
	v_cvt_pk_bf16_f32 v11, v82, v83
	v_cvt_pk_bf16_f32 v12, v84, v85
	v_cvt_pk_bf16_f32 v13, v86, v87
	v_cvt_pk_bf16_f32 v80, v88, v89
	v_cvt_pk_bf16_f32 v81, v90, v91
	v_cvt_pk_bf16_f32 v82, v92, v93
	v_cvt_pk_bf16_f32 v83, v94, v95
	v_add_u32_e32 v0, s21, v187
	v_add_u32_e32 v14, v0, v188
	ds_read_b128 v[84:87], v14
	ds_read_b128 v[88:91], v14 offset:4096
	ds_read_b128 v[92:95], v14 offset:8192
	ds_read_b128 v[96:99], v14 offset:12288
	v_add_u32_e32 v15, v0, v189
	ds_read_b128 v[100:103], v15
	ds_read_b128 v[104:107], v15 offset:4096
	v_add_u32_e32 v14, v0, v190
	v_add_u32_e32 v0, v0, v191
	s_waitcnt lgkmcnt(5)
	v_mfma_f32_32x32x16_bf16 v[64:79], v[84:87], v[2:5], v[64:79]
	ds_read_b128 v[84:87], v15 offset:8192
	s_waitcnt lgkmcnt(5)
	v_mfma_f32_32x32x16_bf16 v[48:63], v[88:91], v[2:5], v[48:63]
	ds_read_b128 v[88:91], v15 offset:12288
	s_waitcnt lgkmcnt(5)
	v_mfma_f32_32x32x16_bf16 v[32:47], v[92:95], v[2:5], v[32:47]
	ds_read_b128 v[92:95], v14
	s_waitcnt lgkmcnt(5)
	v_mfma_f32_32x32x16_bf16 v[16:31], v[96:99], v[2:5], v[16:31]
	ds_read_b128 v[2:5], v14 offset:4096
	s_waitcnt lgkmcnt(5)
	v_mfma_f32_32x32x16_bf16 v[64:79], v[100:103], v[6:9], v[64:79]
	ds_read_b128 v[96:99], v14 offset:8192
	s_waitcnt lgkmcnt(5)
	v_mfma_f32_32x32x16_bf16 v[48:63], v[104:107], v[6:9], v[48:63]
	ds_read_b128 v[100:103], v14 offset:12288
	s_waitcnt lgkmcnt(5)
	v_mfma_f32_32x32x16_bf16 v[32:47], v[84:87], v[6:9], v[32:47]
	ds_read_b128 v[84:87], v0
	s_waitcnt lgkmcnt(5)
	v_mfma_f32_32x32x16_bf16 v[16:31], v[88:91], v[6:9], v[16:31]
	ds_read_b128 v[6:9], v0 offset:4096
	s_waitcnt lgkmcnt(5)
	v_mfma_f32_32x32x16_bf16 v[64:79], v[92:95], v[10:13], v[64:79]
	ds_read_b128 v[88:91], v0 offset:8192
	s_waitcnt lgkmcnt(5)
	v_mfma_f32_32x32x16_bf16 v[48:63], v[2:5], v[10:13], v[48:63]
	ds_read_b128 v[2:5], v0 offset:12288
	s_waitcnt lgkmcnt(5)
	v_mfma_f32_32x32x16_bf16 v[32:47], v[96:99], v[10:13], v[32:47]
	s_waitcnt lgkmcnt(4)
	v_mfma_f32_32x32x16_bf16 v[16:31], v[100:103], v[10:13], v[16:31]
	s_waitcnt lgkmcnt(3)
	v_mfma_f32_32x32x16_bf16 v[64:79], v[84:87], v[80:83], v[64:79]
	s_waitcnt lgkmcnt(2)
	v_mfma_f32_32x32x16_bf16 v[48:63], v[6:9], v[80:83], v[48:63]
	s_waitcnt lgkmcnt(1)
	v_mfma_f32_32x32x16_bf16 v[32:47], v[88:91], v[80:83], v[32:47]
	s_waitcnt lgkmcnt(0)
	v_mfma_f32_32x32x16_bf16 v[16:31], v[2:5], v[80:83], v[16:31]
	s_mov_b64 s[16:17], -1
	s_and_b64 vcc, exec, s[14:15]
	s_cbranch_vccnz .LBB0_1208

; __device__ __forceinline__ unsigned cvt_pk_bf16(float lo, float hi) { unsigned r; asm volatile("v_cvt_pk_bf16_f32 %0, %1, %2" : "=v"(r) : "v"(lo), "v"(hi)); return r; }
; #define LAS __attribute__((address_space(3)))
; template <bool MLA, bool grpB>
; __device__ __forceinline__ void attn_unit_g(LAS unsigned char* lds, const AttnPtrs& P, int b, int h, int qblk) {
;     ...
;         float ps = 0.f;
; #pragma unroll
;         for (int blk = 0; blk < 2; ++blk)
; #pragma unroll
;             for (int r = 0; r < 16; ++r) { const float pv_ = __builtin_amdgcn_exp2f(sc[blk][r] - mref); sc[blk][r] = pv_; ps += pv_; }
;         lrun += ps;
; #pragma unroll
;         for (int blk = 0; blk < 2; ++blk)
; #pragma unroll
;             for (int ks = 0; ks < 2; ++ks) { u32x4 w;
;                 w.x = pg8::cvt_pk_bf16(sc[blk][8 * ks + 0], sc[blk][8 * ks + 1]); w.y = pg8::cvt_pk_bf16(sc[blk][8 * ks + 2], sc[blk][8 * ks + 3]);
;                 w.z = pg8::cvt_pk_bf16(sc[blk][8 * ks + 4], sc[blk][8 * ks + 5]); w.w = pg8::cvt_pk_bf16(sc[blk][8 * ks + 6], sc[blk][8 * ks + 7]);
;                 pb[blk][ks] = __builtin_bit_cast(bf16x8, w); }
;         __builtin_amdgcn_sched_barrier(0);
;     };
;     auto pv = [&](int voff) {
;         const LAS unsigned char* va = lds + varow + voff;
;         bf16x8 a[PFD];
;         auto ld = [&](int i) -> bf16x8 {
;             const int dvb = i & 3, bk = i >> 2, so = ((4 * (bk >> 1) + 2 * hi + (bk & 1)) ^ vswz) * 16;
;             return *(const LAS bf16x8*)(va + 32 * dvb * VROW + so);
;         };
; #pragma unroll
;         for (int i = 0; i < PFD; ++i) a[i] = ld(i);
; #pragma unroll
;         for (int i = 0; i < 16; ++i) {
;             o[i & 3] = __builtin_amdgcn_mfma_f32_32x32x16_bf16(a[i % PFD], pb[i >> 3][(i >> 2) & 1], o[i & 3], 0, 0, 0);
;             if (i + PFD < 16) a[i % PFD] = ld(i + PFD);
;         }
;         __builtin_amdgcn_sched_group_barrier(0x100, PFD, 0);
; #pragma unroll
;         for (int i = 0; i < 16; ++i) { __builtin_amdgcn_sched_group_barrier(0x008, 1, 0); __builtin_amdgcn_sched_group_barrier(0x100, 1, 0); }
;         __builtin_amdgcn_sched_barrier(0);
.LBB0_1268:
	v_sub_f32_e32 v0, v16, v181
	v_exp_f32_e32 v16, v0
	v_sub_f32_e32 v0, v17, v181
	v_exp_f32_e32 v17, v0
	v_sub_f32_e32 v0, v18, v181
	v_exp_f32_e32 v18, v0
	v_sub_f32_e32 v0, v19, v181
	v_exp_f32_e32 v19, v0
	v_sub_f32_e32 v2, v20, v181
	v_add_f32_e32 v0, 0, v16
	v_exp_f32_e32 v20, v2
	v_sub_f32_e32 v2, v21, v181
	v_add_f32_e32 v0, v17, v0
	v_exp_f32_e32 v21, v2
	v_sub_f32_e32 v2, v22, v181
	v_add_f32_e32 v0, v18, v0
	v_exp_f32_e32 v22, v2
	v_sub_f32_e32 v2, v23, v181
	v_add_f32_e32 v0, v19, v0
	v_exp_f32_e32 v23, v2
	v_sub_f32_e32 v2, v24, v181
	v_add_f32_e32 v0, v20, v0
	v_exp_f32_e32 v24, v2
	v_sub_f32_e32 v2, v25, v181
	v_add_f32_e32 v0, v21, v0
	v_exp_f32_e32 v25, v2
	v_sub_f32_e32 v2, v26, v181
	v_add_f32_e32 v0, v22, v0
	v_exp_f32_e32 v26, v2
	v_sub_f32_e32 v2, v27, v181
	v_add_f32_e32 v0, v23, v0
	v_exp_f32_e32 v27, v2
	v_sub_f32_e32 v2, v28, v181
	v_add_f32_e32 v0, v24, v0
	v_exp_f32_e32 v28, v2
	v_sub_f32_e32 v2, v29, v181
	v_add_f32_e32 v0, v25, v0
	v_exp_f32_e32 v29, v2
	v_sub_f32_e32 v2, v30, v181
	v_add_f32_e32 v0, v26, v0
	v_exp_f32_e32 v30, v2
	v_sub_f32_e32 v2, v31, v181
	v_add_f32_e32 v0, v27, v0
	v_exp_f32_e32 v31, v2
	v_sub_f32_e32 v2, v32, v181
	v_add_f32_e32 v0, v28, v0
	v_exp_f32_e32 v32, v2
	v_sub_f32_e32 v2, v33, v181
	v_add_f32_e32 v0, v29, v0
	v_exp_f32_e32 v33, v2
	v_sub_f32_e32 v2, v34, v181
	v_add_f32_e32 v0, v30, v0
	v_exp_f32_e32 v34, v2
	v_sub_f32_e32 v2, v35, v181
	v_add_f32_e32 v0, v31, v0
	v_exp_f32_e32 v35, v2
	v_sub_f32_e32 v2, v36, v181
	v_add_f32_e32 v0, v32, v0
	v_exp_f32_e32 v36, v2
	v_sub_f32_e32 v2, v37, v181
	v_add_f32_e32 v0, v33, v0
	v_exp_f32_e32 v37, v2
	v_sub_f32_e32 v2, v38, v181
	v_add_f32_e32 v0, v34, v0
	v_exp_f32_e32 v38, v2
	v_sub_f32_e32 v2, v39, v181
	v_add_f32_e32 v0, v35, v0
	v_exp_f32_e32 v39, v2
	v_sub_f32_e32 v2, v40, v181
	v_add_f32_e32 v0, v36, v0
	v_exp_f32_e32 v40, v2
	v_sub_f32_e32 v2, v41, v181
	v_add_f32_e32 v0, v37, v0
	v_exp_f32_e32 v41, v2
	v_sub_f32_e32 v2, v42, v181
	v_add_f32_e32 v0, v38, v0
	v_exp_f32_e32 v42, v2
	v_sub_f32_e32 v2, v43, v181
	v_add_f32_e32 v0, v39, v0
	v_exp_f32_e32 v43, v2
	v_sub_f32_e32 v2, v44, v181
	v_add_f32_e32 v0, v40, v0
	v_exp_f32_e32 v44, v2
	v_sub_f32_e32 v2, v45, v181
	v_add_f32_e32 v0, v41, v0
	v_exp_f32_e32 v45, v2
	v_sub_f32_e32 v2, v46, v181
	v_add_f32_e32 v0, v42, v0
	v_exp_f32_e32 v46, v2
	v_sub_f32_e32 v2, v47, v181
	v_add_f32_e32 v0, v43, v0
	v_exp_f32_e32 v47, v2
	v_add_f32_e32 v0, v44, v0
	v_add_f32_e32 v0, v45, v0
	v_add_f32_e32 v0, v46, v0
	v_add_f32_e32 v0, v47, v0
	v_add_f32_e32 v180, v180, v0
	v_cvt_pk_bf16_f32 v2, v16, v17
	v_cvt_pk_bf16_f32 v3, v18, v19
	v_cvt_pk_bf16_f32 v4, v20, v21
	v_cvt_pk_bf16_f32 v5, v22, v23
	v_cvt_pk_bf16_f32 v6, v24, v25
	v_cvt_pk_bf16_f32 v7, v26, v27
	v_cvt_pk_bf16_f32 v8, v28, v29
	v_cvt_pk_bf16_f32 v9, v30, v31
	v_cvt_pk_bf16_f32 v10, v32, v33
	v_cvt_pk_bf16_f32 v11, v34, v35
	v_cvt_pk_bf16_f32 v12, v36, v37
	v_cvt_pk_bf16_f32 v13, v38, v39
	v_cvt_pk_bf16_f32 v182, v40, v41
	v_cvt_pk_bf16_f32 v183, v42, v43
	v_cvt_pk_bf16_f32 v184, v44, v45
	v_cvt_pk_bf16_f32 v185, v46, v47
	v_add_u32_e32 v0, s54, v175
	v_add_u32_e32 v14, v0, v176
	ds_read_b128 v[186:189], v14
	ds_read_b128 v[190:193], v14 offset:4096
	ds_read_b128 v[194:197], v14 offset:8192
	ds_read_b128 v[202:205], v14 offset:12288
	v_add_u32_e32 v15, v0, v177
	ds_read_b128 v[206:209], v15
	ds_read_b128 v[210:213], v15 offset:4096
	v_add_u32_e32 v14, v0, v178
	v_add_u32_e32 v0, v0, v179
	s_waitcnt lgkmcnt(5)
	v_mfma_f32_32x32x16_bf16 v[96:111], v[186:189], v[2:5], v[96:111]
	ds_read_b128 v[186:189], v15 offset:8192
	s_waitcnt lgkmcnt(5)
	v_mfma_f32_32x32x16_bf16 v[80:95], v[190:193], v[2:5], v[80:95]
	ds_read_b128 v[190:193], v15 offset:12288
	s_waitcnt lgkmcnt(5)
	v_mfma_f32_32x32x16_bf16 v[64:79], v[194:197], v[2:5], v[64:79]
	ds_read_b128 v[194:197], v14
	s_waitcnt lgkmcnt(5)
	v_mfma_f32_32x32x16_bf16 v[48:63], v[202:205], v[2:5], v[48:63]
	ds_read_b128 v[2:5], v14 offset:4096
	s_waitcnt lgkmcnt(5)
	v_mfma_f32_32x32x16_bf16 v[96:111], v[206:209], v[6:9], v[96:111]
	ds_read_b128 v[202:205], v14 offset:8192
	s_waitcnt lgkmcnt(5)
	v_mfma_f32_32x32x16_bf16 v[80:95], v[210:213], v[6:9], v[80:95]
	ds_read_b128 v[206:209], v14 offset:12288
	s_waitcnt lgkmcnt(5)
	v_mfma_f32_32x32x16_bf16 v[64:79], v[186:189], v[6:9], v[64:79]
	ds_read_b128 v[186:189], v0
	s_waitcnt lgkmcnt(5)
	v_mfma_f32_32x32x16_bf16 v[48:63], v[190:193], v[6:9], v[48:63]
	ds_read_b128 v[6:9], v0 offset:4096
	s_waitcnt lgkmcnt(5)
	v_mfma_f32_32x32x16_bf16 v[96:111], v[194:197], v[10:13], v[96:111]
	ds_read_b128 v[190:193], v0 offset:8192
	s_waitcnt lgkmcnt(5)
	v_mfma_f32_32x32x16_bf16 v[80:95], v[2:5], v[10:13], v[80:95]
	ds_read_b128 v[2:5], v0 offset:12288
	s_waitcnt lgkmcnt(5)
	v_mfma_f32_32x32x16_bf16 v[64:79], v[202:205], v[10:13], v[64:79]
	s_waitcnt lgkmcnt(4)
	v_mfma_f32_32x32x16_bf16 v[48:63], v[206:209], v[10:13], v[48:63]
	s_waitcnt lgkmcnt(3)
	v_mfma_f32_32x32x16_bf16 v[96:111], v[186:189], v[182:185], v[96:111]
	s_waitcnt lgkmcnt(2)
	v_mfma_f32_32x32x16_bf16 v[80:95], v[6:9], v[182:185], v[80:95]
	s_waitcnt lgkmcnt(1)
	v_mfma_f32_32x32x16_bf16 v[64:79], v[190:193], v[182:185], v[64:79]
	s_waitcnt lgkmcnt(0)
	v_mfma_f32_32x32x16_bf16 v[48:63], v[2:5], v[182:185], v[48:63]
; #define LAS __attribute__((address_space(3)))
; template <bool MLA, bool grpB>
; __device__ __forceinline__ void attn_unit_g(LAS unsigned char* lds, const AttnPtrs& P, int b, int h, int qblk) {
;     ...
;     auto qk = [&](int koff) {
;         if (MLA) {
;         } else {
; #pragma unroll
;             for (int blk = 0; blk < 2; ++blk)
; #pragma unroll
;                 for (int g = 0; g < 4; ++g) { const f32x4 c4 = *(const LAS f32x4*)(lds + koff + KTILE + (32 * blk + 16 * hi + 4 * g) * 4);
; #pragma unroll
;                     for (int e = 0; e < 4; ++e) sc[blk][4 * g + e] = c4[e]; }
;         }
;         const LAS unsigned char* ka = lds + koff + karow;
;         bf16x8 a[PFD];
;         auto ld = [&](int i) -> bf16x8 {
;             const int d0 = i >> 1, blk = i & 1, seg = 2 * d0;
;             int so;
;             if (MLA) so = (((seg + hi) & 24) | (((seg + hi) ^ kswz) & 7)) * 16; else so = ((seg + hi) ^ kswz) * 16;
;             return *(const LAS bf16x8*)(ka + blk * 32 * KROW + so);
;         };
; #pragma unroll
;         for (int i = 0; i < PFD; ++i) a[i] = ld(i);
; #pragma unroll
;         for (int i = 0; i < 2 * ND0; ++i) {
;             const f32x16 zc = {0.f, 0.f, 0.f, 0.f, 0.f, 0.f, 0.f, 0.f, 0.f, 0.f, 0.f, 0.f, 0.f, 0.f, 0.f, 0.f};
;             sc[i & 1] = __builtin_amdgcn_mfma_f32_32x32x16_bf16(a[i % PFD], qf[i >> 1], (MLA && i < 2) ? zc : sc[i & 1], 0, 0, 0);
;             if (i + PFD < 2 * ND0) a[i % PFD] = ld(i + PFD);
;         }
;         __builtin_amdgcn_sched_group_barrier(0x100, PFD, 0);
; #pragma unroll
;         for (int i = 0; i < 2 * ND0; ++i) { __builtin_amdgcn_sched_group_barrier(0x008, 1, 0); __builtin_amdgcn_sched_group_barrier(0x100, 1, 0); }
;         __builtin_amdgcn_sched_barrier(0);
.LBB0_1269:
	s_cmpk_eq_i32 s64, 0xff40
	s_cselect_b64 s[8:9], -1, 0
	s_cmp_gt_i32 s48, s97
	s_cselect_b64 s[10:11], -1, 0
	s_or_b64 s[8:9], s[8:9], s[10:11]
	s_and_b64 vcc, exec, s[8:9]
	s_cbranch_vccnz .LBB0_1273
	s_add_i32 s8, s56, 0
	v_add_u32_e32 v0, s8, v161
	ds_read_b128 v[16:19], v0 offset:16384
	ds_read_b128 v[20:23], v0 offset:16400
	ds_read_b128 v[24:27], v0 offset:16416
	ds_read_b128 v[28:31], v0 offset:16432
	ds_read_b128 v[32:35], v0 offset:16512
	ds_read_b128 v[36:39], v0 offset:16528
	ds_read_b128 v[40:43], v0 offset:16544
	ds_read_b128 v[44:47], v0 offset:16560
	v_add_u32_e32 v0, s8, v147
	v_add_u32_e32 v6, v0, v162
	v_add_u32_e32 v7, v0, v163
	v_add_u32_e32 v8, v0, v164
	v_add_u32_e32 v9, v0, v165
	v_add_u32_e32 v10, v0, v166
	v_add_u32_e32 v11, v0, v167
	v_add_u32_e32 v12, v0, v168
	v_add_u32_e32 v0, v0, v169
	ds_read_b128 v[182:185], v6 offset:8192
	ds_read_b128 v[186:189], v7 offset:8192
	ds_read_b128 v[190:193], v8 offset:8192
	ds_read_b128 v[194:197], v9 offset:8192
	ds_read_b128 v[202:205], v10 offset:8192
	ds_read_b128 v[210:213], v11 offset:8192
	s_waitcnt lgkmcnt(5)
	v_mfma_f32_32x32x16_bf16 v[32:47], v[182:185], v[136:139], v[32:47]
	ds_read_b128 v[182:185], v12 offset:8192
	s_waitcnt lgkmcnt(5)
	v_mfma_f32_32x32x16_bf16 v[32:47], v[186:189], v[112:115], v[32:47]
	ds_read_b128 v[186:189], v0 offset:8192
	s_waitcnt lgkmcnt(5)
	v_mfma_f32_32x32x16_bf16 v[32:47], v[190:193], v[116:119], v[32:47]
	ds_read_b128 v[190:193], v6
	s_waitcnt lgkmcnt(5)
	v_mfma_f32_32x32x16_bf16 v[32:47], v[194:197], v[120:123], v[32:47]
	ds_read_b128 v[194:197], v7
	s_waitcnt lgkmcnt(5)
	v_mfma_f32_32x32x16_bf16 v[32:47], v[202:205], v[124:127], v[32:47]
	ds_read_b128 v[202:205], v8
	s_waitcnt lgkmcnt(5)
	v_mfma_f32_32x32x16_bf16 v[32:47], v[210:213], v[128:131], v[32:47]
	ds_read_b128 v[210:213], v9
	s_waitcnt lgkmcnt(5)
	v_mfma_f32_32x32x16_bf16 v[32:47], v[182:185], v[132:135], v[32:47]
	ds_read_b128 v[182:185], v10
	s_waitcnt lgkmcnt(5)
	v_mfma_f32_32x32x16_bf16 v[32:47], v[186:189], v[140:143], v[32:47]
	ds_read_b128 v[186:189], v11
	s_waitcnt lgkmcnt(5)
	v_mfma_f32_32x32x16_bf16 v[16:31], v[190:193], v[136:139], v[16:31]
	ds_read_b128 v[190:193], v12
	s_waitcnt lgkmcnt(5)
	v_mfma_f32_32x32x16_bf16 v[16:31], v[194:197], v[112:115], v[16:31]
	ds_read_b128 v[194:197], v0
	s_waitcnt lgkmcnt(5)
	v_mfma_f32_32x32x16_bf16 v[16:31], v[202:205], v[116:119], v[16:31]
	s_waitcnt lgkmcnt(4)
	v_mfma_f32_32x32x16_bf16 v[16:31], v[210:213], v[120:123], v[16:31]
	s_waitcnt lgkmcnt(3)
	v_mfma_f32_32x32x16_bf16 v[16:31], v[182:185], v[124:127], v[16:31]
	s_waitcnt lgkmcnt(2)
	v_mfma_f32_32x32x16_bf16 v[16:31], v[186:189], v[128:131], v[16:31]
	s_waitcnt lgkmcnt(1)
	v_mfma_f32_32x32x16_bf16 v[16:31], v[190:193], v[132:135], v[16:31]
	s_waitcnt lgkmcnt(0)
	v_mfma_f32_32x32x16_bf16 v[16:31], v[194:197], v[140:143], v[16:31]
	s_mov_b64 s[8:9], -1
	s_and_b64 vcc, exec, s[74:75]
	s_cbranch_vccnz .LBB0_1274

; #define LAS __attribute__((address_space(3)))
; template <bool MLA, bool grpB>
; __device__ __forceinline__ void attn_unit_g(LAS unsigned char* lds, const AttnPtrs& P, int b, int h, int qblk) {
;     ...
;     auto qk = [&](int koff) {
;         if (MLA) {
;         } else {
; #pragma unroll
;             for (int blk = 0; blk < 2; ++blk)
; #pragma unroll
;                 for (int g = 0; g < 4; ++g) { const f32x4 c4 = *(const LAS f32x4*)(lds + koff + KTILE + (32 * blk + 16 * hi + 4 * g) * 4);
; #pragma unroll
;                     for (int e = 0; e < 4; ++e) sc[blk][4 * g + e] = c4[e]; }
;         }
;         const LAS unsigned char* ka = lds + koff + karow;
;         bf16x8 a[PFD];
;         auto ld = [&](int i) -> bf16x8 {
;             const int d0 = i >> 1, blk = i & 1, seg = 2 * d0;
;             int so;
;             if (MLA) so = (((seg + hi) & 24) | (((seg + hi) ^ kswz) & 7)) * 16; else so = ((seg + hi) ^ kswz) * 16;
;             return *(const LAS bf16x8*)(ka + blk * 32 * KROW + so);
;         };
; #pragma unroll
;         for (int i = 0; i < PFD; ++i) a[i] = ld(i);
; #pragma unroll
;         for (int i = 0; i < 2 * ND0; ++i) {
;             const f32x16 zc = {0.f, 0.f, 0.f, 0.f, 0.f, 0.f, 0.f, 0.f, 0.f, 0.f, 0.f, 0.f, 0.f, 0.f, 0.f, 0.f};
;             sc[i & 1] = __builtin_amdgcn_mfma_f32_32x32x16_bf16(a[i % PFD], qf[i >> 1], (MLA && i < 2) ? zc : sc[i & 1], 0, 0, 0);
;             if (i + PFD < 2 * ND0) a[i % PFD] = ld(i + PFD);
;         }
;         __builtin_amdgcn_sched_group_barrier(0x100, PFD, 0);
; #pragma unroll
;         for (int i = 0; i < 2 * ND0; ++i) { __builtin_amdgcn_sched_group_barrier(0x008, 1, 0); __builtin_amdgcn_sched_group_barrier(0x100, 1, 0); }
;         __builtin_amdgcn_sched_barrier(0);
;     };
;     float mref = -1e30f;
;     auto sm = [&](int j) {
;         if (j >= my_last) {
;             if (MLA) { if (j > my_last) {
; #pragma unroll
;                 for (int r = 0; r < 16; ++r) { sc[0][r] = -2e30f; sc[1][r] = -2e30f; } } }
;             else { const int qpos = q0 + r32;
; #pragma unroll
;                 for (int blk = 0; blk < 2; ++blk)
; #pragma unroll
;                     for (int r = 0; r < 16; ++r) { const int key = 64 * j + 32 * blk + 16 * hi + r; if (key > qpos) sc[blk][r] = -2e30f; } }
.LBB0_1313:
	s_add_i32 s8, s51, 0
	v_add_u32_e32 v0, s8, v161
	ds_read_b128 v[96:99], v0 offset:16384
	ds_read_b128 v[100:103], v0 offset:16400
	ds_read_b128 v[104:107], v0 offset:16416
	ds_read_b128 v[108:111], v0 offset:16432
	ds_read_b128 v[80:83], v0 offset:16512
	ds_read_b128 v[84:87], v0 offset:16528
	ds_read_b128 v[88:91], v0 offset:16544
	ds_read_b128 v[92:95], v0 offset:16560
	v_add_u32_e32 v0, s8, v147
	v_add_u32_e32 v6, v0, v162
	v_add_u32_e32 v7, v0, v163
	v_add_u32_e32 v8, v0, v164
	v_add_u32_e32 v9, v0, v165
	v_add_u32_e32 v10, v0, v166
	v_add_u32_e32 v11, v0, v167
	v_add_u32_e32 v12, v0, v168
	v_add_u32_e32 v0, v0, v169
	ds_read_b128 v[182:185], v6 offset:8192
	ds_read_b128 v[186:189], v7 offset:8192
	ds_read_b128 v[190:193], v8 offset:8192
	ds_read_b128 v[194:197], v9 offset:8192
	ds_read_b128 v[202:205], v10 offset:8192
	ds_read_b128 v[210:213], v11 offset:8192
	s_waitcnt lgkmcnt(5)
	v_mfma_f32_32x32x16_bf16 v[80:95], v[182:185], v[136:139], v[80:95]
	ds_read_b128 v[182:185], v12 offset:8192
	s_waitcnt lgkmcnt(5)
	v_mfma_f32_32x32x16_bf16 v[80:95], v[186:189], v[112:115], v[80:95]
	ds_read_b128 v[186:189], v0 offset:8192
	s_waitcnt lgkmcnt(5)
	v_mfma_f32_32x32x16_bf16 v[80:95], v[190:193], v[116:119], v[80:95]
	ds_read_b128 v[190:193], v6
	s_waitcnt lgkmcnt(5)
	v_mfma_f32_32x32x16_bf16 v[80:95], v[194:197], v[120:123], v[80:95]
	ds_read_b128 v[194:197], v7
	s_waitcnt lgkmcnt(5)
	v_mfma_f32_32x32x16_bf16 v[80:95], v[202:205], v[124:127], v[80:95]
	ds_read_b128 v[202:205], v8
	s_waitcnt lgkmcnt(5)
	v_mfma_f32_32x32x16_bf16 v[80:95], v[210:213], v[128:131], v[80:95]
	ds_read_b128 v[210:213], v9
	s_waitcnt lgkmcnt(5)
	v_mfma_f32_32x32x16_bf16 v[80:95], v[182:185], v[132:135], v[80:95]
	ds_read_b128 v[182:185], v10
	s_waitcnt lgkmcnt(5)
	v_mfma_f32_32x32x16_bf16 v[80:95], v[186:189], v[140:143], v[80:95]
	ds_read_b128 v[186:189], v11
	s_waitcnt lgkmcnt(5)
	v_mfma_f32_32x32x16_bf16 v[96:111], v[190:193], v[136:139], v[96:111]
	ds_read_b128 v[190:193], v12
	s_waitcnt lgkmcnt(5)
	v_mfma_f32_32x32x16_bf16 v[96:111], v[194:197], v[112:115], v[96:111]
	ds_read_b128 v[194:197], v0
	s_waitcnt lgkmcnt(5)
	v_mfma_f32_32x32x16_bf16 v[96:111], v[202:205], v[116:119], v[96:111]
	s_waitcnt lgkmcnt(4)
	v_mfma_f32_32x32x16_bf16 v[96:111], v[210:213], v[120:123], v[96:111]
	s_waitcnt lgkmcnt(3)
	v_mfma_f32_32x32x16_bf16 v[96:111], v[182:185], v[124:127], v[96:111]
	s_waitcnt lgkmcnt(2)
	v_mfma_f32_32x32x16_bf16 v[96:111], v[186:189], v[128:131], v[96:111]
	s_waitcnt lgkmcnt(1)
	v_mfma_f32_32x32x16_bf16 v[96:111], v[190:193], v[132:135], v[96:111]
	s_waitcnt lgkmcnt(0)
	v_mfma_f32_32x32x16_bf16 v[96:111], v[194:197], v[140:143], v[96:111]
	s_cmp_lt_u32 s10, s54
	s_cbranch_scc1 .LBB0_1317
	v_add_u32_e32 v0, s64, v146
	v_add_u32_e32 v2, 0xc0, v0
	v_cmp_le_i32_e32 vcc, v2, v173
	v_cmp_lt_i32_e64 s[8:9], v2, v173
	v_add_u32_e32 v2, 0xc2, v0
	v_cmp_le_i32_e64 s[10:11], v2, v173
	v_add_u32_e32 v2, 0xc3, v0
	v_cmp_le_i32_e64 s[12:13], v2, v173
	v_add_u32_e32 v2, 0xc4, v0
	v_cmp_le_i32_e64 s[14:15], v2, v173
	v_add_u32_e32 v2, 0xc5, v0
	v_cmp_le_i32_e64 s[16:17], v2, v173
	v_add_u32_e32 v2, 0xc6, v0
	v_cmp_le_i32_e64 s[18:19], v2, v173
	v_add_u32_e32 v2, 0xc7, v0
	v_cmp_le_i32_e64 s[20:21], v2, v173
	v_add_u32_e32 v2, 0xc8, v0
	v_cmp_le_i32_e64 s[22:23], v2, v173
	v_add_u32_e32 v2, 0xc9, v0
	v_cmp_le_i32_e64 s[24:25], v2, v173
	v_add_u32_e32 v2, 0xca, v0
	v_cmp_le_i32_e64 s[26:27], v2, v173
	v_add_u32_e32 v2, 0xcb, v0
	v_cmp_le_i32_e64 s[28:29], v2, v173
	v_add_u32_e32 v2, 0xcc, v0
	v_cmp_le_i32_e64 s[30:31], v2, v173
	v_add_u32_e32 v2, 0xcd, v0
	v_cmp_le_i32_e64 s[34:35], v2, v173
	v_add_u32_e32 v2, 0xce, v0
	v_cmp_le_i32_e64 s[36:37], v2, v173
	v_add_u32_e32 v2, 0xcf, v0
	v_cmp_le_i32_e64 s[38:39], v2, v173
	v_add_u32_e32 v2, 0xe0, v0
	v_cmp_le_i32_e64 s[42:43], v2, v173
	v_add_u32_e32 v2, 0xe1, v0
	s_nop 0
	v_cndmask_b32_e64 v80, v159, v80, s[42:43]
	v_cmp_le_i32_e64 s[42:43], v2, v173
	v_add_u32_e32 v2, 0xe2, v0
	s_nop 0
	v_cndmask_b32_e64 v81, v159, v81, s[42:43]
	v_cmp_le_i32_e64 s[42:43], v2, v173
	v_add_u32_e32 v2, 0xe3, v0
	s_nop 0
	v_cndmask_b32_e64 v82, v159, v82, s[42:43]
	v_cmp_le_i32_e64 s[42:43], v2, v173
	v_add_u32_e32 v2, 0xe4, v0
	s_nop 0
	v_cndmask_b32_e64 v83, v159, v83, s[42:43]
	v_cmp_le_i32_e64 s[42:43], v2, v173
	v_add_u32_e32 v2, 0xe5, v0
	s_nop 0
	v_cndmask_b32_e64 v84, v159, v84, s[42:43]
	v_cmp_le_i32_e64 s[42:43], v2, v173
	v_add_u32_e32 v2, 0xe6, v0
	s_nop 0
	v_cndmask_b32_e64 v85, v159, v85, s[42:43]
	v_cmp_le_i32_e64 s[42:43], v2, v173
	v_add_u32_e32 v2, 0xe7, v0
	s_nop 0
	v_cndmask_b32_e64 v86, v159, v86, s[42:43]
	v_cmp_le_i32_e64 s[42:43], v2, v173
	v_add_u32_e32 v2, 0xe8, v0
	s_nop 0
	v_cndmask_b32_e64 v87, v159, v87, s[42:43]
	v_cmp_le_i32_e64 s[42:43], v2, v173
	v_add_u32_e32 v2, 0xe9, v0
	s_nop 0
	v_cndmask_b32_e64 v88, v159, v88, s[42:43]
	v_cmp_le_i32_e64 s[42:43], v2, v173
	v_add_u32_e32 v2, 0xea, v0
	s_nop 0
	v_cndmask_b32_e64 v89, v159, v89, s[42:43]
	v_cmp_le_i32_e64 s[42:43], v2, v173
	v_add_u32_e32 v2, 0xeb, v0
	s_nop 0
	v_cndmask_b32_e64 v90, v159, v90, s[42:43]
	v_cmp_le_i32_e64 s[42:43], v2, v173
	v_add_u32_e32 v2, 0xec, v0
	s_nop 0
	v_cndmask_b32_e64 v91, v159, v91, s[42:43]
	v_cmp_le_i32_e64 s[42:43], v2, v173
	v_add_u32_e32 v2, 0xed, v0
	s_nop 0
	v_cndmask_b32_e64 v92, v159, v92, s[42:43]
	v_cmp_le_i32_e64 s[42:43], v2, v173
	v_add_u32_e32 v2, 0xee, v0
	v_add_u32_e32 v0, 0xef, v0
	v_cndmask_b32_e64 v93, v159, v93, s[42:43]
	v_cmp_le_i32_e64 s[42:43], v2, v173
	s_nop 1
	v_cndmask_b32_e64 v94, v159, v94, s[42:43]
	v_cmp_gt_i32_e64 s[42:43], v0, v173
	s_and_saveexec_b64 s[76:77], s[42:43]
	v_mov_b32_e32 v95, s87
	s_or_b64 exec, exec, s[76:77]
	v_cndmask_b32_e64 v97, v159, v97, s[8:9]
	v_cndmask_b32_e32 v96, v159, v96, vcc
	v_cndmask_b32_e64 v98, v159, v98, s[10:11]
	v_cndmask_b32_e64 v99, v159, v99, s[12:13]
	v_cndmask_b32_e64 v100, v159, v100, s[14:15]
	v_cndmask_b32_e64 v101, v159, v101, s[16:17]
	v_cndmask_b32_e64 v102, v159, v102, s[18:19]
	v_cndmask_b32_e64 v103, v159, v103, s[20:21]
	v_cndmask_b32_e64 v104, v159, v104, s[22:23]
	v_cndmask_b32_e64 v105, v159, v105, s[24:25]
	v_cndmask_b32_e64 v106, v159, v106, s[26:27]
	v_cndmask_b32_e64 v107, v159, v107, s[28:29]
	v_cndmask_b32_e64 v108, v159, v108, s[30:31]
	v_cndmask_b32_e64 v109, v159, v109, s[34:35]
	v_cndmask_b32_e64 v110, v159, v110, s[36:37]
	v_cndmask_b32_e64 v111, v159, v111, s[38:39]

; __device__ __forceinline__ unsigned cvt_pk_bf16(float lo, float hi) { unsigned r; asm volatile("v_cvt_pk_bf16_f32 %0, %1, %2" : "=v"(r) : "v"(lo), "v"(hi)); return r; }
; #define LAS __attribute__((address_space(3)))
; template <bool MLA, bool grpB>
; __device__ __forceinline__ void attn_unit_g(LAS unsigned char* lds, const AttnPtrs& P, int b, int h, int qblk) {
;     ...
;         float ps = 0.f;
; #pragma unroll
;         for (int blk = 0; blk < 2; ++blk)
; #pragma unroll
;             for (int r = 0; r < 16; ++r) { const float pv_ = __builtin_amdgcn_exp2f(sc[blk][r] - mref); sc[blk][r] = pv_; ps += pv_; }
;         lrun += ps;
; #pragma unroll
;         for (int blk = 0; blk < 2; ++blk)
; #pragma unroll
;             for (int ks = 0; ks < 2; ++ks) { u32x4 w;
;                 w.x = pg8::cvt_pk_bf16(sc[blk][8 * ks + 0], sc[blk][8 * ks + 1]); w.y = pg8::cvt_pk_bf16(sc[blk][8 * ks + 2], sc[blk][8 * ks + 3]);
;                 w.z = pg8::cvt_pk_bf16(sc[blk][8 * ks + 4], sc[blk][8 * ks + 5]); w.w = pg8::cvt_pk_bf16(sc[blk][8 * ks + 6], sc[blk][8 * ks + 7]);
;                 pb[blk][ks] = __builtin_bit_cast(bf16x8, w); }
;         __builtin_amdgcn_sched_barrier(0);
;     };
;     auto pv = [&](int voff) {
;         const LAS unsigned char* va = lds + varow + voff;
;         bf16x8 a[PFD];
;         auto ld = [&](int i) -> bf16x8 {
;             const int dvb = i & 3, bk = i >> 2, so = ((4 * (bk >> 1) + 2 * hi + (bk & 1)) ^ vswz) * 16;
;             return *(const LAS bf16x8*)(va + 32 * dvb * VROW + so);
;         };
; #pragma unroll
;         for (int i = 0; i < PFD; ++i) a[i] = ld(i);
; #pragma unroll
;         for (int i = 0; i < 16; ++i) {
;             o[i & 3] = __builtin_amdgcn_mfma_f32_32x32x16_bf16(a[i % PFD], pb[i >> 3][(i >> 2) & 1], o[i & 3], 0, 0, 0);
;             if (i + PFD < 16) a[i % PFD] = ld(i + PFD);
;         }
;         __builtin_amdgcn_sched_group_barrier(0x100, PFD, 0);
; #pragma unroll
;         for (int i = 0; i < 16; ++i) { __builtin_amdgcn_sched_group_barrier(0x008, 1, 0); __builtin_amdgcn_sched_group_barrier(0x100, 1, 0); }
;         __builtin_amdgcn_sched_barrier(0);
.LBB0_1319:
	v_sub_f32_e32 v0, v96, v181
	v_exp_f32_e32 v0, v0
	v_sub_f32_e32 v2, v97, v181
	v_exp_f32_e32 v2, v2
	v_sub_f32_e32 v3, v98, v181
	v_exp_f32_e32 v3, v3
	v_sub_f32_e32 v4, v99, v181
	v_exp_f32_e32 v4, v4
	v_sub_f32_e32 v6, v100, v181
	v_add_f32_e32 v5, 0, v0
	v_exp_f32_e32 v6, v6
	v_sub_f32_e32 v7, v101, v181
	v_add_f32_e32 v5, v2, v5
	v_exp_f32_e32 v7, v7
	v_sub_f32_e32 v8, v102, v181
	v_add_f32_e32 v5, v3, v5
	v_exp_f32_e32 v8, v8
	v_sub_f32_e32 v9, v103, v181
	v_add_f32_e32 v5, v4, v5
	v_exp_f32_e32 v9, v9
	v_sub_f32_e32 v10, v104, v181
	v_add_f32_e32 v5, v6, v5
	v_exp_f32_e32 v10, v10
	v_sub_f32_e32 v11, v105, v181
	v_add_f32_e32 v5, v7, v5
	v_exp_f32_e32 v11, v11
	v_sub_f32_e32 v12, v106, v181
	v_add_f32_e32 v5, v8, v5
	v_exp_f32_e32 v12, v12
	v_sub_f32_e32 v13, v107, v181
	v_add_f32_e32 v5, v9, v5
	v_exp_f32_e32 v13, v13
	v_sub_f32_e32 v14, v108, v181
	v_add_f32_e32 v5, v10, v5
	v_exp_f32_e32 v14, v14
	v_sub_f32_e32 v15, v109, v181
	v_add_f32_e32 v5, v11, v5
	v_exp_f32_e32 v15, v15
	v_sub_f32_e32 v96, v110, v181
	v_add_f32_e32 v5, v12, v5
	v_exp_f32_e32 v96, v96
	v_sub_f32_e32 v97, v111, v181
	v_add_f32_e32 v5, v13, v5
	v_exp_f32_e32 v97, v97
	v_sub_f32_e32 v80, v80, v181
	v_add_f32_e32 v5, v14, v5
	v_exp_f32_e32 v80, v80
	v_sub_f32_e32 v81, v81, v181
	v_add_f32_e32 v5, v15, v5
	v_exp_f32_e32 v81, v81
	v_sub_f32_e32 v82, v82, v181
	v_add_f32_e32 v5, v96, v5
	v_exp_f32_e32 v82, v82
	v_sub_f32_e32 v83, v83, v181
	v_add_f32_e32 v5, v97, v5
	v_exp_f32_e32 v83, v83
	v_sub_f32_e32 v84, v84, v181
	v_add_f32_e32 v5, v80, v5
	v_exp_f32_e32 v84, v84
	v_sub_f32_e32 v85, v85, v181
	v_add_f32_e32 v5, v81, v5
	v_exp_f32_e32 v85, v85
	v_sub_f32_e32 v86, v86, v181
	v_add_f32_e32 v5, v82, v5
	v_exp_f32_e32 v86, v86
	v_sub_f32_e32 v87, v87, v181
	v_add_f32_e32 v5, v83, v5
	v_exp_f32_e32 v87, v87
	v_sub_f32_e32 v88, v88, v181
	v_add_f32_e32 v5, v84, v5
	v_exp_f32_e32 v88, v88
	v_sub_f32_e32 v89, v89, v181
	v_add_f32_e32 v5, v85, v5
	v_exp_f32_e32 v89, v89
	v_sub_f32_e32 v90, v90, v181
	v_add_f32_e32 v5, v86, v5
	v_exp_f32_e32 v90, v90
	v_sub_f32_e32 v91, v91, v181
	v_add_f32_e32 v5, v87, v5
	v_exp_f32_e32 v91, v91
	v_sub_f32_e32 v92, v92, v181
	v_add_f32_e32 v5, v88, v5
	v_exp_f32_e32 v92, v92
	v_sub_f32_e32 v93, v93, v181
	v_add_f32_e32 v5, v89, v5
	v_exp_f32_e32 v93, v93
	v_sub_f32_e32 v94, v94, v181
	v_add_f32_e32 v5, v90, v5
	v_exp_f32_e32 v94, v94
	v_sub_f32_e32 v95, v95, v181
	v_add_f32_e32 v5, v91, v5
	v_exp_f32_e32 v95, v95
	v_add_f32_e32 v5, v92, v5
	v_add_f32_e32 v5, v93, v5
	v_add_f32_e32 v5, v94, v5
	v_add_f32_e32 v5, v95, v5
	v_add_f32_e32 v180, v180, v5
	v_cvt_pk_bf16_f32 v2, v0, v2
	v_cvt_pk_bf16_f32 v3, v3, v4
	v_cvt_pk_bf16_f32 v4, v6, v7
	v_cvt_pk_bf16_f32 v5, v8, v9
	v_cvt_pk_bf16_f32 v6, v10, v11
	v_cvt_pk_bf16_f32 v7, v12, v13
	v_cvt_pk_bf16_f32 v8, v14, v15
	v_cvt_pk_bf16_f32 v9, v96, v97
	v_cvt_pk_bf16_f32 v10, v80, v81
	v_cvt_pk_bf16_f32 v11, v82, v83
	v_cvt_pk_bf16_f32 v12, v84, v85
	v_cvt_pk_bf16_f32 v13, v86, v87
	v_cvt_pk_bf16_f32 v80, v88, v89
	v_cvt_pk_bf16_f32 v81, v90, v91
	v_cvt_pk_bf16_f32 v82, v92, v93
	v_cvt_pk_bf16_f32 v83, v94, v95
	v_add_u32_e32 v0, s41, v175
	v_add_u32_e32 v14, v0, v176
	ds_read_b128 v[84:87], v14
	ds_read_b128 v[88:91], v14 offset:4096
	ds_read_b128 v[92:95], v14 offset:8192
	ds_read_b128 v[96:99], v14 offset:12288
	v_add_u32_e32 v15, v0, v177
	ds_read_b128 v[100:103], v15
	ds_read_b128 v[104:107], v15 offset:4096
	v_add_u32_e32 v14, v0, v178
	v_add_u32_e32 v0, v0, v179
	s_waitcnt lgkmcnt(5)
	v_mfma_f32_32x32x16_bf16 v[64:79], v[84:87], v[2:5], v[64:79]
	ds_read_b128 v[84:87], v15 offset:8192
	s_waitcnt lgkmcnt(5)
	v_mfma_f32_32x32x16_bf16 v[48:63], v[88:91], v[2:5], v[48:63]
	ds_read_b128 v[88:91], v15 offset:12288
	s_waitcnt lgkmcnt(5)
	v_mfma_f32_32x32x16_bf16 v[32:47], v[92:95], v[2:5], v[32:47]
	ds_read_b128 v[92:95], v14
	s_waitcnt lgkmcnt(5)
	v_mfma_f32_32x32x16_bf16 v[16:31], v[96:99], v[2:5], v[16:31]
	ds_read_b128 v[2:5], v14 offset:4096
	s_waitcnt lgkmcnt(5)
	v_mfma_f32_32x32x16_bf16 v[64:79], v[100:103], v[6:9], v[64:79]
	ds_read_b128 v[96:99], v14 offset:8192
	s_waitcnt lgkmcnt(5)
	v_mfma_f32_32x32x16_bf16 v[48:63], v[104:107], v[6:9], v[48:63]
	ds_read_b128 v[100:103], v14 offset:12288
	s_waitcnt lgkmcnt(5)
	v_mfma_f32_32x32x16_bf16 v[32:47], v[84:87], v[6:9], v[32:47]
	ds_read_b128 v[84:87], v0
	s_waitcnt lgkmcnt(5)
	v_mfma_f32_32x32x16_bf16 v[16:31], v[88:91], v[6:9], v[16:31]
	ds_read_b128 v[6:9], v0 offset:4096
	s_waitcnt lgkmcnt(5)
	v_mfma_f32_32x32x16_bf16 v[64:79], v[92:95], v[10:13], v[64:79]
	ds_read_b128 v[88:91], v0 offset:8192
	s_waitcnt lgkmcnt(5)
	v_mfma_f32_32x32x16_bf16 v[48:63], v[2:5], v[10:13], v[48:63]
	ds_read_b128 v[2:5], v0 offset:12288
	s_waitcnt lgkmcnt(5)
	v_mfma_f32_32x32x16_bf16 v[32:47], v[96:99], v[10:13], v[32:47]
	s_waitcnt lgkmcnt(4)
	v_mfma_f32_32x32x16_bf16 v[16:31], v[100:103], v[10:13], v[16:31]
	s_waitcnt lgkmcnt(3)
	v_mfma_f32_32x32x16_bf16 v[64:79], v[84:87], v[80:83], v[64:79]
	s_waitcnt lgkmcnt(2)
	v_mfma_f32_32x32x16_bf16 v[48:63], v[6:9], v[80:83], v[48:63]
	s_waitcnt lgkmcnt(1)
	v_mfma_f32_32x32x16_bf16 v[32:47], v[88:91], v[80:83], v[32:47]
	s_waitcnt lgkmcnt(0)
	v_mfma_f32_32x32x16_bf16 v[16:31], v[2:5], v[80:83], v[16:31]
	s_mov_b64 s[8:9], -1
	s_and_b64 vcc, exec, s[74:75]
	s_cbranch_vccnz .LBB0_1325

; __device__ __forceinline__ unsigned cvt_pk_bf16(float lo, float hi) { unsigned r; asm volatile("v_cvt_pk_bf16_f32 %0, %1, %2" : "=v"(r) : "v"(lo), "v"(hi)); return r; }
; __device__ __forceinline__ float bf_lo(unsigned w) { return __uint_as_float(w << 16); }
; __device__ __forceinline__ float bf_hi(unsigned w) { return __uint_as_float(w & 0xffff0000u); }
; #define GAS1 __attribute__((address_space(1)))
;     __device__ __forceinline__ void operator()(const f32x4 (&acc)[2][2][4][2], const Unit& u, int wr, int wc, int fr, int fq) const {
;     ...
;                 if (MODE == 3 || MODE == 4) {
;                     const u32x4 gw = *(const GAS1 u32x4*)(G + (size_t)row * ldg + col);
;                     const f32x4 g0 = {bf_lo(gw.x), bf_hi(gw.x), bf_lo(gw.y), bf_hi(gw.y)}, g1 = {bf_lo(gw.z), bf_hi(gw.z), bf_lo(gw.w), bf_hi(gw.w)};
;                     v0 = v0 * g0; v1 = v1 * g1;
;                     if (MODE == 4) {
;                         const u32x4 ow = *(const GAS1 u32x4*)((const bf16_t*)O + (size_t)row * ldc + col);
;                         const f32x4 o0 = {bf_lo(ow.x), bf_hi(ow.x), bf_lo(ow.y), bf_hi(ow.y)}, o1 = {bf_lo(ow.z), bf_hi(ow.z), bf_lo(ow.w), bf_hi(ow.w)};
;                         v0 += o0; v1 += o1;
;                     }
;                 }
;                 u32x4 w; w.x = cvt_pk_bf16(v0[0], v0[1]); w.y = cvt_pk_bf16(v0[2], v0[3]); w.z = cvt_pk_bf16(v1[0], v1[1]); w.w = cvt_pk_bf16(v1[2], v1[3]);
;                 if (bj == 0) asm volatile("ds_write_b128 %0, %1" :: "v"(wa), "v"(w)); else asm volatile("ds_write_b128 %0, %1 offset:64" :: "v"(wa), "v"(w));
;             }
;             asm volatile("ds_read_b128 %0, %1" : "=&v"(rb[g & 1][0]) : "v"(ra));
;             asm volatile("ds_read_b128 %0, %1 offset:1152" : "=&v"(rb[g & 1][1]) : "v"(ra));
;             if (g >= 1) {
;                 asm volatile("s_waitcnt lgkmcnt(4)" : "+v"(rb[(g - 1) & 1][0]), "+v"(rb[(g - 1) & 1][1]));
;                 bf16_t* ob = obase + (size_t)(((g - 1) >> 2) * HALF + ((g - 1) & 3) * 16) * ldc;
;                 *(GAS1 u32x4*)ob = rb[(g - 1) & 1][0]; *(GAS1 u32x4*)(ob + (size_t)8 * ldc) = rb[(g - 1) & 1][1];
;             }
.LBB0_1410:
	s_lshl_b32 s25, s34, 8
	s_lshl_b32 s34, s35, 8
	s_add_i32 s25, s25, s65
	v_or_b32_e32 v148, s34, v153
	v_or_b32_e32 v159, s25, v150
	v_mov_b64_e32 v[146:147], s[18:19]
	v_ashrrev_i32_e32 v149, 31, v148
	v_mad_i64_i32 v[160:161], s[36:37], v159, s74, v[146:147]
	v_lshlrev_b64 v[148:149], 1, v[148:149]
	v_lshl_add_u64 v[164:165], v[160:161], 0, v[148:149]
	v_add_u32_e32 v234, 0, v159
	v_mad_i64_i32 v[206:207], s[98:99], v234, s74, v[146:147]
	v_lshl_add_u64 v[206:207], v[206:207], 0, v[148:149]
	global_load_dwordx4 v[176:179], v[206:207], off
	global_load_dwordx4 v[180:183], v[206:207], off offset:64
	v_add_u32_e32 v234, 16, v159
	v_mad_i64_i32 v[206:207], s[98:99], v234, s74, v[146:147]
	v_lshl_add_u64 v[206:207], v[206:207], 0, v[148:149]
	global_load_dwordx4 v[184:187], v[206:207], off
	global_load_dwordx4 v[188:191], v[206:207], off offset:64
	v_add_u32_e32 v234, 32, v159
	v_mad_i64_i32 v[206:207], s[98:99], v234, s74, v[146:147]
	v_lshl_add_u64 v[206:207], v[206:207], 0, v[148:149]
	global_load_dwordx4 v[192:195], v[206:207], off
	global_load_dwordx4 v[196:199], v[206:207], off offset:64
	v_add_u32_e32 v234, 48, v159
	v_mad_i64_i32 v[206:207], s[98:99], v234, s74, v[146:147]
	v_lshl_add_u64 v[206:207], v[206:207], 0, v[148:149]
	global_load_dwordx4 v[202:205], v[206:207], off
	global_load_dwordx4 v[210:213], v[206:207], off offset:64
	v_add_u32_e32 v234, 128, v159
	v_mad_i64_i32 v[206:207], s[98:99], v234, s74, v[146:147]
	v_lshl_add_u64 v[206:207], v[206:207], 0, v[148:149]
	global_load_dwordx4 v[214:217], v[206:207], off
	global_load_dwordx4 v[218:221], v[206:207], off offset:64
	v_add_u32_e32 v234, 144, v159
	v_mad_i64_i32 v[206:207], s[98:99], v234, s74, v[146:147]
	v_lshl_add_u64 v[206:207], v[206:207], 0, v[148:149]
	global_load_dwordx4 v[222:225], v[206:207], off
	global_load_dwordx4 v[226:229], v[206:207], off offset:64
	v_add_u32_e32 v234, 160, v159
	v_mad_i64_i32 v[206:207], s[98:99], v234, s74, v[146:147]
	v_lshl_add_u64 v[206:207], v[206:207], 0, v[148:149]
	global_load_dwordx4 v[236:239], v[206:207], off
	global_load_dwordx4 v[240:243], v[206:207], off offset:64
	v_add_u32_e32 v234, 176, v159
	v_mad_i64_i32 v[206:207], s[98:99], v234, s74, v[146:147]
	v_lshl_add_u64 v[206:207], v[206:207], 0, v[148:149]
	global_load_dwordx4 v[246:249], v[206:207], off
	global_load_dwordx4 v[250:253], v[206:207], off offset:64
	s_ashr_i32 s35, s34, 31
	s_waitcnt vmcnt(15)
	v_mov_b32_e32 v160, v176
	v_mov_b32_e32 v161, v177
	v_mov_b32_e32 v162, v178
	v_mov_b32_e32 v163, v179
	v_lshlrev_b32_e32 v166, 16, v160
	v_and_b32_e32 v167, 0xffff0000, v160
	v_lshlrev_b32_e32 v160, 16, v161
	v_and_b32_e32 v161, 0xffff0000, v161
	v_lshlrev_b32_e32 v168, 16, v162
	v_and_b32_e32 v169, 0xffff0000, v162
	v_lshlrev_b32_e32 v162, 16, v163
	v_and_b32_e32 v163, 0xffff0000, v163
	v_pk_mul_f32 v[126:127], v[126:127], v[160:161]
	v_pk_mul_f32 v[160:161], v[122:123], v[162:163]
	v_pk_mul_f32 v[122:123], v[120:121], v[168:169]
	v_pk_mul_f32 v[124:125], v[124:125], v[166:167]
	s_nop 0
	v_cvt_pk_bf16_f32 v120, v124, v125
	v_cvt_pk_bf16_f32 v121, v126, v127
	v_cvt_pk_bf16_f32 v122, v122, v123
	v_cvt_pk_bf16_f32 v123, v160, v161
	v_or_b32_e32 v124, 16, v159
	ds_write_b128 v154, v[120:123]
	v_mad_i64_i32 v[124:125], s[36:37], v124, s74, v[146:147]
	v_lshl_add_u64 v[124:125], v[124:125], 0, v[148:149]
	s_waitcnt vmcnt(14)
	v_mov_b32_e32 v120, v180
	v_mov_b32_e32 v121, v181
	v_mov_b32_e32 v122, v182
	v_mov_b32_e32 v123, v183
	v_lshlrev_b32_e32 v126, 16, v120
	v_and_b32_e32 v127, 0xffff0000, v120
	v_lshlrev_b32_e32 v120, 16, v121
	v_and_b32_e32 v121, 0xffff0000, v121
	v_lshlrev_b32_e32 v160, 16, v122
	v_and_b32_e32 v161, 0xffff0000, v122
	v_lshlrev_b32_e32 v122, 16, v123
	v_and_b32_e32 v123, 0xffff0000, v123
	v_pk_mul_f32 v[118:119], v[118:119], v[120:121]
	v_pk_mul_f32 v[120:121], v[110:111], v[122:123]
	v_pk_mul_f32 v[110:111], v[108:109], v[160:161]
	v_pk_mul_f32 v[116:117], v[116:117], v[126:127]
	s_nop 0
	v_cvt_pk_bf16_f32 v108, v116, v117
	v_cvt_pk_bf16_f32 v109, v118, v119
	v_cvt_pk_bf16_f32 v110, v110, v111
	v_cvt_pk_bf16_f32 v111, v120, v121
	s_nop 0
	ds_write_b128 v154, v[108:111] offset:64
	ds_read_b128 v[108:111], v155
	ds_read_b128 v[116:119], v155 offset:1152
	s_waitcnt vmcnt(13)
	v_mov_b32_e32 v120, v184
	v_mov_b32_e32 v121, v185
	v_mov_b32_e32 v122, v186
	v_mov_b32_e32 v123, v187
	v_lshlrev_b32_e32 v126, 16, v120
	v_and_b32_e32 v127, 0xffff0000, v120
	v_lshlrev_b32_e32 v120, 16, v121
	v_and_b32_e32 v121, 0xffff0000, v121
	v_lshlrev_b32_e32 v160, 16, v122
	v_and_b32_e32 v161, 0xffff0000, v122
	v_lshlrev_b32_e32 v122, 16, v123
	v_and_b32_e32 v123, 0xffff0000, v123
	v_pk_mul_f32 v[114:115], v[114:115], v[120:121]
	v_pk_mul_f32 v[112:113], v[112:113], v[126:127]
	v_pk_mul_f32 v[120:121], v[106:107], v[122:123]
	v_pk_mul_f32 v[106:107], v[104:105], v[160:161]
	v_cvt_pk_bf16_f32 v104, v112, v113
	v_cvt_pk_bf16_f32 v105, v114, v115
	s_nop 0
	v_cvt_pk_bf16_f32 v106, v106, v107
	v_cvt_pk_bf16_f32 v107, v120, v121
	s_nop 0
	ds_write_b128 v154, v[104:107]
	v_or_b32_e32 v104, s25, v152
	v_ashrrev_i32_e32 v105, 31, v104
	v_lshlrev_b64 v[104:105], 12, v[104:105]
	v_lshl_add_u64 v[104:105], s[8:9], 0, v[104:105]
	v_lshl_add_u64 v[104:105], s[34:35], 1, v[104:105]
	v_or_b32_e32 v106, 32, v159
	v_lshl_add_u64 v[104:105], v[104:105], 0, s[12:13]
	v_mad_i64_i32 v[106:107], s[36:37], v106, s74, v[146:147]
	v_lshl_add_u64 v[104:105], v[104:105], 0, v[136:137]
	v_lshl_add_u64 v[120:121], v[106:107], 0, v[148:149]
	v_add_co_u32_e32 v106, vcc, s69, v104
	s_waitcnt vmcnt(12)
; __device__ __forceinline__ unsigned cvt_pk_bf16(float lo, float hi) { unsigned r; asm volatile("v_cvt_pk_bf16_f32 %0, %1, %2" : "=v"(r) : "v"(lo), "v"(hi)); return r; }
; __device__ __forceinline__ float bf_lo(unsigned w) { return __uint_as_float(w << 16); }
; __device__ __forceinline__ float bf_hi(unsigned w) { return __uint_as_float(w & 0xffff0000u); }
; #define GAS1 __attribute__((address_space(1)))
;     __device__ __forceinline__ void operator()(const f32x4 (&acc)[2][2][4][2], const Unit& u, int wr, int wc, int fr, int fq) const {
;     ...
;                 if (MODE == 3 || MODE == 4) {
;                     const u32x4 gw = *(const GAS1 u32x4*)(G + (size_t)row * ldg + col);
;                     const f32x4 g0 = {bf_lo(gw.x), bf_hi(gw.x), bf_lo(gw.y), bf_hi(gw.y)}, g1 = {bf_lo(gw.z), bf_hi(gw.z), bf_lo(gw.w), bf_hi(gw.w)};
;                     v0 = v0 * g0; v1 = v1 * g1;
;                     if (MODE == 4) {
;                         const u32x4 ow = *(const GAS1 u32x4*)((const bf16_t*)O + (size_t)row * ldc + col);
;                         const f32x4 o0 = {bf_lo(ow.x), bf_hi(ow.x), bf_lo(ow.y), bf_hi(ow.y)}, o1 = {bf_lo(ow.z), bf_hi(ow.z), bf_lo(ow.w), bf_hi(ow.w)};
;                         v0 += o0; v1 += o1;
;                     }
;                 }
;                 u32x4 w; w.x = cvt_pk_bf16(v0[0], v0[1]); w.y = cvt_pk_bf16(v0[2], v0[3]); w.z = cvt_pk_bf16(v1[0], v1[1]); w.w = cvt_pk_bf16(v1[2], v1[3]);
;                 if (bj == 0) asm volatile("ds_write_b128 %0, %1" :: "v"(wa), "v"(w)); else asm volatile("ds_write_b128 %0, %1 offset:64" :: "v"(wa), "v"(w));
;             }
;             asm volatile("ds_read_b128 %0, %1" : "=&v"(rb[g & 1][0]) : "v"(ra));
;             asm volatile("ds_read_b128 %0, %1 offset:1152" : "=&v"(rb[g & 1][1]) : "v"(ra));
;             if (g >= 1) {
;                 asm volatile("s_waitcnt lgkmcnt(4)" : "+v"(rb[(g - 1) & 1][0]), "+v"(rb[(g - 1) & 1][1]));
;                 bf16_t* ob = obase + (size_t)(((g - 1) >> 2) * HALF + ((g - 1) & 3) * 16) * ldc;
;                 *(GAS1 u32x4*)ob = rb[(g - 1) & 1][0]; *(GAS1 u32x4*)(ob + (size_t)8 * ldc) = rb[(g - 1) & 1][1];
;             }
	v_mov_b32_e32 v112, v188
	v_mov_b32_e32 v113, v189
	v_mov_b32_e32 v114, v190
	v_mov_b32_e32 v115, v191
	v_lshlrev_b32_e32 v122, 16, v112
	v_and_b32_e32 v123, 0xffff0000, v112
	v_lshlrev_b32_e32 v112, 16, v113
	v_and_b32_e32 v113, 0xffff0000, v113
	v_lshlrev_b32_e32 v124, 16, v114
	v_and_b32_e32 v125, 0xffff0000, v114
	v_lshlrev_b32_e32 v114, 16, v115
	v_and_b32_e32 v115, 0xffff0000, v115
	v_pk_mul_f32 v[102:103], v[102:103], v[112:113]
	v_pk_mul_f32 v[112:113], v[94:95], v[114:115]
	v_pk_mul_f32 v[94:95], v[92:93], v[124:125]
	v_pk_mul_f32 v[100:101], v[100:101], v[122:123]
	v_addc_co_u32_e32 v107, vcc, 0, v105, vcc
	v_cvt_pk_bf16_f32 v92, v100, v101
	v_cvt_pk_bf16_f32 v93, v102, v103
	v_cvt_pk_bf16_f32 v94, v94, v95
	v_cvt_pk_bf16_f32 v95, v112, v113
	s_nop 0
	ds_write_b128 v154, v[92:95] offset:64
	ds_read_b128 v[92:95], v155
	ds_read_b128 v[100:103], v155 offset:1152
	s_waitcnt lgkmcnt(4)
	global_store_dwordx4 v[104:105], v[108:111], off
	global_store_dwordx4 v[106:107], v[116:119], off
	s_waitcnt vmcnt(13)
	v_mov_b32_e32 v106, v192
	v_mov_b32_e32 v107, v193
	v_mov_b32_e32 v108, v194
	v_mov_b32_e32 v109, v195
	v_lshlrev_b32_e32 v110, 16, v106
	v_and_b32_e32 v111, 0xffff0000, v106
	v_lshlrev_b32_e32 v106, 16, v107
	v_and_b32_e32 v107, 0xffff0000, v107
	v_lshlrev_b32_e32 v112, 16, v108
	v_and_b32_e32 v113, 0xffff0000, v108
	v_lshlrev_b32_e32 v108, 16, v109
	v_and_b32_e32 v109, 0xffff0000, v109
	v_pk_mul_f32 v[98:99], v[98:99], v[106:107]
	v_pk_mul_f32 v[106:107], v[90:91], v[108:109]
	v_pk_mul_f32 v[90:91], v[88:89], v[112:113]
	v_pk_mul_f32 v[96:97], v[96:97], v[110:111]
	s_nop 0
	v_cvt_pk_bf16_f32 v88, v96, v97
	v_cvt_pk_bf16_f32 v89, v98, v99
	v_cvt_pk_bf16_f32 v90, v90, v91
	v_cvt_pk_bf16_f32 v91, v106, v107
	v_add_co_u32_e32 v98, vcc, s64, v104
	ds_write_b128 v154, v[88:91]
	v_or_b32_e32 v96, 48, v159
	v_addc_co_u32_e32 v99, vcc, 0, v105, vcc
	v_mad_i64_i32 v[96:97], s[34:35], v96, s74, v[146:147]
	v_add_co_u32_e32 v106, vcc, s68, v104
	v_lshl_add_u64 v[96:97], v[96:97], 0, v[148:149]
	s_nop 0
	v_addc_co_u32_e32 v107, vcc, 0, v105, vcc
	s_waitcnt vmcnt(12)
	v_mov_b32_e32 v88, v196
	v_mov_b32_e32 v89, v197
	v_mov_b32_e32 v90, v198
	v_mov_b32_e32 v91, v199
	v_lshlrev_b32_e32 v108, 16, v88
	v_and_b32_e32 v109, 0xffff0000, v88
	v_lshlrev_b32_e32 v88, 16, v89
	v_and_b32_e32 v89, 0xffff0000, v89
	v_lshlrev_b32_e32 v110, 16, v90
	v_and_b32_e32 v111, 0xffff0000, v90
	v_lshlrev_b32_e32 v90, 16, v91
	v_and_b32_e32 v91, 0xffff0000, v91
	v_pk_mul_f32 v[86:87], v[86:87], v[88:89]
	v_pk_mul_f32 v[88:89], v[78:79], v[90:91]
	v_pk_mul_f32 v[78:79], v[76:77], v[110:111]
	v_pk_mul_f32 v[84:85], v[84:85], v[108:109]
	s_nop 0
	v_cvt_pk_bf16_f32 v76, v84, v85
	v_cvt_pk_bf16_f32 v77, v86, v87
	v_cvt_pk_bf16_f32 v78, v78, v79
	v_cvt_pk_bf16_f32 v79, v88, v89
	s_nop 0
	ds_write_b128 v154, v[76:79] offset:64
	ds_read_b128 v[76:79], v155
	ds_read_b128 v[84:87], v155 offset:1152
	s_waitcnt lgkmcnt(4)
	global_store_dwordx4 v[98:99], v[92:95], off
	global_store_dwordx4 v[106:107], v[100:103], off
	s_waitcnt vmcnt(13)
	v_mov_b32_e32 v88, v202
	v_mov_b32_e32 v89, v203
	v_mov_b32_e32 v90, v204
	v_mov_b32_e32 v91, v205
	v_lshlrev_b32_e32 v92, 16, v88
	v_and_b32_e32 v93, 0xffff0000, v88
	v_lshlrev_b32_e32 v88, 16, v89
	v_and_b32_e32 v89, 0xffff0000, v89
	v_lshlrev_b32_e32 v94, 16, v90
	v_and_b32_e32 v95, 0xffff0000, v90
	v_lshlrev_b32_e32 v90, 16, v91
	v_and_b32_e32 v91, 0xffff0000, v91
	v_pk_mul_f32 v[82:83], v[82:83], v[88:89]
	v_pk_mul_f32 v[88:89], v[74:75], v[90:91]
	v_pk_mul_f32 v[74:75], v[72:73], v[94:95]
	v_pk_mul_f32 v[80:81], v[80:81], v[92:93]
	s_nop 0
	v_cvt_pk_bf16_f32 v72, v80, v81
	v_cvt_pk_bf16_f32 v73, v82, v83
	v_cvt_pk_bf16_f32 v74, v74, v75
	v_cvt_pk_bf16_f32 v75, v88, v89
	v_add_co_u32_e32 v82, vcc, s75, v104
	ds_write_b128 v154, v[72:75]
	v_add_u32_e32 v80, 0x80, v159
	v_addc_co_u32_e32 v83, vcc, 0, v105, vcc
	v_mad_i64_i32 v[80:81], s[34:35], v80, s74, v[146:147]
	v_add_co_u32_e32 v88, vcc, s76, v104
	v_lshl_add_u64 v[80:81], v[80:81], 0, v[148:149]
	s_nop 0
	v_addc_co_u32_e32 v89, vcc, 0, v105, vcc
	s_waitcnt vmcnt(12)
	v_mov_b32_e32 v72, v210
	v_mov_b32_e32 v73, v211
	v_mov_b32_e32 v74, v212
	v_mov_b32_e32 v75, v213
	v_lshlrev_b32_e32 v90, 16, v72
	v_and_b32_e32 v91, 0xffff0000, v72
	v_lshlrev_b32_e32 v72, 16, v73
	v_and_b32_e32 v73, 0xffff0000, v73
	v_lshlrev_b32_e32 v92, 16, v74
	v_and_b32_e32 v93, 0xffff0000, v74
	v_lshlrev_b32_e32 v74, 16, v75
	v_and_b32_e32 v75, 0xffff0000, v75
	v_pk_mul_f32 v[70:71], v[70:71], v[72:73]
	v_pk_mul_f32 v[72:73], v[66:67], v[74:75]
	v_pk_mul_f32 v[66:67], v[64:65], v[92:93]
	v_pk_mul_f32 v[68:69], v[68:69], v[90:91]
	s_nop 0
	v_cvt_pk_bf16_f32 v64, v68, v69
	v_cvt_pk_bf16_f32 v65, v70, v71
	v_cvt_pk_bf16_f32 v66, v66, v67
	v_cvt_pk_bf16_f32 v67, v72, v73
	s_nop 0
	ds_write_b128 v154, v[64:67] offset:64
	ds_read_b128 v[64:67], v155
	ds_read_b128 v[68:71], v155 offset:1152
	s_waitcnt lgkmcnt(4)
	global_store_dwordx4 v[82:83], v[76:79], off
	global_store_dwordx4 v[88:89], v[84:87], off
	s_waitcnt vmcnt(13)
	v_mov_b32_e32 v72, v214
	v_mov_b32_e32 v73, v215
	v_mov_b32_e32 v74, v216
	v_mov_b32_e32 v75, v217
	v_lshlrev_b32_e32 v76, 16, v72
	v_and_b32_e32 v77, 0xffff0000, v72
	v_lshlrev_b32_e32 v72, 16, v73
	v_and_b32_e32 v73, 0xffff0000, v73
	v_lshlrev_b32_e32 v78, 16, v74
	v_and_b32_e32 v79, 0xffff0000, v74
	v_lshlrev_b32_e32 v74, 16, v75
	v_and_b32_e32 v75, 0xffff0000, v75
	v_pk_mul_f32 v[62:63], v[62:63], v[72:73]
	v_pk_mul_f32 v[72:73], v[58:59], v[74:75]
	v_pk_mul_f32 v[58:59], v[56:57], v[78:79]
	v_pk_mul_f32 v[60:61], v[60:61], v[76:77]
	s_nop 0
	v_cvt_pk_bf16_f32 v56, v60, v61
	v_cvt_pk_bf16_f32 v57, v62, v63
	v_cvt_pk_bf16_f32 v58, v58, v59
	v_cvt_pk_bf16_f32 v59, v72, v73
	v_add_co_u32_e32 v62, vcc, s77, v104
	ds_write_b128 v154, v[56:59]
	v_add_u32_e32 v60, 0x90, v159
	v_addc_co_u32_e32 v63, vcc, 0, v105, vcc
	v_mad_i64_i32 v[60:61], s[34:35], v60, s74, v[146:147]
	v_add_co_u32_e32 v72, vcc, s79, v104
	v_lshl_add_u64 v[60:61], v[60:61], 0, v[148:149]
	s_nop 0
	v_addc_co_u32_e32 v73, vcc, 0, v105, vcc
	s_waitcnt vmcnt(12)
; __device__ __forceinline__ unsigned cvt_pk_bf16(float lo, float hi) { unsigned r; asm volatile("v_cvt_pk_bf16_f32 %0, %1, %2" : "=v"(r) : "v"(lo), "v"(hi)); return r; }
; __device__ __forceinline__ float bf_lo(unsigned w) { return __uint_as_float(w << 16); }
; __device__ __forceinline__ float bf_hi(unsigned w) { return __uint_as_float(w & 0xffff0000u); }
; #define GAS1 __attribute__((address_space(1)))
;     __device__ __forceinline__ void operator()(const f32x4 (&acc)[2][2][4][2], const Unit& u, int wr, int wc, int fr, int fq) const {
;     ...
;                 if (MODE == 3 || MODE == 4) {
;                     const u32x4 gw = *(const GAS1 u32x4*)(G + (size_t)row * ldg + col);
;                     const f32x4 g0 = {bf_lo(gw.x), bf_hi(gw.x), bf_lo(gw.y), bf_hi(gw.y)}, g1 = {bf_lo(gw.z), bf_hi(gw.z), bf_lo(gw.w), bf_hi(gw.w)};
;                     v0 = v0 * g0; v1 = v1 * g1;
;                     if (MODE == 4) {
;                         const u32x4 ow = *(const GAS1 u32x4*)((const bf16_t*)O + (size_t)row * ldc + col);
;                         const f32x4 o0 = {bf_lo(ow.x), bf_hi(ow.x), bf_lo(ow.y), bf_hi(ow.y)}, o1 = {bf_lo(ow.z), bf_hi(ow.z), bf_lo(ow.w), bf_hi(ow.w)};
;                         v0 += o0; v1 += o1;
;                     }
;                 }
;                 u32x4 w; w.x = cvt_pk_bf16(v0[0], v0[1]); w.y = cvt_pk_bf16(v0[2], v0[3]); w.z = cvt_pk_bf16(v1[0], v1[1]); w.w = cvt_pk_bf16(v1[2], v1[3]);
;                 if (bj == 0) asm volatile("ds_write_b128 %0, %1" :: "v"(wa), "v"(w)); else asm volatile("ds_write_b128 %0, %1 offset:64" :: "v"(wa), "v"(w));
;             }
;             asm volatile("ds_read_b128 %0, %1" : "=&v"(rb[g & 1][0]) : "v"(ra));
;             asm volatile("ds_read_b128 %0, %1 offset:1152" : "=&v"(rb[g & 1][1]) : "v"(ra));
;             if (g >= 1) {
;                 asm volatile("s_waitcnt lgkmcnt(4)" : "+v"(rb[(g - 1) & 1][0]), "+v"(rb[(g - 1) & 1][1]));
;                 bf16_t* ob = obase + (size_t)(((g - 1) >> 2) * HALF + ((g - 1) & 3) * 16) * ldc;
;                 *(GAS1 u32x4*)ob = rb[(g - 1) & 1][0]; *(GAS1 u32x4*)(ob + (size_t)8 * ldc) = rb[(g - 1) & 1][1];
;             }
	v_mov_b32_e32 v56, v218
	v_mov_b32_e32 v57, v219
	v_mov_b32_e32 v58, v220
	v_mov_b32_e32 v59, v221
	v_lshlrev_b32_e32 v74, 16, v56
	v_and_b32_e32 v75, 0xffff0000, v56
	v_lshlrev_b32_e32 v56, 16, v57
	v_and_b32_e32 v57, 0xffff0000, v57
	v_lshlrev_b32_e32 v76, 16, v58
	v_and_b32_e32 v77, 0xffff0000, v58
	v_lshlrev_b32_e32 v58, 16, v59
	v_and_b32_e32 v59, 0xffff0000, v59
	v_pk_mul_f32 v[54:55], v[54:55], v[56:57]
	v_pk_mul_f32 v[56:57], v[46:47], v[58:59]
	v_pk_mul_f32 v[46:47], v[44:45], v[76:77]
	v_pk_mul_f32 v[52:53], v[52:53], v[74:75]
	s_nop 0
	v_cvt_pk_bf16_f32 v44, v52, v53
	v_cvt_pk_bf16_f32 v45, v54, v55
	v_cvt_pk_bf16_f32 v46, v46, v47
	v_cvt_pk_bf16_f32 v47, v56, v57
	s_nop 0
	ds_write_b128 v154, v[44:47] offset:64
	ds_read_b128 v[44:47], v155
	ds_read_b128 v[52:55], v155 offset:1152
	s_waitcnt lgkmcnt(4)
	global_store_dwordx4 v[62:63], v[64:67], off
	global_store_dwordx4 v[72:73], v[68:71], off
	s_waitcnt vmcnt(13)
	v_mov_b32_e32 v56, v222
	v_mov_b32_e32 v57, v223
	v_mov_b32_e32 v58, v224
	v_mov_b32_e32 v59, v225
	v_lshlrev_b32_e32 v62, 16, v56
	v_and_b32_e32 v63, 0xffff0000, v56
	v_lshlrev_b32_e32 v56, 16, v57
	v_and_b32_e32 v57, 0xffff0000, v57
	v_lshlrev_b32_e32 v64, 16, v58
	v_and_b32_e32 v65, 0xffff0000, v58
	v_lshlrev_b32_e32 v58, 16, v59
	v_and_b32_e32 v59, 0xffff0000, v59
	v_pk_mul_f32 v[50:51], v[50:51], v[56:57]
	v_pk_mul_f32 v[56:57], v[42:43], v[58:59]
	v_pk_mul_f32 v[42:43], v[40:41], v[64:65]
	v_pk_mul_f32 v[48:49], v[48:49], v[62:63]
	s_nop 0
	v_cvt_pk_bf16_f32 v40, v48, v49
	v_cvt_pk_bf16_f32 v41, v50, v51
	v_cvt_pk_bf16_f32 v42, v42, v43
	v_cvt_pk_bf16_f32 v43, v56, v57
	v_add_co_u32_e32 v50, vcc, s80, v104
	ds_write_b128 v154, v[40:43]
	v_add_u32_e32 v48, 0xa0, v159
	v_addc_co_u32_e32 v51, vcc, 0, v105, vcc
	v_mad_i64_i32 v[48:49], s[34:35], v48, s74, v[146:147]
	v_add_co_u32_e32 v56, vcc, s81, v104
	v_lshl_add_u64 v[48:49], v[48:49], 0, v[148:149]
	s_nop 0
	v_addc_co_u32_e32 v57, vcc, 0, v105, vcc
	s_waitcnt vmcnt(12)
	v_mov_b32_e32 v40, v226
	v_mov_b32_e32 v41, v227
	v_mov_b32_e32 v42, v228
	v_mov_b32_e32 v43, v229
	v_lshlrev_b32_e32 v58, 16, v40
	v_and_b32_e32 v59, 0xffff0000, v40
	v_lshlrev_b32_e32 v40, 16, v41
	v_and_b32_e32 v41, 0xffff0000, v41
	v_lshlrev_b32_e32 v60, 16, v42
	v_and_b32_e32 v61, 0xffff0000, v42
	v_lshlrev_b32_e32 v42, 16, v43
	v_and_b32_e32 v43, 0xffff0000, v43
	v_pk_mul_f32 v[38:39], v[38:39], v[40:41]
	v_pk_mul_f32 v[40:41], v[30:31], v[42:43]
	v_pk_mul_f32 v[30:31], v[28:29], v[60:61]
	v_pk_mul_f32 v[36:37], v[36:37], v[58:59]
	s_nop 0
	v_cvt_pk_bf16_f32 v28, v36, v37
	v_cvt_pk_bf16_f32 v29, v38, v39
	v_cvt_pk_bf16_f32 v30, v30, v31
	v_cvt_pk_bf16_f32 v31, v40, v41
	s_nop 0
	ds_write_b128 v154, v[28:31] offset:64
	ds_read_b128 v[28:31], v155
	ds_read_b128 v[36:39], v155 offset:1152
	s_waitcnt lgkmcnt(4)
	global_store_dwordx4 v[50:51], v[44:47], off
	global_store_dwordx4 v[56:57], v[52:55], off
	s_waitcnt vmcnt(13)
	v_mov_b32_e32 v40, v236
	v_mov_b32_e32 v41, v237
	v_mov_b32_e32 v42, v238
	v_mov_b32_e32 v43, v239
	v_lshlrev_b32_e32 v44, 16, v40
	v_and_b32_e32 v45, 0xffff0000, v40
	v_lshlrev_b32_e32 v40, 16, v41
	v_and_b32_e32 v41, 0xffff0000, v41
	v_lshlrev_b32_e32 v46, 16, v42
	v_and_b32_e32 v47, 0xffff0000, v42
	v_lshlrev_b32_e32 v42, 16, v43
	v_and_b32_e32 v43, 0xffff0000, v43
	v_pk_mul_f32 v[34:35], v[34:35], v[40:41]
	v_pk_mul_f32 v[40:41], v[26:27], v[42:43]
	v_pk_mul_f32 v[26:27], v[24:25], v[46:47]
	v_pk_mul_f32 v[32:33], v[32:33], v[44:45]
	s_nop 0
	v_cvt_pk_bf16_f32 v24, v32, v33
	v_cvt_pk_bf16_f32 v25, v34, v35
	v_cvt_pk_bf16_f32 v26, v26, v27
	v_cvt_pk_bf16_f32 v27, v40, v41
	v_add_co_u32_e32 v34, vcc, s82, v104
	ds_write_b128 v154, v[24:27]
	v_add_u32_e32 v32, 0xb0, v159
	v_addc_co_u32_e32 v35, vcc, 0, v105, vcc
	v_mad_i64_i32 v[32:33], s[34:35], v32, s74, v[146:147]
	v_add_co_u32_e32 v40, vcc, s83, v104
	v_lshl_add_u64 v[32:33], v[32:33], 0, v[148:149]
	s_nop 0
	v_addc_co_u32_e32 v41, vcc, 0, v105, vcc
	s_waitcnt vmcnt(12)
	v_mov_b32_e32 v24, v240
	v_mov_b32_e32 v25, v241
	v_mov_b32_e32 v26, v242
	v_mov_b32_e32 v27, v243
	v_lshlrev_b32_e32 v42, 16, v24
	v_and_b32_e32 v43, 0xffff0000, v24
	v_lshlrev_b32_e32 v24, 16, v25
	v_and_b32_e32 v25, 0xffff0000, v25
	v_lshlrev_b32_e32 v44, 16, v26
	v_and_b32_e32 v45, 0xffff0000, v26
	v_lshlrev_b32_e32 v26, 16, v27
	v_and_b32_e32 v27, 0xffff0000, v27
	v_pk_mul_f32 v[22:23], v[22:23], v[24:25]
	v_pk_mul_f32 v[24:25], v[14:15], v[26:27]
	v_pk_mul_f32 v[14:15], v[12:13], v[44:45]
	v_pk_mul_f32 v[20:21], v[20:21], v[42:43]
	s_nop 0
	v_cvt_pk_bf16_f32 v12, v20, v21
	v_cvt_pk_bf16_f32 v13, v22, v23
	v_cvt_pk_bf16_f32 v14, v14, v15
	v_cvt_pk_bf16_f32 v15, v24, v25
	s_nop 0
	ds_write_b128 v154, v[12:15] offset:64
	ds_read_b128 v[12:15], v155
	ds_read_b128 v[20:23], v155 offset:1152
	s_waitcnt lgkmcnt(4)
	global_store_dwordx4 v[34:35], v[28:31], off
	global_store_dwordx4 v[40:41], v[36:39], off
	s_waitcnt vmcnt(13)
	v_mov_b32_e32 v24, v246
	v_mov_b32_e32 v25, v247
	v_mov_b32_e32 v26, v248
	v_mov_b32_e32 v27, v249
	v_lshlrev_b32_e32 v28, 16, v24
	v_and_b32_e32 v29, 0xffff0000, v24
	v_lshlrev_b32_e32 v24, 16, v25
	v_and_b32_e32 v25, 0xffff0000, v25
	v_lshlrev_b32_e32 v30, 16, v26
	v_and_b32_e32 v31, 0xffff0000, v26
	v_lshlrev_b32_e32 v26, 16, v27
	v_and_b32_e32 v27, 0xffff0000, v27
	v_pk_mul_f32 v[18:19], v[18:19], v[24:25]
	v_pk_mul_f32 v[24:25], v[10:11], v[26:27]
	v_pk_mul_f32 v[10:11], v[8:9], v[30:31]
	v_pk_mul_f32 v[16:17], v[16:17], v[28:29]
	s_nop 0
	v_cvt_pk_bf16_f32 v8, v16, v17
	v_cvt_pk_bf16_f32 v9, v18, v19
	v_cvt_pk_bf16_f32 v10, v10, v11
	v_cvt_pk_bf16_f32 v11, v24, v25
	v_add_co_u32_e32 v16, vcc, s84, v104
	ds_write_b128 v154, v[8:11]
	s_nop 0
	v_addc_co_u32_e32 v17, vcc, 0, v105, vcc
	v_add_co_u32_e32 v18, vcc, s85, v104
	s_waitcnt vmcnt(12)
	v_mov_b32_e32 v8, v250
	v_mov_b32_e32 v9, v251
	v_mov_b32_e32 v10, v252
	v_mov_b32_e32 v11, v253
	v_lshlrev_b32_e32 v28, 16, v8
	v_addc_co_u32_e32 v19, vcc, 0, v105, vcc
	v_add_co_u32_e32 v24, vcc, 0xb0000, v104
	v_and_b32_e32 v29, 0xffff0000, v8
	v_lshlrev_b32_e32 v8, 16, v9
	v_and_b32_e32 v9, 0xffff0000, v9
	v_lshlrev_b32_e32 v30, 16, v10
	v_and_b32_e32 v31, 0xffff0000, v10
	v_lshlrev_b32_e32 v10, 16, v11
	v_and_b32_e32 v11, 0xffff0000, v11
	v_addc_co_u32_e32 v25, vcc, 0, v105, vcc
	v_pk_mul_f32 v[6:7], v[6:7], v[8:9]
	v_pk_mul_f32 v[8:9], v[2:3], v[10:11]
	v_pk_mul_f32 v[2:3], v[0:1], v[30:31]
	v_add_co_u32_e32 v26, vcc, 0xb8000, v104
	v_pk_mul_f32 v[4:5], v[4:5], v[28:29]
	s_nop 0
	v_addc_co_u32_e32 v27, vcc, 0, v105, vcc
	v_cvt_pk_bf16_f32 v0, v4, v5
	v_cvt_pk_bf16_f32 v1, v6, v7
	v_cvt_pk_bf16_f32 v2, v2, v3
	v_cvt_pk_bf16_f32 v3, v8, v9
	s_andn2_b64 vcc, exec, s[6:7]
	ds_write_b128 v154, v[0:3] offset:64
	ds_read_b128 v[0:3], v155
	ds_read_b128 v[4:7], v155 offset:1152
	s_waitcnt lgkmcnt(4)
	global_store_dwordx4 v[16:17], v[12:15], off
	global_store_dwordx4 v[18:19], v[20:23], off
	s_waitcnt lgkmcnt(0)
	s_mov_b64 s[6:7], -1
	global_store_dwordx4 v[24:25], v[0:3], off
	global_store_dwordx4 v[26:27], v[4:7], off
	s_cbranch_vccnz .LBB0_1399
; #define PG8_BAR __builtin_amdgcn_s_barrier()
; template <class Epi, class Sched, bool ALIGN_EPI = false, bool SP2 = false>
; __device__ __forceinline__ void gemm_phase(PG8_LAS unsigned char* lds, const Gemm g, const Sched& S, const Epi& E) {
;     ...
;         if (!has_next) break;
; #pragma unroll
;         for (int a = 0; a < 2; ++a)
; #pragma unroll
;             for (int b = 0; b < 2; ++b)
; #pragma unroll
;                 for (int m = 0; m < 4; ++m)
; #pragma unroll
;                     for (int n = 0; n < 2; ++n) acc[a][b][m][n] = (f32x4){0.f, 0.f, 0.f, 0.f};
;         cur = nxt; cA = nA; cB = nB; ++ui;
;         if constexpr (ALIGN_EPI) { if (wr == 1) PG8_BAR; }
;     }
	s_andn2_b64 vcc, exec, s[16:17]
	s_cbranch_vccnz .LBB0_1398
	s_barrier
	s_branch .LBB0_1398

; __device__ __forceinline__ unsigned cvt_pk_bf16(float lo, float hi) { unsigned r; asm volatile("v_cvt_pk_bf16_f32 %0, %1, %2" : "=v"(r) : "v"(lo), "v"(hi)); return r; }
; __device__ __forceinline__ float bf_lo(unsigned w) { return __uint_as_float(w << 16); }
; __device__ __forceinline__ float bf_hi(unsigned w) { return __uint_as_float(w & 0xffff0000u); }
; #define GAS1 __attribute__((address_space(1)))
;     __device__ __forceinline__ void operator()(const f32x4 (&acc)[2][2][4][2], const Unit& u, int wr, int wc, int fr, int fq) const {
;     ...
;                 if (MODE == 3 || MODE == 4) {
;                     const u32x4 gw = *(const GAS1 u32x4*)(G + (size_t)row * ldg + col);
;                     const f32x4 g0 = {bf_lo(gw.x), bf_hi(gw.x), bf_lo(gw.y), bf_hi(gw.y)}, g1 = {bf_lo(gw.z), bf_hi(gw.z), bf_lo(gw.w), bf_hi(gw.w)};
;                     v0 = v0 * g0; v1 = v1 * g1;
;                     if (MODE == 4) {
;                         const u32x4 ow = *(const GAS1 u32x4*)((const bf16_t*)O + (size_t)row * ldc + col);
;                         const f32x4 o0 = {bf_lo(ow.x), bf_hi(ow.x), bf_lo(ow.y), bf_hi(ow.y)}, o1 = {bf_lo(ow.z), bf_hi(ow.z), bf_lo(ow.w), bf_hi(ow.w)};
;                         v0 += o0; v1 += o1;
;                     }
;                 }
;                 u32x4 w; w.x = cvt_pk_bf16(v0[0], v0[1]); w.y = cvt_pk_bf16(v0[2], v0[3]); w.z = cvt_pk_bf16(v1[0], v1[1]); w.w = cvt_pk_bf16(v1[2], v1[3]);
;                 if (bj == 0) asm volatile("ds_write_b128 %0, %1" :: "v"(wa), "v"(w)); else asm volatile("ds_write_b128 %0, %1 offset:64" :: "v"(wa), "v"(w));
;             }
;             asm volatile("ds_read_b128 %0, %1" : "=&v"(rb[g & 1][0]) : "v"(ra));
;             asm volatile("ds_read_b128 %0, %1 offset:1152" : "=&v"(rb[g & 1][1]) : "v"(ra));
;             if (g >= 1) {
;                 asm volatile("s_waitcnt lgkmcnt(4)" : "+v"(rb[(g - 1) & 1][0]), "+v"(rb[(g - 1) & 1][1]));
;                 bf16_t* ob = obase + (size_t)(((g - 1) >> 2) * HALF + ((g - 1) & 3) * 16) * ldc;
;                 *(GAS1 u32x4*)ob = rb[(g - 1) & 1][0]; *(GAS1 u32x4*)(ob + (size_t)8 * ldc) = rb[(g - 1) & 1][1];
;             }
.LBB0_1434:
	s_lshl_b32 s21, s28, 8
	s_add_i32 s21, s21, s63
	v_or_b32_e32 v148, s21, v152
	s_lshl_b32 s28, s29, 8
	v_or_b32_e32 v146, s28, v155
	v_ashrrev_i32_e32 v149, 31, v148
	v_mov_b64_e32 v[150:151], s[14:15]
	v_ashrrev_i32_e32 v147, 31, v146
	v_lshlrev_b64 v[166:167], 12, v[148:149]
	v_mad_i64_i32 v[162:163], s[30:31], v148, s72, v[150:151]
	v_lshlrev_b64 v[146:147], 1, v[146:147]
	v_lshl_add_u64 v[166:167], s[8:9], 0, v[166:167]
	v_lshl_add_u64 v[176:177], v[162:163], 0, v[146:147]
	v_lshl_add_u64 v[178:179], v[166:167], 0, v[146:147]
	v_add_u32_e32 v254, 0, v148
	v_ashrrev_i32_e32 v255, 31, v254
	v_mad_i64_i32 v[206:207], s[98:99], v254, s72, v[150:151]
	v_lshlrev_b64 v[232:233], 12, v[254:255]
	v_lshl_add_u64 v[206:207], v[206:207], 0, v[146:147]
	v_lshl_add_u64 v[232:233], s[8:9], 0, v[232:233]
	v_lshl_add_u64 v[232:233], v[232:233], 0, v[146:147]
	global_load_dwordx4 v[188:191], v[206:207], off
	global_load_dwordx4 v[192:195], v[232:233], off
	global_load_dwordx4 v[196:199], v[206:207], off offset:64
	global_load_dwordx4 v[202:205], v[232:233], off offset:64
	v_add_u32_e32 v254, 16, v148
	v_ashrrev_i32_e32 v255, 31, v254
	v_mad_i64_i32 v[206:207], s[98:99], v254, s72, v[150:151]
	v_lshlrev_b64 v[232:233], 12, v[254:255]
	v_lshl_add_u64 v[206:207], v[206:207], 0, v[146:147]
	v_lshl_add_u64 v[232:233], s[8:9], 0, v[232:233]
	v_lshl_add_u64 v[232:233], v[232:233], 0, v[146:147]
	global_load_dwordx4 v[210:213], v[206:207], off
	global_load_dwordx4 v[214:217], v[232:233], off
	global_load_dwordx4 v[218:221], v[206:207], off offset:64
	global_load_dwordx4 v[222:225], v[232:233], off offset:64
	v_add_u32_e32 v254, 32, v148
	v_ashrrev_i32_e32 v255, 31, v254
	v_mad_i64_i32 v[206:207], s[98:99], v254, s72, v[150:151]
	v_lshlrev_b64 v[232:233], 12, v[254:255]
	v_lshl_add_u64 v[206:207], v[206:207], 0, v[146:147]
	v_lshl_add_u64 v[232:233], s[8:9], 0, v[232:233]
	v_lshl_add_u64 v[232:233], v[232:233], 0, v[146:147]
	global_load_dwordx4 v[226:229], v[206:207], off
	global_load_dwordx4 v[236:239], v[232:233], off
	global_load_dwordx4 v[240:243], v[206:207], off offset:64
	global_load_dwordx4 v[246:249], v[232:233], off offset:64
	s_ashr_i32 s29, s28, 31
	s_waitcnt vmcnt(10)
	v_mov_b32_e32 v162, v188
	v_mov_b32_e32 v163, v189
	v_mov_b32_e32 v164, v190
	v_mov_b32_e32 v165, v191
	v_mov_b32_e32 v166, v192
	v_mov_b32_e32 v167, v193
	v_mov_b32_e32 v168, v194
	v_mov_b32_e32 v169, v195
	v_lshlrev_b32_e32 v180, 16, v162
	v_and_b32_e32 v181, 0xffff0000, v162
	v_lshlrev_b32_e32 v162, 16, v163
	v_and_b32_e32 v163, 0xffff0000, v163
	v_lshlrev_b32_e32 v182, 16, v164
	v_and_b32_e32 v183, 0xffff0000, v164
	v_lshlrev_b32_e32 v164, 16, v165
	v_and_b32_e32 v165, 0xffff0000, v165
	v_lshlrev_b32_e32 v184, 16, v166
	v_and_b32_e32 v185, 0xffff0000, v166
	v_lshlrev_b32_e32 v166, 16, v167
	v_and_b32_e32 v167, 0xffff0000, v167
	v_lshlrev_b32_e32 v186, 16, v168
	v_and_b32_e32 v187, 0xffff0000, v168
	v_lshlrev_b32_e32 v168, 16, v169
	v_and_b32_e32 v169, 0xffff0000, v169
	v_pk_fma_f32 v[126:127], v[126:127], v[162:163], v[166:167]
	v_pk_fma_f32 v[162:163], v[122:123], v[164:165], v[168:169]
	v_pk_fma_f32 v[122:123], v[120:121], v[182:183], v[186:187]
	v_pk_fma_f32 v[124:125], v[124:125], v[180:181], v[184:185]
	s_nop 0
	v_cvt_pk_bf16_f32 v120, v124, v125
	v_cvt_pk_bf16_f32 v121, v126, v127
	v_cvt_pk_bf16_f32 v122, v122, v123
	v_cvt_pk_bf16_f32 v123, v162, v163
	v_or_b32_e32 v162, 16, v148
	ds_write_b128 v156, v[120:123]
	v_ashrrev_i32_e32 v163, 31, v162
	v_mad_i64_i32 v[164:165], s[30:31], v162, s72, v[150:151]
	v_lshl_add_u64 v[164:165], v[164:165], 0, v[146:147]
	s_waitcnt vmcnt(9)
	v_mov_b32_e32 v120, v196
	v_mov_b32_e32 v121, v197
	v_mov_b32_e32 v122, v198
	v_mov_b32_e32 v123, v199
	v_lshlrev_b32_e32 v166, 16, v120
	v_and_b32_e32 v167, 0xffff0000, v120
	v_lshlrev_b32_e32 v120, 16, v121
	v_and_b32_e32 v121, 0xffff0000, v121
	s_waitcnt vmcnt(8)
	v_mov_b32_e32 v124, v202
	v_mov_b32_e32 v125, v203
	v_mov_b32_e32 v126, v204
	v_mov_b32_e32 v127, v205
	v_lshlrev_b32_e32 v176, 16, v124
	v_and_b32_e32 v177, 0xffff0000, v124
	v_lshlrev_b32_e32 v124, 16, v125
	v_and_b32_e32 v125, 0xffff0000, v125
	v_lshlrev_b32_e32 v168, 16, v122
	v_and_b32_e32 v169, 0xffff0000, v122
	v_lshlrev_b32_e32 v122, 16, v123
	v_and_b32_e32 v123, 0xffff0000, v123
	v_lshlrev_b32_e32 v178, 16, v126
	v_and_b32_e32 v179, 0xffff0000, v126
	v_lshlrev_b32_e32 v126, 16, v127
	v_and_b32_e32 v127, 0xffff0000, v127
	v_pk_fma_f32 v[118:119], v[118:119], v[120:121], v[124:125]
	v_lshlrev_b64 v[124:125], 12, v[162:163]
	v_pk_fma_f32 v[120:121], v[114:115], v[122:123], v[126:127]
	v_pk_fma_f32 v[114:115], v[112:113], v[168:169], v[178:179]
	v_lshl_add_u64 v[124:125], s[8:9], 0, v[124:125]
	v_pk_fma_f32 v[116:117], v[116:117], v[166:167], v[176:177]
	v_lshl_add_u64 v[162:163], v[124:125], 0, v[146:147]
	v_cvt_pk_bf16_f32 v112, v116, v117
	v_cvt_pk_bf16_f32 v113, v118, v119
	v_cvt_pk_bf16_f32 v114, v114, v115
	v_cvt_pk_bf16_f32 v115, v120, v121
	s_nop 0
	ds_write_b128 v156, v[112:115] offset:64
	ds_read_b128 v[112:115], v157
	ds_read_b128 v[116:119], v157 offset:1152
	s_waitcnt vmcnt(7)
	v_mov_b32_e32 v120, v210
	v_mov_b32_e32 v121, v211
	v_mov_b32_e32 v122, v212
	v_mov_b32_e32 v123, v213
	v_lshlrev_b32_e32 v166, 16, v120
	v_and_b32_e32 v167, 0xffff0000, v120
	v_lshlrev_b32_e32 v120, 16, v121
	v_and_b32_e32 v121, 0xffff0000, v121
	v_lshlrev_b32_e32 v168, 16, v122
	v_and_b32_e32 v169, 0xffff0000, v122
	v_lshlrev_b32_e32 v122, 16, v123
	v_and_b32_e32 v123, 0xffff0000, v123
	s_waitcnt vmcnt(6)
; __device__ __forceinline__ unsigned cvt_pk_bf16(float lo, float hi) { unsigned r; asm volatile("v_cvt_pk_bf16_f32 %0, %1, %2" : "=v"(r) : "v"(lo), "v"(hi)); return r; }
; __device__ __forceinline__ float bf_lo(unsigned w) { return __uint_as_float(w << 16); }
; __device__ __forceinline__ float bf_hi(unsigned w) { return __uint_as_float(w & 0xffff0000u); }
; #define GAS1 __attribute__((address_space(1)))
;     __device__ __forceinline__ void operator()(const f32x4 (&acc)[2][2][4][2], const Unit& u, int wr, int wc, int fr, int fq) const {
;     ...
;                 if (MODE == 3 || MODE == 4) {
;                     const u32x4 gw = *(const GAS1 u32x4*)(G + (size_t)row * ldg + col);
;                     const f32x4 g0 = {bf_lo(gw.x), bf_hi(gw.x), bf_lo(gw.y), bf_hi(gw.y)}, g1 = {bf_lo(gw.z), bf_hi(gw.z), bf_lo(gw.w), bf_hi(gw.w)};
;                     v0 = v0 * g0; v1 = v1 * g1;
;                     if (MODE == 4) {
;                         const u32x4 ow = *(const GAS1 u32x4*)((const bf16_t*)O + (size_t)row * ldc + col);
;                         const f32x4 o0 = {bf_lo(ow.x), bf_hi(ow.x), bf_lo(ow.y), bf_hi(ow.y)}, o1 = {bf_lo(ow.z), bf_hi(ow.z), bf_lo(ow.w), bf_hi(ow.w)};
;                         v0 += o0; v1 += o1;
;                     }
;                 }
;                 u32x4 w; w.x = cvt_pk_bf16(v0[0], v0[1]); w.y = cvt_pk_bf16(v0[2], v0[3]); w.z = cvt_pk_bf16(v1[0], v1[1]); w.w = cvt_pk_bf16(v1[2], v1[3]);
;                 if (bj == 0) asm volatile("ds_write_b128 %0, %1" :: "v"(wa), "v"(w)); else asm volatile("ds_write_b128 %0, %1 offset:64" :: "v"(wa), "v"(w));
;             }
;             asm volatile("ds_read_b128 %0, %1" : "=&v"(rb[g & 1][0]) : "v"(ra));
;             asm volatile("ds_read_b128 %0, %1 offset:1152" : "=&v"(rb[g & 1][1]) : "v"(ra));
;             if (g >= 1) {
;                 asm volatile("s_waitcnt lgkmcnt(4)" : "+v"(rb[(g - 1) & 1][0]), "+v"(rb[(g - 1) & 1][1]));
;                 bf16_t* ob = obase + (size_t)(((g - 1) >> 2) * HALF + ((g - 1) & 3) * 16) * ldc;
;                 *(GAS1 u32x4*)ob = rb[(g - 1) & 1][0]; *(GAS1 u32x4*)(ob + (size_t)8 * ldc) = rb[(g - 1) & 1][1];
;             }
	v_mov_b32_e32 v124, v214
	v_mov_b32_e32 v125, v215
	v_mov_b32_e32 v126, v216
	v_mov_b32_e32 v127, v217
	v_lshlrev_b32_e32 v176, 16, v124
	v_and_b32_e32 v177, 0xffff0000, v124
	v_lshlrev_b32_e32 v124, 16, v125
	v_and_b32_e32 v125, 0xffff0000, v125
	v_lshlrev_b32_e32 v178, 16, v126
	v_and_b32_e32 v179, 0xffff0000, v126
	v_lshlrev_b32_e32 v126, 16, v127
	v_and_b32_e32 v127, 0xffff0000, v127
	v_pk_fma_f32 v[110:111], v[110:111], v[120:121], v[124:125]
	v_pk_fma_f32 v[120:121], v[106:107], v[122:123], v[126:127]
	v_pk_fma_f32 v[106:107], v[104:105], v[168:169], v[178:179]
	v_pk_fma_f32 v[108:109], v[108:109], v[166:167], v[176:177]
	s_nop 0
	v_cvt_pk_bf16_f32 v104, v108, v109
	v_cvt_pk_bf16_f32 v105, v110, v111
	v_cvt_pk_bf16_f32 v106, v106, v107
	v_cvt_pk_bf16_f32 v107, v120, v121
	v_or_b32_e32 v110, 32, v148
	ds_write_b128 v156, v[104:107]
	v_or_b32_e32 v104, s21, v154
	v_ashrrev_i32_e32 v105, 31, v104
	v_lshlrev_b64 v[104:105], 12, v[104:105]
	v_lshl_add_u64 v[104:105], s[8:9], 0, v[104:105]
	v_lshl_add_u64 v[104:105], s[28:29], 1, v[104:105]
	v_lshl_add_u64 v[104:105], v[104:105], 0, s[10:11]
	v_ashrrev_i32_e32 v111, 31, v110
	v_mad_i64_i32 v[124:125], s[30:31], v110, s72, v[150:151]
	v_lshl_add_u64 v[104:105], v[104:105], 0, v[136:137]
	v_lshlrev_b64 v[110:111], 12, v[110:111]
	v_add_co_u32_e32 v126, vcc, s67, v104
	v_lshl_add_u64 v[110:111], s[8:9], 0, v[110:111]
	v_lshl_add_u64 v[124:125], v[124:125], 0, v[146:147]
	v_addc_co_u32_e32 v127, vcc, 0, v105, vcc
	s_waitcnt vmcnt(5)
	v_mov_b32_e32 v106, v218
	v_mov_b32_e32 v107, v219
	v_mov_b32_e32 v108, v220
	v_mov_b32_e32 v109, v221
	v_lshlrev_b32_e32 v162, 16, v106
	v_and_b32_e32 v163, 0xffff0000, v106
	v_lshlrev_b32_e32 v106, 16, v107
	v_and_b32_e32 v107, 0xffff0000, v107
	v_lshlrev_b32_e32 v164, 16, v108
	v_and_b32_e32 v165, 0xffff0000, v108
	v_lshlrev_b32_e32 v108, 16, v109
	v_and_b32_e32 v109, 0xffff0000, v109
	s_waitcnt vmcnt(4)
	v_mov_b32_e32 v120, v222
	v_mov_b32_e32 v121, v223
	v_mov_b32_e32 v122, v224
	v_mov_b32_e32 v123, v225
	v_lshlrev_b32_e32 v166, 16, v120
	v_and_b32_e32 v167, 0xffff0000, v120
	v_lshlrev_b32_e32 v120, 16, v121
	v_and_b32_e32 v121, 0xffff0000, v121
	v_lshlrev_b32_e32 v168, 16, v122
	v_and_b32_e32 v169, 0xffff0000, v122
	v_lshlrev_b32_e32 v122, 16, v123
	v_and_b32_e32 v123, 0xffff0000, v123
	v_pk_fma_f32 v[102:103], v[102:103], v[106:107], v[120:121]
	v_pk_fma_f32 v[106:107], v[98:99], v[108:109], v[122:123]
	v_pk_fma_f32 v[98:99], v[96:97], v[164:165], v[168:169]
	v_pk_fma_f32 v[100:101], v[100:101], v[162:163], v[166:167]
	s_nop 0
	v_cvt_pk_bf16_f32 v96, v100, v101
	v_cvt_pk_bf16_f32 v97, v102, v103
	v_cvt_pk_bf16_f32 v98, v98, v99
	v_cvt_pk_bf16_f32 v99, v106, v107
	s_nop 0
	ds_write_b128 v156, v[96:99] offset:64
	ds_read_b128 v[96:99], v157
	ds_read_b128 v[100:103], v157 offset:1152
	s_waitcnt lgkmcnt(4)
	global_store_dwordx4 v[104:105], v[112:115], off
	global_store_dwordx4 v[126:127], v[116:119], off
	v_lshl_add_u64 v[114:115], v[110:111], 0, v[146:147]
	s_waitcnt vmcnt(5)
	v_mov_b32_e32 v106, v226
	v_mov_b32_e32 v107, v227
	v_mov_b32_e32 v108, v228
	v_mov_b32_e32 v109, v229
	v_lshlrev_b32_e32 v116, 16, v106
	v_and_b32_e32 v117, 0xffff0000, v106
	v_lshlrev_b32_e32 v106, 16, v107
	v_and_b32_e32 v107, 0xffff0000, v107
	v_lshlrev_b32_e32 v118, 16, v108
	v_and_b32_e32 v119, 0xffff0000, v108
	v_lshlrev_b32_e32 v108, 16, v109
	v_and_b32_e32 v109, 0xffff0000, v109
	s_waitcnt vmcnt(4)
	v_mov_b32_e32 v110, v236
	v_mov_b32_e32 v111, v237
	v_mov_b32_e32 v112, v238
	v_mov_b32_e32 v113, v239
	v_lshlrev_b32_e32 v120, 16, v110
	v_and_b32_e32 v121, 0xffff0000, v110
	v_lshlrev_b32_e32 v110, 16, v111
	v_and_b32_e32 v111, 0xffff0000, v111
	v_lshlrev_b32_e32 v122, 16, v112
	v_and_b32_e32 v123, 0xffff0000, v112
	v_lshlrev_b32_e32 v112, 16, v113
	v_and_b32_e32 v113, 0xffff0000, v113
	v_pk_fma_f32 v[94:95], v[94:95], v[106:107], v[110:111]
	v_pk_fma_f32 v[106:107], v[90:91], v[108:109], v[112:113]
	v_pk_fma_f32 v[90:91], v[88:89], v[118:119], v[122:123]
	v_pk_fma_f32 v[92:93], v[92:93], v[116:117], v[120:121]
	v_add_co_u32_e32 v110, vcc, s62, v104
	v_cvt_pk_bf16_f32 v88, v92, v93
	v_cvt_pk_bf16_f32 v89, v94, v95
	v_cvt_pk_bf16_f32 v90, v90, v91
	v_cvt_pk_bf16_f32 v91, v106, v107
	v_or_b32_e32 v106, 48, v148
	ds_write_b128 v156, v[88:91]
	v_ashrrev_i32_e32 v107, 31, v106
	v_addc_co_u32_e32 v111, vcc, 0, v105, vcc
	v_mad_i64_i32 v[108:109], s[28:29], v106, s72, v[150:151]
	v_add_co_u32_e32 v112, vcc, s66, v104
	v_lshl_add_u64 v[108:109], v[108:109], 0, v[146:147]
	s_nop 0
	v_addc_co_u32_e32 v113, vcc, 0, v105, vcc
	s_waitcnt vmcnt(3)
	v_mov_b32_e32 v88, v240
	v_mov_b32_e32 v89, v241
	v_mov_b32_e32 v90, v242
	v_mov_b32_e32 v91, v243
	v_lshlrev_b32_e32 v114, 16, v88
	v_and_b32_e32 v115, 0xffff0000, v88
	v_lshlrev_b32_e32 v88, 16, v89
	v_and_b32_e32 v89, 0xffff0000, v89
	v_lshlrev_b32_e32 v116, 16, v90
	v_and_b32_e32 v117, 0xffff0000, v90
	v_lshlrev_b32_e32 v90, 16, v91
	v_and_b32_e32 v91, 0xffff0000, v91
	s_waitcnt vmcnt(2)
; __device__ __forceinline__ unsigned cvt_pk_bf16(float lo, float hi) { unsigned r; asm volatile("v_cvt_pk_bf16_f32 %0, %1, %2" : "=v"(r) : "v"(lo), "v"(hi)); return r; }
; __device__ __forceinline__ float bf_lo(unsigned w) { return __uint_as_float(w << 16); }
; __device__ __forceinline__ float bf_hi(unsigned w) { return __uint_as_float(w & 0xffff0000u); }
; #define GAS1 __attribute__((address_space(1)))
;     __device__ __forceinline__ void operator()(const f32x4 (&acc)[2][2][4][2], const Unit& u, int wr, int wc, int fr, int fq) const {
;     ...
;                 if (MODE == 3 || MODE == 4) {
;                     const u32x4 gw = *(const GAS1 u32x4*)(G + (size_t)row * ldg + col);
;                     const f32x4 g0 = {bf_lo(gw.x), bf_hi(gw.x), bf_lo(gw.y), bf_hi(gw.y)}, g1 = {bf_lo(gw.z), bf_hi(gw.z), bf_lo(gw.w), bf_hi(gw.w)};
;                     v0 = v0 * g0; v1 = v1 * g1;
;                     if (MODE == 4) {
;                         const u32x4 ow = *(const GAS1 u32x4*)((const bf16_t*)O + (size_t)row * ldc + col);
;                         const f32x4 o0 = {bf_lo(ow.x), bf_hi(ow.x), bf_lo(ow.y), bf_hi(ow.y)}, o1 = {bf_lo(ow.z), bf_hi(ow.z), bf_lo(ow.w), bf_hi(ow.w)};
;                         v0 += o0; v1 += o1;
;                     }
;                 }
;                 u32x4 w; w.x = cvt_pk_bf16(v0[0], v0[1]); w.y = cvt_pk_bf16(v0[2], v0[3]); w.z = cvt_pk_bf16(v1[0], v1[1]); w.w = cvt_pk_bf16(v1[2], v1[3]);
;                 if (bj == 0) asm volatile("ds_write_b128 %0, %1" :: "v"(wa), "v"(w)); else asm volatile("ds_write_b128 %0, %1 offset:64" :: "v"(wa), "v"(w));
;             }
;             asm volatile("ds_read_b128 %0, %1" : "=&v"(rb[g & 1][0]) : "v"(ra));
;             asm volatile("ds_read_b128 %0, %1 offset:1152" : "=&v"(rb[g & 1][1]) : "v"(ra));
;             if (g >= 1) {
;                 asm volatile("s_waitcnt lgkmcnt(4)" : "+v"(rb[(g - 1) & 1][0]), "+v"(rb[(g - 1) & 1][1]));
;                 bf16_t* ob = obase + (size_t)(((g - 1) >> 2) * HALF + ((g - 1) & 3) * 16) * ldc;
;                 *(GAS1 u32x4*)ob = rb[(g - 1) & 1][0]; *(GAS1 u32x4*)(ob + (size_t)8 * ldc) = rb[(g - 1) & 1][1];
;             }
	v_mov_b32_e32 v92, v246
	v_mov_b32_e32 v93, v247
	v_mov_b32_e32 v94, v248
	v_mov_b32_e32 v95, v249
	v_add_u32_e32 v254, 48, v148
	v_ashrrev_i32_e32 v255, 31, v254
	v_mad_i64_i32 v[206:207], s[98:99], v254, s72, v[150:151]
	v_lshlrev_b64 v[232:233], 12, v[254:255]
	v_lshl_add_u64 v[206:207], v[206:207], 0, v[146:147]
	v_lshl_add_u64 v[232:233], s[8:9], 0, v[232:233]
	v_lshl_add_u64 v[232:233], v[232:233], 0, v[146:147]
	global_load_dwordx4 v[188:191], v[206:207], off
	global_load_dwordx4 v[192:195], v[232:233], off
	global_load_dwordx4 v[196:199], v[206:207], off offset:64
	global_load_dwordx4 v[202:205], v[232:233], off offset:64
	v_add_u32_e32 v254, 128, v148
	v_ashrrev_i32_e32 v255, 31, v254
	v_mad_i64_i32 v[206:207], s[98:99], v254, s72, v[150:151]
	v_lshlrev_b64 v[232:233], 12, v[254:255]
	v_lshl_add_u64 v[206:207], v[206:207], 0, v[146:147]
	v_lshl_add_u64 v[232:233], s[8:9], 0, v[232:233]
	v_lshl_add_u64 v[232:233], v[232:233], 0, v[146:147]
	global_load_dwordx4 v[210:213], v[206:207], off
	global_load_dwordx4 v[214:217], v[232:233], off
	global_load_dwordx4 v[218:221], v[206:207], off offset:64
	global_load_dwordx4 v[222:225], v[232:233], off offset:64
	v_add_u32_e32 v254, 144, v148
	v_ashrrev_i32_e32 v255, 31, v254
	v_mad_i64_i32 v[206:207], s[98:99], v254, s72, v[150:151]
	v_lshlrev_b64 v[232:233], 12, v[254:255]
	v_lshl_add_u64 v[206:207], v[206:207], 0, v[146:147]
	v_lshl_add_u64 v[232:233], s[8:9], 0, v[232:233]
	v_lshl_add_u64 v[232:233], v[232:233], 0, v[146:147]
	global_load_dwordx4 v[226:229], v[206:207], off
	global_load_dwordx4 v[236:239], v[232:233], off
	global_load_dwordx4 v[240:243], v[206:207], off offset:64
	global_load_dwordx4 v[246:249], v[232:233], off offset:64
	v_lshlrev_b32_e32 v118, 16, v92
	v_and_b32_e32 v119, 0xffff0000, v92
	v_lshlrev_b32_e32 v92, 16, v93
	v_and_b32_e32 v93, 0xffff0000, v93
	v_lshlrev_b32_e32 v120, 16, v94
	v_and_b32_e32 v121, 0xffff0000, v94
	v_lshlrev_b32_e32 v94, 16, v95
	v_and_b32_e32 v95, 0xffff0000, v95
	v_pk_fma_f32 v[86:87], v[86:87], v[88:89], v[92:93]
	v_pk_fma_f32 v[88:89], v[82:83], v[90:91], v[94:95]
	v_pk_fma_f32 v[82:83], v[80:81], v[116:117], v[120:121]
	v_pk_fma_f32 v[84:85], v[84:85], v[114:115], v[118:119]
	v_lshlrev_b64 v[92:93], 12, v[106:107]
	v_cvt_pk_bf16_f32 v80, v84, v85
	v_cvt_pk_bf16_f32 v81, v86, v87
	v_cvt_pk_bf16_f32 v82, v82, v83
	v_cvt_pk_bf16_f32 v83, v88, v89
	v_lshl_add_u64 v[92:93], s[8:9], 0, v[92:93]
	ds_write_b128 v156, v[80:83] offset:64
	ds_read_b128 v[80:83], v157
	ds_read_b128 v[84:87], v157 offset:1152
	s_waitcnt lgkmcnt(4)
	global_store_dwordx4 v[110:111], v[96:99], off
	global_store_dwordx4 v[112:113], v[100:103], off
	v_lshl_add_u64 v[96:97], v[92:93], 0, v[146:147]
	s_waitcnt vmcnt(13)
	v_mov_b32_e32 v88, v188
	v_mov_b32_e32 v89, v189
	v_mov_b32_e32 v90, v190
	v_mov_b32_e32 v91, v191
	v_lshlrev_b32_e32 v98, 16, v88
	v_and_b32_e32 v99, 0xffff0000, v88
	v_lshlrev_b32_e32 v88, 16, v89
	v_and_b32_e32 v89, 0xffff0000, v89
	v_lshlrev_b32_e32 v100, 16, v90
	v_and_b32_e32 v101, 0xffff0000, v90
	v_lshlrev_b32_e32 v90, 16, v91
	v_and_b32_e32 v91, 0xffff0000, v91
	s_waitcnt vmcnt(12)
	v_mov_b32_e32 v92, v192
	v_mov_b32_e32 v93, v193
	v_mov_b32_e32 v94, v194
	v_mov_b32_e32 v95, v195
	v_lshlrev_b32_e32 v102, 16, v92
	v_and_b32_e32 v103, 0xffff0000, v92
	v_lshlrev_b32_e32 v92, 16, v93
	v_and_b32_e32 v93, 0xffff0000, v93
	v_lshlrev_b32_e32 v106, 16, v94
	v_and_b32_e32 v107, 0xffff0000, v94
	v_lshlrev_b32_e32 v94, 16, v95
	v_and_b32_e32 v95, 0xffff0000, v95
	v_pk_fma_f32 v[78:79], v[78:79], v[88:89], v[92:93]
	v_pk_fma_f32 v[88:89], v[74:75], v[90:91], v[94:95]
	v_pk_fma_f32 v[74:75], v[72:73], v[100:101], v[106:107]
	v_pk_fma_f32 v[76:77], v[76:77], v[98:99], v[102:103]
	v_add_co_u32_e32 v92, vcc, s73, v104
	v_cvt_pk_bf16_f32 v72, v76, v77
	v_cvt_pk_bf16_f32 v73, v78, v79
	v_cvt_pk_bf16_f32 v74, v74, v75
	v_cvt_pk_bf16_f32 v75, v88, v89
	v_add_u32_e32 v88, 0x80, v148
	ds_write_b128 v156, v[72:75]
	v_ashrrev_i32_e32 v89, 31, v88
	v_addc_co_u32_e32 v93, vcc, 0, v105, vcc
	v_mad_i64_i32 v[90:91], s[28:29], v88, s72, v[150:151]
	v_add_co_u32_e32 v94, vcc, s74, v104
	v_lshl_add_u64 v[90:91], v[90:91], 0, v[146:147]
	s_nop 0
	v_addc_co_u32_e32 v95, vcc, 0, v105, vcc
	s_waitcnt vmcnt(11)
	v_mov_b32_e32 v72, v196
	v_mov_b32_e32 v73, v197
	v_mov_b32_e32 v74, v198
	v_mov_b32_e32 v75, v199
	v_lshlrev_b32_e32 v96, 16, v72
	v_and_b32_e32 v97, 0xffff0000, v72
	v_lshlrev_b32_e32 v72, 16, v73
	v_and_b32_e32 v73, 0xffff0000, v73
	v_lshlrev_b32_e32 v98, 16, v74
	v_and_b32_e32 v99, 0xffff0000, v74
	v_lshlrev_b32_e32 v74, 16, v75
	v_and_b32_e32 v75, 0xffff0000, v75
	s_waitcnt vmcnt(10)
	v_mov_b32_e32 v76, v202
	v_mov_b32_e32 v77, v203
	v_mov_b32_e32 v78, v204
	v_mov_b32_e32 v79, v205
	v_lshlrev_b32_e32 v100, 16, v76
	v_and_b32_e32 v101, 0xffff0000, v76
	v_lshlrev_b32_e32 v76, 16, v77
	v_and_b32_e32 v77, 0xffff0000, v77
	v_lshlrev_b32_e32 v102, 16, v78
	v_and_b32_e32 v103, 0xffff0000, v78
	v_lshlrev_b32_e32 v78, 16, v79
	v_and_b32_e32 v79, 0xffff0000, v79
	v_pk_fma_f32 v[70:71], v[70:71], v[72:73], v[76:77]
	v_pk_fma_f32 v[72:73], v[66:67], v[74:75], v[78:79]
	v_pk_fma_f32 v[66:67], v[64:65], v[98:99], v[102:103]
	v_pk_fma_f32 v[68:69], v[68:69], v[96:97], v[100:101]
	v_lshlrev_b64 v[76:77], 12, v[88:89]
	v_cvt_pk_bf16_f32 v64, v68, v69
	v_cvt_pk_bf16_f32 v65, v70, v71
	v_cvt_pk_bf16_f32 v66, v66, v67
	v_cvt_pk_bf16_f32 v67, v72, v73
	v_lshl_add_u64 v[76:77], s[8:9], 0, v[76:77]
	ds_write_b128 v156, v[64:67] offset:64
	ds_read_b128 v[64:67], v157
	ds_read_b128 v[68:71], v157 offset:1152
	s_waitcnt lgkmcnt(4)
; __device__ __forceinline__ unsigned cvt_pk_bf16(float lo, float hi) { unsigned r; asm volatile("v_cvt_pk_bf16_f32 %0, %1, %2" : "=v"(r) : "v"(lo), "v"(hi)); return r; }
; __device__ __forceinline__ float bf_lo(unsigned w) { return __uint_as_float(w << 16); }
; __device__ __forceinline__ float bf_hi(unsigned w) { return __uint_as_float(w & 0xffff0000u); }
; #define GAS1 __attribute__((address_space(1)))
;     __device__ __forceinline__ void operator()(const f32x4 (&acc)[2][2][4][2], const Unit& u, int wr, int wc, int fr, int fq) const {
;     ...
;                 if (MODE == 3 || MODE == 4) {
;                     const u32x4 gw = *(const GAS1 u32x4*)(G + (size_t)row * ldg + col);
;                     const f32x4 g0 = {bf_lo(gw.x), bf_hi(gw.x), bf_lo(gw.y), bf_hi(gw.y)}, g1 = {bf_lo(gw.z), bf_hi(gw.z), bf_lo(gw.w), bf_hi(gw.w)};
;                     v0 = v0 * g0; v1 = v1 * g1;
;                     if (MODE == 4) {
;                         const u32x4 ow = *(const GAS1 u32x4*)((const bf16_t*)O + (size_t)row * ldc + col);
;                         const f32x4 o0 = {bf_lo(ow.x), bf_hi(ow.x), bf_lo(ow.y), bf_hi(ow.y)}, o1 = {bf_lo(ow.z), bf_hi(ow.z), bf_lo(ow.w), bf_hi(ow.w)};
;                         v0 += o0; v1 += o1;
;                     }
;                 }
;                 u32x4 w; w.x = cvt_pk_bf16(v0[0], v0[1]); w.y = cvt_pk_bf16(v0[2], v0[3]); w.z = cvt_pk_bf16(v1[0], v1[1]); w.w = cvt_pk_bf16(v1[2], v1[3]);
;                 if (bj == 0) asm volatile("ds_write_b128 %0, %1" :: "v"(wa), "v"(w)); else asm volatile("ds_write_b128 %0, %1 offset:64" :: "v"(wa), "v"(w));
;             }
;             asm volatile("ds_read_b128 %0, %1" : "=&v"(rb[g & 1][0]) : "v"(ra));
;             asm volatile("ds_read_b128 %0, %1 offset:1152" : "=&v"(rb[g & 1][1]) : "v"(ra));
;             if (g >= 1) {
;                 asm volatile("s_waitcnt lgkmcnt(4)" : "+v"(rb[(g - 1) & 1][0]), "+v"(rb[(g - 1) & 1][1]));
;                 bf16_t* ob = obase + (size_t)(((g - 1) >> 2) * HALF + ((g - 1) & 3) * 16) * ldc;
;                 *(GAS1 u32x4*)ob = rb[(g - 1) & 1][0]; *(GAS1 u32x4*)(ob + (size_t)8 * ldc) = rb[(g - 1) & 1][1];
;             }
	global_store_dwordx4 v[92:93], v[80:83], off
	global_store_dwordx4 v[94:95], v[84:87], off
	v_lshl_add_u64 v[80:81], v[76:77], 0, v[146:147]
	s_waitcnt vmcnt(11)
	v_mov_b32_e32 v72, v210
	v_mov_b32_e32 v73, v211
	v_mov_b32_e32 v74, v212
	v_mov_b32_e32 v75, v213
	v_lshlrev_b32_e32 v82, 16, v72
	v_and_b32_e32 v83, 0xffff0000, v72
	v_lshlrev_b32_e32 v72, 16, v73
	v_and_b32_e32 v73, 0xffff0000, v73
	v_lshlrev_b32_e32 v84, 16, v74
	v_and_b32_e32 v85, 0xffff0000, v74
	v_lshlrev_b32_e32 v74, 16, v75
	v_and_b32_e32 v75, 0xffff0000, v75
	s_waitcnt vmcnt(10)
	v_mov_b32_e32 v76, v214
	v_mov_b32_e32 v77, v215
	v_mov_b32_e32 v78, v216
	v_mov_b32_e32 v79, v217
	v_lshlrev_b32_e32 v86, 16, v76
	v_and_b32_e32 v87, 0xffff0000, v76
	v_lshlrev_b32_e32 v76, 16, v77
	v_and_b32_e32 v77, 0xffff0000, v77
	v_lshlrev_b32_e32 v88, 16, v78
	v_and_b32_e32 v89, 0xffff0000, v78
	v_lshlrev_b32_e32 v78, 16, v79
	v_and_b32_e32 v79, 0xffff0000, v79
	v_pk_fma_f32 v[62:63], v[62:63], v[72:73], v[76:77]
	v_pk_fma_f32 v[72:73], v[58:59], v[74:75], v[78:79]
	v_pk_fma_f32 v[58:59], v[56:57], v[84:85], v[88:89]
	v_pk_fma_f32 v[60:61], v[60:61], v[82:83], v[86:87]
	v_add_co_u32_e32 v76, vcc, s75, v104
	v_cvt_pk_bf16_f32 v56, v60, v61
	v_cvt_pk_bf16_f32 v57, v62, v63
	v_cvt_pk_bf16_f32 v58, v58, v59
	v_cvt_pk_bf16_f32 v59, v72, v73
	v_add_u32_e32 v72, 0x90, v148
	ds_write_b128 v156, v[56:59]
	v_ashrrev_i32_e32 v73, 31, v72
	v_addc_co_u32_e32 v77, vcc, 0, v105, vcc
	v_mad_i64_i32 v[74:75], s[28:29], v72, s72, v[150:151]
	v_add_co_u32_e32 v78, vcc, s76, v104
	v_lshl_add_u64 v[74:75], v[74:75], 0, v[146:147]
	s_nop 0
	v_addc_co_u32_e32 v79, vcc, 0, v105, vcc
	s_waitcnt vmcnt(9)
	v_mov_b32_e32 v56, v218
	v_mov_b32_e32 v57, v219
	v_mov_b32_e32 v58, v220
	v_mov_b32_e32 v59, v221
	v_lshlrev_b32_e32 v80, 16, v56
	v_and_b32_e32 v81, 0xffff0000, v56
	v_lshlrev_b32_e32 v56, 16, v57
	v_and_b32_e32 v57, 0xffff0000, v57
	v_lshlrev_b32_e32 v82, 16, v58
	v_and_b32_e32 v83, 0xffff0000, v58
	v_lshlrev_b32_e32 v58, 16, v59
	v_and_b32_e32 v59, 0xffff0000, v59
	s_waitcnt vmcnt(8)
	v_mov_b32_e32 v60, v222
	v_mov_b32_e32 v61, v223
	v_mov_b32_e32 v62, v224
	v_mov_b32_e32 v63, v225
	v_lshlrev_b32_e32 v84, 16, v60
	v_and_b32_e32 v85, 0xffff0000, v60
	v_lshlrev_b32_e32 v60, 16, v61
	v_and_b32_e32 v61, 0xffff0000, v61
	v_lshlrev_b32_e32 v86, 16, v62
	v_and_b32_e32 v87, 0xffff0000, v62
	v_lshlrev_b32_e32 v62, 16, v63
	v_and_b32_e32 v63, 0xffff0000, v63
	v_pk_fma_f32 v[54:55], v[54:55], v[56:57], v[60:61]
	v_pk_fma_f32 v[56:57], v[50:51], v[58:59], v[62:63]
	v_pk_fma_f32 v[50:51], v[48:49], v[82:83], v[86:87]
	v_pk_fma_f32 v[52:53], v[52:53], v[80:81], v[84:85]
	v_lshlrev_b64 v[60:61], 12, v[72:73]
	v_cvt_pk_bf16_f32 v48, v52, v53
	v_cvt_pk_bf16_f32 v49, v54, v55
	v_cvt_pk_bf16_f32 v50, v50, v51
	v_cvt_pk_bf16_f32 v51, v56, v57
	v_lshl_add_u64 v[60:61], s[8:9], 0, v[60:61]
	ds_write_b128 v156, v[48:51] offset:64
	ds_read_b128 v[48:51], v157
	ds_read_b128 v[52:55], v157 offset:1152
	s_waitcnt lgkmcnt(4)
	global_store_dwordx4 v[76:77], v[64:67], off
	global_store_dwordx4 v[78:79], v[68:71], off
	v_lshl_add_u64 v[64:65], v[60:61], 0, v[146:147]
	s_waitcnt vmcnt(9)
	v_mov_b32_e32 v56, v226
	v_mov_b32_e32 v57, v227
	v_mov_b32_e32 v58, v228
	v_mov_b32_e32 v59, v229
	v_lshlrev_b32_e32 v66, 16, v56
	v_and_b32_e32 v67, 0xffff0000, v56
	v_lshlrev_b32_e32 v56, 16, v57
	v_and_b32_e32 v57, 0xffff0000, v57
	v_lshlrev_b32_e32 v68, 16, v58
	v_and_b32_e32 v69, 0xffff0000, v58
	v_lshlrev_b32_e32 v58, 16, v59
	v_and_b32_e32 v59, 0xffff0000, v59
	s_waitcnt vmcnt(8)
	v_mov_b32_e32 v60, v236
	v_mov_b32_e32 v61, v237
	v_mov_b32_e32 v62, v238
	v_mov_b32_e32 v63, v239
	v_lshlrev_b32_e32 v70, 16, v60
	v_and_b32_e32 v71, 0xffff0000, v60
	v_lshlrev_b32_e32 v60, 16, v61
	v_and_b32_e32 v61, 0xffff0000, v61
	v_lshlrev_b32_e32 v72, 16, v62
	v_and_b32_e32 v73, 0xffff0000, v62
	v_lshlrev_b32_e32 v62, 16, v63
	v_and_b32_e32 v63, 0xffff0000, v63
	v_pk_fma_f32 v[46:47], v[46:47], v[56:57], v[60:61]
	v_pk_fma_f32 v[56:57], v[42:43], v[58:59], v[62:63]
	v_pk_fma_f32 v[42:43], v[40:41], v[68:69], v[72:73]
	v_pk_fma_f32 v[44:45], v[44:45], v[66:67], v[70:71]
	v_add_co_u32_e32 v60, vcc, s77, v104
	v_cvt_pk_bf16_f32 v40, v44, v45
	v_cvt_pk_bf16_f32 v41, v46, v47
	v_cvt_pk_bf16_f32 v42, v42, v43
	v_cvt_pk_bf16_f32 v43, v56, v57
	v_add_u32_e32 v56, 0xa0, v148
	ds_write_b128 v156, v[40:43]
	v_ashrrev_i32_e32 v57, 31, v56
	v_addc_co_u32_e32 v61, vcc, 0, v105, vcc
	v_mad_i64_i32 v[58:59], s[28:29], v56, s72, v[150:151]
	v_add_co_u32_e32 v62, vcc, s79, v104
	v_lshl_add_u64 v[58:59], v[58:59], 0, v[146:147]
	s_nop 0
	v_addc_co_u32_e32 v63, vcc, 0, v105, vcc
	s_waitcnt vmcnt(7)
	v_mov_b32_e32 v40, v240
	v_mov_b32_e32 v41, v241
	v_mov_b32_e32 v42, v242
	v_mov_b32_e32 v43, v243
	v_lshlrev_b32_e32 v64, 16, v40
	v_and_b32_e32 v65, 0xffff0000, v40
	v_lshlrev_b32_e32 v40, 16, v41
	v_and_b32_e32 v41, 0xffff0000, v41
	v_lshlrev_b32_e32 v66, 16, v42
	v_and_b32_e32 v67, 0xffff0000, v42
	v_lshlrev_b32_e32 v42, 16, v43
	v_and_b32_e32 v43, 0xffff0000, v43
	s_waitcnt vmcnt(6)
; __device__ __forceinline__ unsigned cvt_pk_bf16(float lo, float hi) { unsigned r; asm volatile("v_cvt_pk_bf16_f32 %0, %1, %2" : "=v"(r) : "v"(lo), "v"(hi)); return r; }
; __device__ __forceinline__ float bf_lo(unsigned w) { return __uint_as_float(w << 16); }
; __device__ __forceinline__ float bf_hi(unsigned w) { return __uint_as_float(w & 0xffff0000u); }
; #define GAS1 __attribute__((address_space(1)))
;     __device__ __forceinline__ void operator()(const f32x4 (&acc)[2][2][4][2], const Unit& u, int wr, int wc, int fr, int fq) const {
;     ...
;                 if (MODE == 3 || MODE == 4) {
;                     const u32x4 gw = *(const GAS1 u32x4*)(G + (size_t)row * ldg + col);
;                     const f32x4 g0 = {bf_lo(gw.x), bf_hi(gw.x), bf_lo(gw.y), bf_hi(gw.y)}, g1 = {bf_lo(gw.z), bf_hi(gw.z), bf_lo(gw.w), bf_hi(gw.w)};
;                     v0 = v0 * g0; v1 = v1 * g1;
;                     if (MODE == 4) {
;                         const u32x4 ow = *(const GAS1 u32x4*)((const bf16_t*)O + (size_t)row * ldc + col);
;                         const f32x4 o0 = {bf_lo(ow.x), bf_hi(ow.x), bf_lo(ow.y), bf_hi(ow.y)}, o1 = {bf_lo(ow.z), bf_hi(ow.z), bf_lo(ow.w), bf_hi(ow.w)};
;                         v0 += o0; v1 += o1;
;                     }
;                 }
;                 u32x4 w; w.x = cvt_pk_bf16(v0[0], v0[1]); w.y = cvt_pk_bf16(v0[2], v0[3]); w.z = cvt_pk_bf16(v1[0], v1[1]); w.w = cvt_pk_bf16(v1[2], v1[3]);
;                 if (bj == 0) asm volatile("ds_write_b128 %0, %1" :: "v"(wa), "v"(w)); else asm volatile("ds_write_b128 %0, %1 offset:64" :: "v"(wa), "v"(w));
;             }
;             asm volatile("ds_read_b128 %0, %1" : "=&v"(rb[g & 1][0]) : "v"(ra));
;             asm volatile("ds_read_b128 %0, %1 offset:1152" : "=&v"(rb[g & 1][1]) : "v"(ra));
;             if (g >= 1) {
;                 asm volatile("s_waitcnt lgkmcnt(4)" : "+v"(rb[(g - 1) & 1][0]), "+v"(rb[(g - 1) & 1][1]));
;                 bf16_t* ob = obase + (size_t)(((g - 1) >> 2) * HALF + ((g - 1) & 3) * 16) * ldc;
;                 *(GAS1 u32x4*)ob = rb[(g - 1) & 1][0]; *(GAS1 u32x4*)(ob + (size_t)8 * ldc) = rb[(g - 1) & 1][1];
	v_mov_b32_e32 v44, v246
	v_mov_b32_e32 v45, v247
	v_mov_b32_e32 v46, v248
	v_mov_b32_e32 v47, v249
	v_add_u32_e32 v254, 160, v148
	v_ashrrev_i32_e32 v255, 31, v254
	v_mad_i64_i32 v[206:207], s[98:99], v254, s72, v[150:151]
	v_lshlrev_b64 v[232:233], 12, v[254:255]
	v_lshl_add_u64 v[206:207], v[206:207], 0, v[146:147]
	v_lshl_add_u64 v[232:233], s[8:9], 0, v[232:233]
	v_lshl_add_u64 v[232:233], v[232:233], 0, v[146:147]
	global_load_dwordx4 v[188:191], v[206:207], off
	global_load_dwordx4 v[192:195], v[232:233], off
	global_load_dwordx4 v[196:199], v[206:207], off offset:64
	global_load_dwordx4 v[202:205], v[232:233], off offset:64
	v_add_u32_e32 v254, 176, v148
	v_ashrrev_i32_e32 v255, 31, v254
	v_mad_i64_i32 v[206:207], s[98:99], v254, s72, v[150:151]
	v_lshlrev_b64 v[232:233], 12, v[254:255]
	v_lshl_add_u64 v[206:207], v[206:207], 0, v[146:147]
	v_lshl_add_u64 v[232:233], s[8:9], 0, v[232:233]
	v_lshl_add_u64 v[232:233], v[232:233], 0, v[146:147]
	global_load_dwordx4 v[210:213], v[206:207], off
	global_load_dwordx4 v[214:217], v[232:233], off
	global_load_dwordx4 v[218:221], v[206:207], off offset:64
	global_load_dwordx4 v[222:225], v[232:233], off offset:64
	v_lshlrev_b32_e32 v68, 16, v44
	v_and_b32_e32 v69, 0xffff0000, v44
	v_lshlrev_b32_e32 v44, 16, v45
	v_and_b32_e32 v45, 0xffff0000, v45
	v_lshlrev_b32_e32 v70, 16, v46
	v_and_b32_e32 v71, 0xffff0000, v46
	v_lshlrev_b32_e32 v46, 16, v47
	v_and_b32_e32 v47, 0xffff0000, v47
	v_pk_fma_f32 v[38:39], v[38:39], v[40:41], v[44:45]
	v_pk_fma_f32 v[40:41], v[34:35], v[42:43], v[46:47]
	v_pk_fma_f32 v[34:35], v[32:33], v[66:67], v[70:71]
	v_pk_fma_f32 v[36:37], v[36:37], v[64:65], v[68:69]
	v_lshlrev_b64 v[44:45], 12, v[56:57]
	v_cvt_pk_bf16_f32 v32, v36, v37
	v_cvt_pk_bf16_f32 v33, v38, v39
	v_cvt_pk_bf16_f32 v34, v34, v35
	v_cvt_pk_bf16_f32 v35, v40, v41
	v_lshl_add_u64 v[44:45], s[8:9], 0, v[44:45]
	ds_write_b128 v156, v[32:35] offset:64
	ds_read_b128 v[32:35], v157
	ds_read_b128 v[36:39], v157 offset:1152
	s_waitcnt lgkmcnt(4)
	global_store_dwordx4 v[60:61], v[48:51], off
	global_store_dwordx4 v[62:63], v[52:55], off
	v_lshl_add_u64 v[48:49], v[44:45], 0, v[146:147]
	s_waitcnt vmcnt(9)
	v_mov_b32_e32 v40, v188
	v_mov_b32_e32 v41, v189
	v_mov_b32_e32 v42, v190
	v_mov_b32_e32 v43, v191
	v_lshlrev_b32_e32 v50, 16, v40
	v_and_b32_e32 v51, 0xffff0000, v40
	v_lshlrev_b32_e32 v40, 16, v41
	v_and_b32_e32 v41, 0xffff0000, v41
	v_lshlrev_b32_e32 v52, 16, v42
	v_and_b32_e32 v53, 0xffff0000, v42
	v_lshlrev_b32_e32 v42, 16, v43
	v_and_b32_e32 v43, 0xffff0000, v43
	s_waitcnt vmcnt(8)
	v_mov_b32_e32 v44, v192
	v_mov_b32_e32 v45, v193
	v_mov_b32_e32 v46, v194
	v_mov_b32_e32 v47, v195
	v_lshlrev_b32_e32 v54, 16, v44
	v_and_b32_e32 v55, 0xffff0000, v44
	v_lshlrev_b32_e32 v44, 16, v45
	v_and_b32_e32 v45, 0xffff0000, v45
	v_lshlrev_b32_e32 v56, 16, v46
	v_and_b32_e32 v57, 0xffff0000, v46
	v_lshlrev_b32_e32 v46, 16, v47
	v_and_b32_e32 v47, 0xffff0000, v47
	v_pk_fma_f32 v[30:31], v[30:31], v[40:41], v[44:45]
	v_pk_fma_f32 v[40:41], v[26:27], v[42:43], v[46:47]
	v_pk_fma_f32 v[26:27], v[24:25], v[52:53], v[56:57]
	v_pk_fma_f32 v[28:29], v[28:29], v[50:51], v[54:55]
	v_add_co_u32_e32 v44, vcc, s80, v104
	v_cvt_pk_bf16_f32 v24, v28, v29
	v_cvt_pk_bf16_f32 v25, v30, v31
	v_cvt_pk_bf16_f32 v26, v26, v27
	v_cvt_pk_bf16_f32 v27, v40, v41
	v_add_u32_e32 v40, 0xb0, v148
	ds_write_b128 v156, v[24:27]
	v_ashrrev_i32_e32 v41, 31, v40
	v_addc_co_u32_e32 v45, vcc, 0, v105, vcc
	v_mad_i64_i32 v[42:43], s[28:29], v40, s72, v[150:151]
	v_add_co_u32_e32 v46, vcc, s81, v104
	v_lshl_add_u64 v[42:43], v[42:43], 0, v[146:147]
	s_nop 0
	v_addc_co_u32_e32 v47, vcc, 0, v105, vcc
	s_waitcnt vmcnt(7)
	v_mov_b32_e32 v24, v196
	v_mov_b32_e32 v25, v197
	v_mov_b32_e32 v26, v198
	v_mov_b32_e32 v27, v199
	v_lshlrev_b32_e32 v48, 16, v24
	v_and_b32_e32 v49, 0xffff0000, v24
	v_lshlrev_b32_e32 v24, 16, v25
	v_and_b32_e32 v25, 0xffff0000, v25
	v_lshlrev_b32_e32 v50, 16, v26
	v_and_b32_e32 v51, 0xffff0000, v26
	v_lshlrev_b32_e32 v26, 16, v27
	v_and_b32_e32 v27, 0xffff0000, v27
	s_waitcnt vmcnt(6)
; __device__ __forceinline__ unsigned cvt_pk_bf16(float lo, float hi) { unsigned r; asm volatile("v_cvt_pk_bf16_f32 %0, %1, %2" : "=v"(r) : "v"(lo), "v"(hi)); return r; }
; __device__ __forceinline__ float bf_lo(unsigned w) { return __uint_as_float(w << 16); }
; __device__ __forceinline__ float bf_hi(unsigned w) { return __uint_as_float(w & 0xffff0000u); }
; #define GAS1 __attribute__((address_space(1)))
;     __device__ __forceinline__ void operator()(const f32x4 (&acc)[2][2][4][2], const Unit& u, int wr, int wc, int fr, int fq) const {
;     ...
;                 if (MODE == 3 || MODE == 4) {
;                     const u32x4 gw = *(const GAS1 u32x4*)(G + (size_t)row * ldg + col);
;                     const f32x4 g0 = {bf_lo(gw.x), bf_hi(gw.x), bf_lo(gw.y), bf_hi(gw.y)}, g1 = {bf_lo(gw.z), bf_hi(gw.z), bf_lo(gw.w), bf_hi(gw.w)};
;                     v0 = v0 * g0; v1 = v1 * g1;
;                     if (MODE == 4) {
;                         const u32x4 ow = *(const GAS1 u32x4*)((const bf16_t*)O + (size_t)row * ldc + col);
;                         const f32x4 o0 = {bf_lo(ow.x), bf_hi(ow.x), bf_lo(ow.y), bf_hi(ow.y)}, o1 = {bf_lo(ow.z), bf_hi(ow.z), bf_lo(ow.w), bf_hi(ow.w)};
;                         v0 += o0; v1 += o1;
;                     }
;                 }
;                 u32x4 w; w.x = cvt_pk_bf16(v0[0], v0[1]); w.y = cvt_pk_bf16(v0[2], v0[3]); w.z = cvt_pk_bf16(v1[0], v1[1]); w.w = cvt_pk_bf16(v1[2], v1[3]);
;                 if (bj == 0) asm volatile("ds_write_b128 %0, %1" :: "v"(wa), "v"(w)); else asm volatile("ds_write_b128 %0, %1 offset:64" :: "v"(wa), "v"(w));
;             }
;             asm volatile("ds_read_b128 %0, %1" : "=&v"(rb[g & 1][0]) : "v"(ra));
;             asm volatile("ds_read_b128 %0, %1 offset:1152" : "=&v"(rb[g & 1][1]) : "v"(ra));
;             if (g >= 1) {
;                 asm volatile("s_waitcnt lgkmcnt(4)" : "+v"(rb[(g - 1) & 1][0]), "+v"(rb[(g - 1) & 1][1]));
;                 bf16_t* ob = obase + (size_t)(((g - 1) >> 2) * HALF + ((g - 1) & 3) * 16) * ldc;
;                 *(GAS1 u32x4*)ob = rb[(g - 1) & 1][0]; *(GAS1 u32x4*)(ob + (size_t)8 * ldc) = rb[(g - 1) & 1][1];
;             }
;         }
;         asm volatile("s_waitcnt lgkmcnt(0)" : "+v"(rb[1][0]), "+v"(rb[1][1]));
;         { bf16_t* ob = obase + (size_t)(HALF + 3 * 16) * ldc; *(GAS1 u32x4*)ob = rb[1][0]; *(GAS1 u32x4*)(ob + (size_t)8 * ldc) = rb[1][1]; }
	v_mov_b32_e32 v28, v202
	v_mov_b32_e32 v29, v203
	v_mov_b32_e32 v30, v204
	v_mov_b32_e32 v31, v205
	v_lshlrev_b32_e32 v52, 16, v28
	v_and_b32_e32 v53, 0xffff0000, v28
	v_lshlrev_b32_e32 v28, 16, v29
	v_and_b32_e32 v29, 0xffff0000, v29
	v_lshlrev_b32_e32 v54, 16, v30
	v_and_b32_e32 v55, 0xffff0000, v30
	v_lshlrev_b32_e32 v30, 16, v31
	v_and_b32_e32 v31, 0xffff0000, v31
	v_pk_fma_f32 v[22:23], v[22:23], v[24:25], v[28:29]
	v_pk_fma_f32 v[24:25], v[18:19], v[26:27], v[30:31]
	v_pk_fma_f32 v[18:19], v[16:17], v[50:51], v[54:55]
	v_pk_fma_f32 v[20:21], v[20:21], v[48:49], v[52:53]
	v_lshlrev_b64 v[28:29], 12, v[40:41]
	v_cvt_pk_bf16_f32 v16, v20, v21
	v_cvt_pk_bf16_f32 v17, v22, v23
	v_cvt_pk_bf16_f32 v18, v18, v19
	v_cvt_pk_bf16_f32 v19, v24, v25
	v_lshl_add_u64 v[28:29], s[8:9], 0, v[28:29]
	ds_write_b128 v156, v[16:19] offset:64
	ds_read_b128 v[16:19], v157
	ds_read_b128 v[20:23], v157 offset:1152
	s_waitcnt lgkmcnt(4)
	global_store_dwordx4 v[44:45], v[32:35], off
	global_store_dwordx4 v[46:47], v[36:39], off
	v_lshl_add_u64 v[32:33], v[28:29], 0, v[146:147]
	s_waitcnt vmcnt(7)
	v_mov_b32_e32 v24, v210
	v_mov_b32_e32 v25, v211
	v_mov_b32_e32 v26, v212
	v_mov_b32_e32 v27, v213
	v_lshlrev_b32_e32 v34, 16, v24
	v_and_b32_e32 v35, 0xffff0000, v24
	v_lshlrev_b32_e32 v24, 16, v25
	v_and_b32_e32 v25, 0xffff0000, v25
	v_lshlrev_b32_e32 v36, 16, v26
	v_and_b32_e32 v37, 0xffff0000, v26
	v_lshlrev_b32_e32 v26, 16, v27
	v_and_b32_e32 v27, 0xffff0000, v27
	s_waitcnt vmcnt(6)
	v_mov_b32_e32 v28, v214
	v_mov_b32_e32 v29, v215
	v_mov_b32_e32 v30, v216
	v_mov_b32_e32 v31, v217
	v_lshlrev_b32_e32 v38, 16, v28
	v_and_b32_e32 v39, 0xffff0000, v28
	v_lshlrev_b32_e32 v28, 16, v29
	v_and_b32_e32 v29, 0xffff0000, v29
	v_lshlrev_b32_e32 v40, 16, v30
	v_and_b32_e32 v41, 0xffff0000, v30
	v_lshlrev_b32_e32 v30, 16, v31
	v_and_b32_e32 v31, 0xffff0000, v31
	v_pk_fma_f32 v[14:15], v[14:15], v[24:25], v[28:29]
	v_pk_fma_f32 v[24:25], v[10:11], v[26:27], v[30:31]
	v_pk_fma_f32 v[10:11], v[8:9], v[36:37], v[40:41]
	v_pk_fma_f32 v[12:13], v[12:13], v[34:35], v[38:39]
	s_nop 0
	v_cvt_pk_bf16_f32 v8, v12, v13
	v_cvt_pk_bf16_f32 v9, v14, v15
	v_cvt_pk_bf16_f32 v10, v10, v11
	v_cvt_pk_bf16_f32 v11, v24, v25
	v_add_co_u32_e32 v24, vcc, s82, v104
	ds_write_b128 v156, v[8:11]
	v_addc_co_u32_e32 v25, vcc, 0, v105, vcc
	v_add_co_u32_e32 v26, vcc, s83, v104
	s_waitcnt vmcnt(5)
	v_mov_b32_e32 v8, v218
	v_mov_b32_e32 v9, v219
	v_mov_b32_e32 v10, v220
	v_mov_b32_e32 v11, v221
	v_lshlrev_b32_e32 v32, 16, v8
	v_addc_co_u32_e32 v27, vcc, 0, v105, vcc
	v_add_co_u32_e32 v28, vcc, 0xb0000, v104
	v_and_b32_e32 v33, 0xffff0000, v8
	v_lshlrev_b32_e32 v8, 16, v9
	v_and_b32_e32 v9, 0xffff0000, v9
	v_lshlrev_b32_e32 v34, 16, v10
	v_and_b32_e32 v35, 0xffff0000, v10
	v_lshlrev_b32_e32 v10, 16, v11
	v_and_b32_e32 v11, 0xffff0000, v11
	s_waitcnt vmcnt(4)
	v_mov_b32_e32 v12, v222
	v_mov_b32_e32 v13, v223
	v_mov_b32_e32 v14, v224
	v_mov_b32_e32 v15, v225
	v_lshlrev_b32_e32 v36, 16, v12
	v_and_b32_e32 v37, 0xffff0000, v12
	v_lshlrev_b32_e32 v12, 16, v13
	v_and_b32_e32 v13, 0xffff0000, v13
	v_lshlrev_b32_e32 v38, 16, v14
	v_and_b32_e32 v39, 0xffff0000, v14
	v_lshlrev_b32_e32 v14, 16, v15
	v_and_b32_e32 v15, 0xffff0000, v15
	v_addc_co_u32_e32 v29, vcc, 0, v105, vcc
	v_pk_fma_f32 v[6:7], v[6:7], v[8:9], v[12:13]
	v_pk_fma_f32 v[8:9], v[2:3], v[10:11], v[14:15]
	v_pk_fma_f32 v[2:3], v[0:1], v[34:35], v[38:39]
	v_add_co_u32_e32 v30, vcc, 0xb8000, v104
	v_pk_fma_f32 v[4:5], v[4:5], v[32:33], v[36:37]
	s_nop 0
	v_addc_co_u32_e32 v31, vcc, 0, v105, vcc
	v_cvt_pk_bf16_f32 v0, v4, v5
	v_cvt_pk_bf16_f32 v1, v6, v7
	v_cvt_pk_bf16_f32 v2, v2, v3
	v_cvt_pk_bf16_f32 v3, v8, v9
	s_andn2_b64 vcc, exec, s[6:7]
	ds_write_b128 v156, v[0:3] offset:64
	ds_read_b128 v[0:3], v157
	ds_read_b128 v[4:7], v157 offset:1152
	s_waitcnt lgkmcnt(4)
	global_store_dwordx4 v[24:25], v[16:19], off
	global_store_dwordx4 v[26:27], v[20:23], off
	s_waitcnt lgkmcnt(0)
	s_mov_b64 s[6:7], -1
	global_store_dwordx4 v[28:29], v[0:3], off
	global_store_dwordx4 v[30:31], v[4:7], off
	s_cbranch_vccnz .LBB0_1423
	s_andn2_b64 vcc, exec, s[12:13]
	s_cbranch_vccnz .LBB0_1422
	s_barrier
	s_branch .LBB0_1422

; __global__ void __launch_bounds__(512, 2) mega_fwd(Args a) {
	.amdhsa_kernel _Z8mega_fwd4Args
		.amdhsa_group_segment_fixed_size 0
		.amdhsa_private_segment_fixed_size 0
		.amdhsa_kernarg_size 560
		.amdhsa_user_sgpr_count 2
		.amdhsa_user_sgpr_dispatch_ptr 0
		.amdhsa_user_sgpr_queue_ptr 0
		.amdhsa_user_sgpr_kernarg_segment_ptr 1
		.amdhsa_user_sgpr_dispatch_id 0
		.amdhsa_user_sgpr_kernarg_preload_length 0
		.amdhsa_user_sgpr_kernarg_preload_offset 0
		.amdhsa_user_sgpr_private_segment_size 0
		.amdhsa_uses_dynamic_stack 0
		.amdhsa_enable_private_segment 0
		.amdhsa_system_sgpr_workgroup_id_x 1
		.amdhsa_system_sgpr_workgroup_id_y 0
		.amdhsa_system_sgpr_workgroup_id_z 0
		.amdhsa_system_sgpr_workgroup_info 0
		.amdhsa_system_vgpr_workitem_id 2
		.amdhsa_next_free_vgpr 256
		.amdhsa_next_free_sgpr 100
		.amdhsa_accum_offset 256
		.amdhsa_reserve_vcc 1
		.amdhsa_float_round_mode_32 0
		.amdhsa_float_round_mode_16_64 0
		.amdhsa_float_denorm_mode_32 3
		.amdhsa_float_denorm_mode_16_64 3
		.amdhsa_dx10_clamp 1
		.amdhsa_ieee_mode 1
		.amdhsa_fp16_overflow 0
		.amdhsa_tg_split 0
		.amdhsa_exception_fp_ieee_invalid_op 0
		.amdhsa_exception_fp_denorm_src 0
		.amdhsa_exception_fp_ieee_div_zero 0
		.amdhsa_exception_fp_ieee_overflow 0
		.amdhsa_exception_fp_ieee_underflow 0
		.amdhsa_exception_fp_ieee_inexact 0
		.amdhsa_exception_int_div_zero 0
	.end_amdhsa_kernel

; __global__ void __launch_bounds__(512, 2) mega_fwd(Args a) {
amdhsa.kernels:
  - .agpr_count:     0
    .args:
      - .offset:         0
        .size:           304
        .value_kind:     by_value
      - .offset:         304
        .size:           4
        .value_kind:     hidden_block_count_x
      - .offset:         308
        .size:           4
        .value_kind:     hidden_block_count_y
      - .offset:         312
        .size:           4
        .value_kind:     hidden_block_count_z
      - .offset:         316
        .size:           2
        .value_kind:     hidden_group_size_x
      - .offset:         318
        .size:           2
        .value_kind:     hidden_group_size_y
      - .offset:         320
        .size:           2
        .value_kind:     hidden_group_size_z
      - .offset:         322
        .size:           2
        .value_kind:     hidden_remainder_x
      - .offset:         324
        .size:           2
        .value_kind:     hidden_remainder_y
      - .offset:         326
        .size:           2
        .value_kind:     hidden_remainder_z
      - .offset:         344
        .size:           8
        .value_kind:     hidden_global_offset_x
      - .offset:         352
        .size:           8
        .value_kind:     hidden_global_offset_y
      - .offset:         360
        .size:           8
        .value_kind:     hidden_global_offset_z
      - .offset:         368
        .size:           2
        .value_kind:     hidden_grid_dims
      - .offset:         392
        .size:           8
        .value_kind:     hidden_multigrid_sync_arg
      - .offset:         424
        .size:           4
        .value_kind:     hidden_dynamic_lds_size
    .group_segment_fixed_size: 0
    .kernarg_segment_align: 8
    .kernarg_segment_size: 560
    .language:       OpenCL C
    .language_version:
      - 2
      - 0
    .max_flat_workgroup_size: 512
    .name:           _Z8mega_fwd4Args
    .private_segment_fixed_size: 0
    .sgpr_count:     106
    .sgpr_spill_count: 11
    .symbol:         _Z8mega_fwd4Args.kd
    .uniform_work_group_size: 1
    .uses_dynamic_stack: false
    .vgpr_count:     256
    .vgpr_spill_count: 0
    .wavefront_size: 64
